# vmcnt(8) stage-load wait moved behind the four pre-barrier MFMAs (still ahead of the barrier)
# baseline (speedup 1.0000x reference)
; #define PG8_LAS __attribute__((address_space(3)))
; #define PG8_STAGE(bufoff, gbase, voff) do { _Pragma("unroll") for (int _i = 0; _i < 2; ++_i) \
;         __builtin_amdgcn_global_load_lds((const unsigned*)((const char*)(gbase) + (voff)[_i]), (PG8_LAS unsigned*)(lds + (bufoff) + ldsw + _i * 8192), 16, 0, 0); } while (0)
; #define PG8_LDA(dst, b, h) do { _Pragma("unroll") for (int m = 0; m < 4; ++m) _Pragma("unroll") for (int k = 0; k < 2; ++k) dst[m][k] = *(const PG8_LAS bf16x8*)(lds + PG8_SA(b, h) + aoff + m * 2048 + k * 1024); } while (0)
; #define PG8_LDB(dst, b, h) do { _Pragma("unroll") for (int n = 0; n < 2; ++n) _Pragma("unroll") for (int k = 0; k < 2; ++k) dst[n][k] = *(const PG8_LAS bf16x8*)(lds + PG8_SB(b, h) + boff + n * 2048 + k * 1024); } while (0)
; #define PG8_WAIT_V(n) asm volatile("s_waitcnt vmcnt(" #n ")" ::: "memory")
; template <class Epi, class Sched, bool ALIGN_EPI = false, bool SP2 = false, bool ABLK = false, bool BBLK = false>
; __device__ __forceinline__ void gemm_phase(PG8_LAS unsigned char* lds, const Gemm g, const Sched& S, const Epi& E) {
;     ...
;         const bool has_next = S.next(ui + 1, nxt);
;         PG8_LAS unsigned char* const rs_area = lds + STAGE_BYTES + wid * 512;
;         E.stage(cur, rs_area, wr, lane);
;         const char* nA = has_next ? (const char*)g.A + (size_t)nxt.pm * tstep : cA; const char* nB = has_next ? (const char*)g.Bt + (size_t)nxt.pn * tstep : cB;
;         for (int t = 0; t < nt; t += 2) {
;             const bool last = (t == nt - 2);
;             const char* a1 = cA + (size_t)(t + 1) * kstepA;
;             const char* a2 = last ? nA : cA + (size_t)(t + 2) * kstepA; const char* b2 = last ? nB : cB + (size_t)(t + 2) * kstepB;
;             const char* a3 = a2 + kstepA; const char* b3 = b2 + kstepB;
;             if (last && has_next) S.a_ready(nxt);
;             if constexpr (SP2) {
;             PG8_LDB(B0, 0, 0); PG8_LDB(B1, 0, 1); PG8_SCHED; PG8_LDA(At, 0, 0); PG8_STAGE(PG8_SA(1, 1), a1 + hstepA, voffA);
;             PG8_WAIT_V(8); PG8_WAIT_L(0); PG8_BAR; PG8_MMA(0, 0, At, B0); PG8_MMA(0, 1, At, B1); PG8_BAR; PG8_SCHED;
;             PG8_LDA(At, 0, 1); PG8_STAGE(PG8_SB(0, 0), b2, voffB); PG8_STAGE(PG8_SB(0, 1), b2 + hstepB, voffB); PG8_STAGE(PG8_SA(0, 0), a2, voffA);
;             PG8_WAIT_V(8); PG8_WAIT_L(0); PG8_BAR; PG8_MMA(1, 0, At, B0); PG8_MMA(1, 1, At, B1); PG8_BAR; PG8_SCHED;
.LBB0_184:
	s_lshl_b32 s10, s18, 8
	s_ashr_i32 s11, s10, 31
	s_mov_b32 m0, s64
	v_lshl_add_u64 v[4:5], s[10:11], 2, v[144:145]
	global_load_lds_dword v[4:5], off
	v_lshl_add_u64 v[4:5], v[4:5], 0, s[90:91]
	s_add_i32 m0, s64, 0x100
	s_ashr_i32 s9, s8, 31
	global_load_lds_dword v[4:5], off
	s_lshl_b64 s[10:11], s[8:9], 20
	v_readlane_b32 s16, v252, 27
	v_readlane_b32 s17, v252, 28
	s_add_u32 s10, s16, s10
	s_addc_u32 s11, s17, s11
	s_and_b64 s[16:17], s[2:3], exec
	s_cselect_b32 s9, s11, s21
	s_cselect_b32 s70, s10, s20
	s_ashr_i32 s7, s6, 31
	s_lshl_b64 s[16:17], s[6:7], 20
	s_add_u32 s16, s29, s16
	s_addc_u32 s17, s30, s17
	s_and_b64 s[24:25], s[2:3], exec
	s_cselect_b32 s7, s17, s23
	s_cselect_b32 s71, s16, s22
	s_add_u32 s20, s20, 0xc000
	s_addc_u32 s21, s21, 0
	s_add_u32 s77, s22, 0x10000
	s_addc_u32 vcc_lo, s23, 0
	s_mov_b32 vcc_hi, -2
	s_add_u32 s13, s20, 0x4000
	s_addc_u32 s22, s21, 0
	s_cmp_eq_u32 vcc_hi, 28
	s_cselect_b32 s26, s70, s13
	s_cselect_b32 s27, s9, s22
	s_cselect_b32 s24, s71, s77
	s_cselect_b32 s25, s7, vcc_lo
	s_add_u32 s22, s26, 0x8000
	s_addc_u32 s23, s27, 0
	s_add_i32 s13, 0, 0x10000
	v_add_u32_e32 v36, s13, v160
	s_add_i32 s88, 0, 0x14000
	ds_read_b128 v[152:155], v36
	ds_read_b128 v[156:159], v36 offset:1024
	ds_read_b128 v[162:165], v36 offset:2048
	ds_read_b128 v[166:169], v36 offset:3072
	v_add_u32_e32 v36, s88, v160
	ds_read_b128 v[170:173], v36
	ds_read_b128 v[174:177], v36 offset:1024
	ds_read_b128 v[178:181], v36 offset:2048
	ds_read_b128 v[182:185], v36 offset:3072
	s_add_i32 m0, s19, 0xc000
	ds_read_b128 v[186:189], v161
	ds_read_b128 v[190:193], v161 offset:1024
	ds_read_b128 v[194:197], v161 offset:2048
	ds_read_b128 v[198:201], v161 offset:3072
	ds_read_b128 v[202:205], v161 offset:4096
	ds_read_b128 v[206:209], v161 offset:5120
	ds_read_b128 v[210:213], v161 offset:6144
	ds_read_b128 v[214:217], v161 offset:7168
	global_load_lds_dwordx4 v148, s[20:21]
	s_add_i32 m0, s19, 0xe000
	s_nop 0
	global_load_lds_dwordx4 v150, s[20:21]
	s_waitcnt lgkmcnt(0)
	v_mfma_f32_16x16x32_bf16 v[132:135], v[152:155], v[186:189], 0
	v_mfma_f32_16x16x32_bf16 v[132:135], v[156:159], v[190:193], v[132:135]
	v_mfma_f32_16x16x32_bf16 v[128:131], v[166:169], v[190:193], 0
	v_mfma_f32_16x16x32_bf16 v[128:131], v[162:165], v[186:189], v[128:131]
	s_waitcnt vmcnt(8)
	s_barrier
	s_setprio 1
	v_mfma_f32_16x16x32_bf16 v[112:115], v[162:165], v[194:197], 0
	v_mfma_f32_16x16x32_bf16 v[112:115], v[166:169], v[198:201], v[112:115]
	v_mfma_f32_16x16x32_bf16 v[116:119], v[156:159], v[198:201], 0
	v_mfma_f32_16x16x32_bf16 v[116:119], v[152:155], v[194:197], v[116:119]
	v_mfma_f32_16x16x32_bf16 v[100:103], v[152:155], v[202:205], 0
	v_mfma_f32_16x16x32_bf16 v[100:103], v[156:159], v[206:209], v[100:103]
	v_mfma_f32_16x16x32_bf16 v[96:99], v[166:169], v[206:209], 0
	v_mfma_f32_16x16x32_bf16 v[96:99], v[162:165], v[202:205], v[96:99]
	v_mfma_f32_16x16x32_bf16 v[80:83], v[162:165], v[210:213], 0
	v_mfma_f32_16x16x32_bf16 v[80:83], v[166:169], v[214:217], v[80:83]
	v_mfma_f32_16x16x32_bf16 v[84:87], v[156:159], v[214:217], 0
	v_mfma_f32_16x16x32_bf16 v[84:87], v[152:155], v[210:213], v[84:87]
	v_mfma_f32_16x16x32_bf16 v[76:79], v[170:173], v[210:213], 0
	v_mfma_f32_16x16x32_bf16 v[76:79], v[174:177], v[214:217], v[76:79]
	v_mfma_f32_16x16x32_bf16 v[124:127], v[174:177], v[190:193], 0
	v_mfma_f32_16x16x32_bf16 v[124:127], v[170:173], v[186:189], v[124:127]
	v_mfma_f32_16x16x32_bf16 v[120:123], v[178:181], v[186:189], 0
	v_mfma_f32_16x16x32_bf16 v[120:123], v[182:185], v[190:193], v[120:123]
	v_mfma_f32_16x16x32_bf16 v[104:107], v[182:185], v[198:201], 0
	v_mfma_f32_16x16x32_bf16 v[104:107], v[178:181], v[194:197], v[104:107]
	v_mfma_f32_16x16x32_bf16 v[108:111], v[170:173], v[194:197], 0
	v_mfma_f32_16x16x32_bf16 v[108:111], v[174:177], v[198:201], v[108:111]
	v_mfma_f32_16x16x32_bf16 v[92:95], v[174:177], v[206:209], 0
	v_mfma_f32_16x16x32_bf16 v[92:95], v[170:173], v[202:205], v[92:95]
	v_mfma_f32_16x16x32_bf16 v[88:91], v[178:181], v[202:205], 0
	v_mfma_f32_16x16x32_bf16 v[88:91], v[182:185], v[206:209], v[88:91]
	v_mfma_f32_16x16x32_bf16 v[72:75], v[182:185], v[214:217], 0
	v_mfma_f32_16x16x32_bf16 v[72:75], v[178:181], v[210:213], v[72:75]
	s_setprio 0
	s_barrier
	s_add_i32 s13, s13, s31
	s_mov_b32 m0, s13
	ds_read_b128 v[186:189], v161 offset:16384
	ds_read_b128 v[190:193], v161 offset:17408
	ds_read_b128 v[194:197], v161 offset:18432
	ds_read_b128 v[198:201], v161 offset:19456
	ds_read_b128 v[202:205], v161 offset:20480
	ds_read_b128 v[206:209], v161 offset:21504
	ds_read_b128 v[210:213], v161 offset:22528
	ds_read_b128 v[214:217], v161 offset:23552
	global_load_lds_dwordx4 v140, s[24:25]
	s_add_i32 m0, s13, 0x2000
	s_add_u32 s68, s24, 0x4000
	s_addc_u32 s69, s25, 0
	s_add_i32 s13, s88, s31
	global_load_lds_dwordx4 v136, s[24:25]
	s_mov_b32 m0, s13
	s_nop 0
	global_load_lds_dwordx4 v140, s[68:69]
	s_add_i32 m0, s13, 0x2000
	s_nop 0
	global_load_lds_dwordx4 v136, s[68:69]
	s_mov_b32 m0, s19
	s_nop 0
	global_load_lds_dwordx4 v142, s[26:27]
	s_mov_b32 m0, s35
	s_nop 0
	global_load_lds_dwordx4 v138, s[26:27]
	s_waitcnt lgkmcnt(0)
	v_mfma_f32_16x16x32_bf16 v[68:71], v[152:155], v[186:189], 0
	v_mfma_f32_16x16x32_bf16 v[68:71], v[156:159], v[190:193], v[68:71]
	v_mfma_f32_16x16x32_bf16 v[64:67], v[166:169], v[190:193], 0
	v_mfma_f32_16x16x32_bf16 v[64:67], v[162:165], v[186:189], v[64:67]
	s_waitcnt vmcnt(8)
	s_barrier
; #define PG8_STAGE(bufoff, gbase, voff) do { _Pragma("unroll") for (int _i = 0; _i < 2; ++_i) \
;         __builtin_amdgcn_global_load_lds((const unsigned*)((const char*)(gbase) + (voff)[_i]), (PG8_LAS unsigned*)(lds + (bufoff) + ldsw + _i * 8192), 16, 0, 0); } while (0)
; #define PG8_LDA(dst, b, h) do { _Pragma("unroll") for (int m = 0; m < 4; ++m) _Pragma("unroll") for (int k = 0; k < 2; ++k) dst[m][k] = *(const PG8_LAS bf16x8*)(lds + PG8_SA(b, h) + aoff + m * 2048 + k * 1024); } while (0)
; #define PG8_LDB(dst, b, h) do { _Pragma("unroll") for (int n = 0; n < 2; ++n) _Pragma("unroll") for (int k = 0; k < 2; ++k) dst[n][k] = *(const PG8_LAS bf16x8*)(lds + PG8_SB(b, h) + boff + n * 2048 + k * 1024); } while (0)
; #define PG8_MMA(ai, bj, At, Bt) do { __builtin_amdgcn_s_setprio(1); _Pragma("unroll") for (int m = 0; m < 4; ++m) _Pragma("unroll") for (int n = 0; n < 2; ++n) _Pragma("unroll") for (int k = 0; k < 2; ++k) \
;         acc[ai][bj][m][n] = __builtin_amdgcn_mfma_f32_16x16x32_bf16(Bt[n][k], At[m][k], acc[ai][bj][m][n], 0, 0, 0); __builtin_amdgcn_s_setprio(0); } while (0)
; #define PG8_WAIT_V(n) asm volatile("s_waitcnt vmcnt(" #n ")" ::: "memory")
; #define PG8_WAIT_L(n) asm volatile("s_waitcnt lgkmcnt(" #n ")" ::: "memory")
; #define PG8_BAR __builtin_amdgcn_s_barrier()
; #define PG8_SCHED __builtin_amdgcn_sched_barrier(0)
; template <class Epi, class Sched, bool ALIGN_EPI = false, bool SP2 = false, bool ABLK = false, bool BBLK = false>
; __device__ __forceinline__ void gemm_phase(PG8_LAS unsigned char* lds, const Gemm g, const Sched& S, const Epi& E) {
;     ...
;             PG8_WAIT_V(8); PG8_WAIT_L(0); PG8_BAR; PG8_MMA(1, 0, At, B0); PG8_MMA(1, 1, At, B1); PG8_BAR; PG8_SCHED;
;             PG8_LDB(B0, 1, 0); PG8_LDB(B1, 1, 1); PG8_SCHED; PG8_LDA(At, 1, 0); PG8_STAGE(PG8_SA(0, 1), a2 + hstepA, voffA);
;             PG8_WAIT_V(8); PG8_WAIT_L(0); PG8_BAR; PG8_MMA(0, 0, At, B0); PG8_MMA(0, 1, At, B1); PG8_BAR; PG8_SCHED;
	s_setprio 1
	v_mfma_f32_16x16x32_bf16 v[48:51], v[162:165], v[194:197], 0
	v_mfma_f32_16x16x32_bf16 v[48:51], v[166:169], v[198:201], v[48:51]
	v_mfma_f32_16x16x32_bf16 v[52:55], v[156:159], v[198:201], 0
	v_mfma_f32_16x16x32_bf16 v[52:55], v[152:155], v[194:197], v[52:55]
	v_mfma_f32_16x16x32_bf16 v[32:35], v[152:155], v[202:205], 0
	v_mfma_f32_16x16x32_bf16 v[32:35], v[156:159], v[206:209], v[32:35]
	v_mfma_f32_16x16x32_bf16 v[28:31], v[166:169], v[206:209], 0
	v_mfma_f32_16x16x32_bf16 v[28:31], v[162:165], v[202:205], v[28:31]
	v_mfma_f32_16x16x32_bf16 v[12:15], v[162:165], v[210:213], 0
	v_mfma_f32_16x16x32_bf16 v[12:15], v[166:169], v[214:217], v[12:15]
	v_mfma_f32_16x16x32_bf16 v[16:19], v[156:159], v[214:217], 0
	v_mfma_f32_16x16x32_bf16 v[16:19], v[152:155], v[210:213], v[16:19]
	v_mfma_f32_16x16x32_bf16 v[8:11], v[170:173], v[210:213], 0
	v_mfma_f32_16x16x32_bf16 v[8:11], v[174:177], v[214:217], v[8:11]
	v_mfma_f32_16x16x32_bf16 v[60:63], v[174:177], v[190:193], 0
	v_mfma_f32_16x16x32_bf16 v[60:63], v[170:173], v[186:189], v[60:63]
	v_mfma_f32_16x16x32_bf16 v[56:59], v[178:181], v[186:189], 0
	v_mfma_f32_16x16x32_bf16 v[56:59], v[182:185], v[190:193], v[56:59]
	v_mfma_f32_16x16x32_bf16 v[40:43], v[182:185], v[198:201], 0
	v_mfma_f32_16x16x32_bf16 v[40:43], v[178:181], v[194:197], v[40:43]
	v_mfma_f32_16x16x32_bf16 v[44:47], v[170:173], v[194:197], 0
	v_mfma_f32_16x16x32_bf16 v[44:47], v[174:177], v[198:201], v[44:47]
	v_mfma_f32_16x16x32_bf16 v[24:27], v[174:177], v[206:209], 0
	v_mfma_f32_16x16x32_bf16 v[24:27], v[170:173], v[202:205], v[24:27]
	v_mfma_f32_16x16x32_bf16 v[20:23], v[178:181], v[202:205], 0
	v_mfma_f32_16x16x32_bf16 v[20:23], v[182:185], v[206:209], v[20:23]
	v_mfma_f32_16x16x32_bf16 v[4:7], v[182:185], v[214:217], 0
	v_mfma_f32_16x16x32_bf16 v[4:7], v[178:181], v[210:213], v[4:7]
	s_setprio 0
	s_barrier
	s_add_i32 s13, 0, 0x18000
	v_add_u32_e32 v36, s13, v160
	s_add_i32 s68, 0, 0x1c000
	ds_read_b128 v[152:155], v36
	ds_read_b128 v[156:159], v36 offset:1024
	ds_read_b128 v[162:165], v36 offset:2048
	ds_read_b128 v[166:169], v36 offset:3072
	v_add_u32_e32 v36, s68, v160
	ds_read_b128 v[170:173], v36
	ds_read_b128 v[174:177], v36 offset:1024
	ds_read_b128 v[178:181], v36 offset:2048
	ds_read_b128 v[182:185], v36 offset:3072
	s_add_u32 s26, s26, 0x4000
	s_addc_u32 s27, s27, 0
	s_mov_b32 m0, s36
	ds_read_b128 v[186:189], v161 offset:32768
	ds_read_b128 v[190:193], v161 offset:33792
	ds_read_b128 v[194:197], v161 offset:34816
	ds_read_b128 v[198:201], v161 offset:35840
	ds_read_b128 v[202:205], v161 offset:36864
	ds_read_b128 v[206:209], v161 offset:37888
	ds_read_b128 v[210:213], v161 offset:38912
	ds_read_b128 v[214:217], v161 offset:39936
	global_load_lds_dwordx4 v142, s[26:27]
	s_mov_b32 m0, s37
	s_nop 0
	global_load_lds_dwordx4 v138, s[26:27]
	s_waitcnt lgkmcnt(0)
	v_mfma_f32_16x16x32_bf16 v[132:135], v[152:155], v[186:189], v[132:135]
	v_mfma_f32_16x16x32_bf16 v[132:135], v[156:159], v[190:193], v[132:135]
	v_mfma_f32_16x16x32_bf16 v[128:131], v[166:169], v[190:193], v[128:131]
	v_mfma_f32_16x16x32_bf16 v[128:131], v[162:165], v[186:189], v[128:131]
	s_waitcnt vmcnt(8)
	s_barrier
	s_setprio 1
	v_mfma_f32_16x16x32_bf16 v[112:115], v[162:165], v[194:197], v[112:115]
	v_mfma_f32_16x16x32_bf16 v[112:115], v[166:169], v[198:201], v[112:115]
	v_mfma_f32_16x16x32_bf16 v[116:119], v[156:159], v[198:201], v[116:119]
	v_mfma_f32_16x16x32_bf16 v[116:119], v[152:155], v[194:197], v[116:119]
	v_mfma_f32_16x16x32_bf16 v[100:103], v[152:155], v[202:205], v[100:103]
	v_mfma_f32_16x16x32_bf16 v[100:103], v[156:159], v[206:209], v[100:103]
	v_mfma_f32_16x16x32_bf16 v[96:99], v[166:169], v[206:209], v[96:99]
	v_mfma_f32_16x16x32_bf16 v[96:99], v[162:165], v[202:205], v[96:99]
	v_mfma_f32_16x16x32_bf16 v[80:83], v[162:165], v[210:213], v[80:83]
	v_mfma_f32_16x16x32_bf16 v[80:83], v[166:169], v[214:217], v[80:83]
	v_mfma_f32_16x16x32_bf16 v[84:87], v[156:159], v[214:217], v[84:87]
	v_mfma_f32_16x16x32_bf16 v[84:87], v[152:155], v[210:213], v[84:87]
	v_mfma_f32_16x16x32_bf16 v[76:79], v[170:173], v[210:213], v[76:79]
	v_mfma_f32_16x16x32_bf16 v[76:79], v[174:177], v[214:217], v[76:79]
	v_mfma_f32_16x16x32_bf16 v[124:127], v[174:177], v[190:193], v[124:127]
	v_mfma_f32_16x16x32_bf16 v[124:127], v[170:173], v[186:189], v[124:127]
	v_mfma_f32_16x16x32_bf16 v[120:123], v[178:181], v[186:189], v[120:123]
	v_mfma_f32_16x16x32_bf16 v[120:123], v[182:185], v[190:193], v[120:123]
	v_mfma_f32_16x16x32_bf16 v[104:107], v[182:185], v[198:201], v[104:107]
	v_mfma_f32_16x16x32_bf16 v[104:107], v[178:181], v[194:197], v[104:107]
	v_mfma_f32_16x16x32_bf16 v[108:111], v[170:173], v[194:197], v[108:111]
	v_mfma_f32_16x16x32_bf16 v[108:111], v[174:177], v[198:201], v[108:111]
	v_mfma_f32_16x16x32_bf16 v[92:95], v[174:177], v[206:209], v[92:95]
	v_mfma_f32_16x16x32_bf16 v[92:95], v[170:173], v[202:205], v[92:95]
	v_mfma_f32_16x16x32_bf16 v[88:91], v[178:181], v[202:205], v[88:91]
	v_mfma_f32_16x16x32_bf16 v[88:91], v[182:185], v[206:209], v[88:91]
	v_mfma_f32_16x16x32_bf16 v[72:75], v[182:185], v[214:217], v[72:75]
	v_mfma_f32_16x16x32_bf16 v[72:75], v[178:181], v[210:213], v[72:75]
	s_setprio 0
	s_barrier
; #define PG8_STAGE(bufoff, gbase, voff) do { _Pragma("unroll") for (int _i = 0; _i < 2; ++_i) \
;         __builtin_amdgcn_global_load_lds((const unsigned*)((const char*)(gbase) + (voff)[_i]), (PG8_LAS unsigned*)(lds + (bufoff) + ldsw + _i * 8192), 16, 0, 0); } while (0)
; #define PG8_LDA(dst, b, h) do { _Pragma("unroll") for (int m = 0; m < 4; ++m) _Pragma("unroll") for (int k = 0; k < 2; ++k) dst[m][k] = *(const PG8_LAS bf16x8*)(lds + PG8_SA(b, h) + aoff + m * 2048 + k * 1024); } while (0)
; #define PG8_LDB(dst, b, h) do { _Pragma("unroll") for (int n = 0; n < 2; ++n) _Pragma("unroll") for (int k = 0; k < 2; ++k) dst[n][k] = *(const PG8_LAS bf16x8*)(lds + PG8_SB(b, h) + boff + n * 2048 + k * 1024); } while (0)
; #define PG8_MMA(ai, bj, At, Bt) do { __builtin_amdgcn_s_setprio(1); _Pragma("unroll") for (int m = 0; m < 4; ++m) _Pragma("unroll") for (int n = 0; n < 2; ++n) _Pragma("unroll") for (int k = 0; k < 2; ++k) \
;         acc[ai][bj][m][n] = __builtin_amdgcn_mfma_f32_16x16x32_bf16(Bt[n][k], At[m][k], acc[ai][bj][m][n], 0, 0, 0); __builtin_amdgcn_s_setprio(0); } while (0)
; #define PG8_WAIT_V(n) asm volatile("s_waitcnt vmcnt(" #n ")" ::: "memory")
; #define PG8_BAR __builtin_amdgcn_s_barrier()
; template <class Epi, class Sched, bool ALIGN_EPI = false, bool SP2 = false, bool ABLK = false, bool BBLK = false>
; __device__ __forceinline__ void gemm_phase(PG8_LAS unsigned char* lds, const Gemm g, const Sched& S, const Epi& E) {
;     ...
;             const bool last = (t == nt - 2);
;             const char* a1 = cA + (size_t)(t + 1) * kstepA;
;             const char* a2 = last ? nA : cA + (size_t)(t + 2) * kstepA; const char* b2 = last ? nB : cB + (size_t)(t + 2) * kstepB;
;             const char* a3 = a2 + kstepA; const char* b3 = b2 + kstepB;
;             if (last && has_next) S.a_ready(nxt);
;             if constexpr (SP2) {
;             PG8_LDB(B0, 0, 0); PG8_LDB(B1, 0, 1); PG8_SCHED; PG8_LDA(At, 0, 0); PG8_STAGE(PG8_SA(1, 1), a1 + hstepA, voffA);
;             PG8_WAIT_V(8); PG8_WAIT_L(0); PG8_BAR; PG8_MMA(0, 0, At, B0); PG8_MMA(0, 1, At, B1); PG8_BAR; PG8_SCHED;
;     ...
;             PG8_LDA(At, 1, 1); PG8_STAGE(PG8_SB(1, 0), b3, voffB); PG8_STAGE(PG8_SB(1, 1), b3 + hstepB, voffB); PG8_STAGE(PG8_SA(1, 0), a3, voffA);
;             PG8_WAIT_V(8); PG8_WAIT_L(0); PG8_BAR; PG8_MMA(1, 0, At, B0); PG8_MMA(1, 1, At, B1); PG8_BAR; PG8_SCHED;
	s_add_u32 s26, s24, 0x8000
	s_addc_u32 s27, s25, 0
	s_add_i32 s13, s13, s31
	s_mov_b32 m0, s13
	ds_read_b128 v[186:189], v161 offset:49152
	ds_read_b128 v[190:193], v161 offset:50176
	ds_read_b128 v[194:197], v161 offset:51200
	ds_read_b128 v[198:201], v161 offset:52224
	ds_read_b128 v[202:205], v161 offset:53248
	ds_read_b128 v[206:209], v161 offset:54272
	ds_read_b128 v[210:213], v161 offset:55296
	ds_read_b128 v[214:217], v161 offset:56320
	global_load_lds_dwordx4 v140, s[26:27]
	s_add_i32 m0, s13, 0x2000
	s_add_u32 s24, s24, 0xc000
	s_addc_u32 s25, s25, 0
	s_add_i32 s13, s68, s31
	global_load_lds_dwordx4 v136, s[26:27]
	s_mov_b32 m0, s13
	s_nop 0
	global_load_lds_dwordx4 v140, s[24:25]
	s_add_i32 m0, s13, 0x2000
	s_nop 0
	global_load_lds_dwordx4 v136, s[24:25]
	s_mov_b32 m0, s62
	s_nop 0
	global_load_lds_dwordx4 v142, s[22:23]
	s_mov_b32 m0, s63
	s_nop 0
	global_load_lds_dwordx4 v138, s[22:23]
	s_waitcnt lgkmcnt(0)
	v_mfma_f32_16x16x32_bf16 v[68:71], v[152:155], v[186:189], v[68:71]
	v_mfma_f32_16x16x32_bf16 v[68:71], v[156:159], v[190:193], v[68:71]
	v_mfma_f32_16x16x32_bf16 v[64:67], v[166:169], v[190:193], v[64:67]
	v_mfma_f32_16x16x32_bf16 v[64:67], v[162:165], v[186:189], v[64:67]
	s_waitcnt vmcnt(8)
	s_barrier
	s_setprio 1
	v_mfma_f32_16x16x32_bf16 v[48:51], v[162:165], v[194:197], v[48:51]
	v_mfma_f32_16x16x32_bf16 v[48:51], v[166:169], v[198:201], v[48:51]
	v_mfma_f32_16x16x32_bf16 v[52:55], v[156:159], v[198:201], v[52:55]
	v_mfma_f32_16x16x32_bf16 v[52:55], v[152:155], v[194:197], v[52:55]
	v_mfma_f32_16x16x32_bf16 v[32:35], v[152:155], v[202:205], v[32:35]
	v_mfma_f32_16x16x32_bf16 v[32:35], v[156:159], v[206:209], v[32:35]
	v_mfma_f32_16x16x32_bf16 v[28:31], v[166:169], v[206:209], v[28:31]
	v_mfma_f32_16x16x32_bf16 v[28:31], v[162:165], v[202:205], v[28:31]
	v_mfma_f32_16x16x32_bf16 v[12:15], v[162:165], v[210:213], v[12:15]
	v_mfma_f32_16x16x32_bf16 v[12:15], v[166:169], v[214:217], v[12:15]
	v_mfma_f32_16x16x32_bf16 v[16:19], v[156:159], v[214:217], v[16:19]
	v_mfma_f32_16x16x32_bf16 v[16:19], v[152:155], v[210:213], v[16:19]
	v_mfma_f32_16x16x32_bf16 v[8:11], v[170:173], v[210:213], v[8:11]
	v_mfma_f32_16x16x32_bf16 v[8:11], v[174:177], v[214:217], v[8:11]
	v_mfma_f32_16x16x32_bf16 v[60:63], v[174:177], v[190:193], v[60:63]
	v_mfma_f32_16x16x32_bf16 v[60:63], v[170:173], v[186:189], v[60:63]
	v_mfma_f32_16x16x32_bf16 v[56:59], v[178:181], v[186:189], v[56:59]
	v_mfma_f32_16x16x32_bf16 v[56:59], v[182:185], v[190:193], v[56:59]
	v_mfma_f32_16x16x32_bf16 v[40:43], v[182:185], v[198:201], v[40:43]
	v_mfma_f32_16x16x32_bf16 v[40:43], v[178:181], v[194:197], v[40:43]
	v_mfma_f32_16x16x32_bf16 v[44:47], v[170:173], v[194:197], v[44:47]
	v_mfma_f32_16x16x32_bf16 v[44:47], v[174:177], v[198:201], v[44:47]
	v_mfma_f32_16x16x32_bf16 v[24:27], v[174:177], v[206:209], v[24:27]
	v_mfma_f32_16x16x32_bf16 v[24:27], v[170:173], v[202:205], v[24:27]
	v_mfma_f32_16x16x32_bf16 v[20:23], v[178:181], v[202:205], v[20:23]
	v_mfma_f32_16x16x32_bf16 v[20:23], v[182:185], v[206:209], v[20:23]
	v_mfma_f32_16x16x32_bf16 v[4:7], v[182:185], v[214:217], v[4:7]
	v_mfma_f32_16x16x32_bf16 v[4:7], v[178:181], v[210:213], v[4:7]
	s_setprio 0
	s_barrier
	s_add_i32 vcc_hi, vcc_hi, 2
	s_add_u32 s20, s20, 0x10000
	s_addc_u32 s21, s21, 0
	s_add_u32 s77, s77, 0x10000
	s_addc_u32 vcc_lo, vcc_lo, 0
	s_cmp_gt_u32 vcc_hi, 29
.LBB0_185:
	s_add_u32 s13, s20, 0x4000
	s_addc_u32 s22, s21, 0
	s_cmp_eq_u32 vcc_hi, 28
	s_cselect_b32 s26, s70, s13
	s_cselect_b32 s27, s9, s22
	s_cselect_b32 s24, s71, s77
	s_cselect_b32 s25, s7, vcc_lo
	s_add_u32 s22, s26, 0x8000
	s_addc_u32 s23, s27, 0
	s_add_i32 s13, 0, 0x10000
	v_add_u32_e32 v36, s13, v160
	s_add_i32 s88, 0, 0x14000
	ds_read_b128 v[152:155], v36
	ds_read_b128 v[156:159], v36 offset:1024
	ds_read_b128 v[162:165], v36 offset:2048
	ds_read_b128 v[166:169], v36 offset:3072
	v_add_u32_e32 v36, s88, v160
	ds_read_b128 v[170:173], v36
	ds_read_b128 v[174:177], v36 offset:1024
	ds_read_b128 v[178:181], v36 offset:2048
	ds_read_b128 v[182:185], v36 offset:3072
	s_add_i32 m0, s19, 0xc000
	ds_read_b128 v[186:189], v161
	ds_read_b128 v[190:193], v161 offset:1024
	ds_read_b128 v[194:197], v161 offset:2048
	ds_read_b128 v[198:201], v161 offset:3072
	ds_read_b128 v[202:205], v161 offset:4096
	ds_read_b128 v[206:209], v161 offset:5120
	ds_read_b128 v[210:213], v161 offset:6144
	ds_read_b128 v[214:217], v161 offset:7168
	global_load_lds_dwordx4 v148, s[20:21]
	s_add_i32 m0, s19, 0xe000
	s_nop 0
	global_load_lds_dwordx4 v150, s[20:21]
	s_waitcnt lgkmcnt(0)
	v_mfma_f32_16x16x32_bf16 v[132:135], v[152:155], v[186:189], v[132:135]
	v_mfma_f32_16x16x32_bf16 v[132:135], v[156:159], v[190:193], v[132:135]
	v_mfma_f32_16x16x32_bf16 v[128:131], v[166:169], v[190:193], v[128:131]
	v_mfma_f32_16x16x32_bf16 v[128:131], v[162:165], v[186:189], v[128:131]
	s_waitcnt vmcnt(8)
	s_barrier
; #define PG8_STAGE(bufoff, gbase, voff) do { _Pragma("unroll") for (int _i = 0; _i < 2; ++_i) \
;         __builtin_amdgcn_global_load_lds((const unsigned*)((const char*)(gbase) + (voff)[_i]), (PG8_LAS unsigned*)(lds + (bufoff) + ldsw + _i * 8192), 16, 0, 0); } while (0)
; #define PG8_LDA(dst, b, h) do { _Pragma("unroll") for (int m = 0; m < 4; ++m) _Pragma("unroll") for (int k = 0; k < 2; ++k) dst[m][k] = *(const PG8_LAS bf16x8*)(lds + PG8_SA(b, h) + aoff + m * 2048 + k * 1024); } while (0)
; #define PG8_LDB(dst, b, h) do { _Pragma("unroll") for (int n = 0; n < 2; ++n) _Pragma("unroll") for (int k = 0; k < 2; ++k) dst[n][k] = *(const PG8_LAS bf16x8*)(lds + PG8_SB(b, h) + boff + n * 2048 + k * 1024); } while (0)
; #define PG8_MMA(ai, bj, At, Bt) do { __builtin_amdgcn_s_setprio(1); _Pragma("unroll") for (int m = 0; m < 4; ++m) _Pragma("unroll") for (int n = 0; n < 2; ++n) _Pragma("unroll") for (int k = 0; k < 2; ++k) \
;         acc[ai][bj][m][n] = __builtin_amdgcn_mfma_f32_16x16x32_bf16(Bt[n][k], At[m][k], acc[ai][bj][m][n], 0, 0, 0); __builtin_amdgcn_s_setprio(0); } while (0)
; #define PG8_WAIT_V(n) asm volatile("s_waitcnt vmcnt(" #n ")" ::: "memory")
; #define PG8_WAIT_L(n) asm volatile("s_waitcnt lgkmcnt(" #n ")" ::: "memory")
; #define PG8_BAR __builtin_amdgcn_s_barrier()
; #define PG8_SCHED __builtin_amdgcn_sched_barrier(0)
; template <class Epi, class Sched, bool ALIGN_EPI = false, bool SP2 = false, bool ABLK = false, bool BBLK = false>
; __device__ __forceinline__ void gemm_phase(PG8_LAS unsigned char* lds, const Gemm g, const Sched& S, const Epi& E) {
;     ...
;             PG8_LDB(B0, 0, 0); PG8_LDB(B1, 0, 1); PG8_SCHED; PG8_LDA(At, 0, 0); PG8_STAGE(PG8_SA(1, 1), a1 + hstepA, voffA);
;             PG8_WAIT_V(8); PG8_WAIT_L(0); PG8_BAR; PG8_MMA(0, 0, At, B0); PG8_MMA(0, 1, At, B1); PG8_BAR; PG8_SCHED;
;             PG8_LDA(At, 0, 1); PG8_STAGE(PG8_SB(0, 0), b2, voffB); PG8_STAGE(PG8_SB(0, 1), b2 + hstepB, voffB); PG8_STAGE(PG8_SA(0, 0), a2, voffA);
;             PG8_WAIT_V(8); PG8_WAIT_L(0); PG8_BAR; PG8_MMA(1, 0, At, B0); PG8_MMA(1, 1, At, B1); PG8_BAR; PG8_SCHED;
	s_setprio 1
	v_mfma_f32_16x16x32_bf16 v[112:115], v[162:165], v[194:197], v[112:115]
	v_mfma_f32_16x16x32_bf16 v[112:115], v[166:169], v[198:201], v[112:115]
	v_mfma_f32_16x16x32_bf16 v[116:119], v[156:159], v[198:201], v[116:119]
	v_mfma_f32_16x16x32_bf16 v[116:119], v[152:155], v[194:197], v[116:119]
	v_mfma_f32_16x16x32_bf16 v[100:103], v[152:155], v[202:205], v[100:103]
	v_mfma_f32_16x16x32_bf16 v[100:103], v[156:159], v[206:209], v[100:103]
	v_mfma_f32_16x16x32_bf16 v[96:99], v[166:169], v[206:209], v[96:99]
	v_mfma_f32_16x16x32_bf16 v[96:99], v[162:165], v[202:205], v[96:99]
	v_mfma_f32_16x16x32_bf16 v[80:83], v[162:165], v[210:213], v[80:83]
	v_mfma_f32_16x16x32_bf16 v[80:83], v[166:169], v[214:217], v[80:83]
	v_mfma_f32_16x16x32_bf16 v[84:87], v[156:159], v[214:217], v[84:87]
	v_mfma_f32_16x16x32_bf16 v[84:87], v[152:155], v[210:213], v[84:87]
	v_mfma_f32_16x16x32_bf16 v[76:79], v[170:173], v[210:213], v[76:79]
	v_mfma_f32_16x16x32_bf16 v[76:79], v[174:177], v[214:217], v[76:79]
	v_mfma_f32_16x16x32_bf16 v[124:127], v[174:177], v[190:193], v[124:127]
	v_mfma_f32_16x16x32_bf16 v[124:127], v[170:173], v[186:189], v[124:127]
	v_mfma_f32_16x16x32_bf16 v[120:123], v[178:181], v[186:189], v[120:123]
	v_mfma_f32_16x16x32_bf16 v[120:123], v[182:185], v[190:193], v[120:123]
	v_mfma_f32_16x16x32_bf16 v[104:107], v[182:185], v[198:201], v[104:107]
	v_mfma_f32_16x16x32_bf16 v[104:107], v[178:181], v[194:197], v[104:107]
	v_mfma_f32_16x16x32_bf16 v[108:111], v[170:173], v[194:197], v[108:111]
	v_mfma_f32_16x16x32_bf16 v[108:111], v[174:177], v[198:201], v[108:111]
	v_mfma_f32_16x16x32_bf16 v[92:95], v[174:177], v[206:209], v[92:95]
	v_mfma_f32_16x16x32_bf16 v[92:95], v[170:173], v[202:205], v[92:95]
	v_mfma_f32_16x16x32_bf16 v[88:91], v[178:181], v[202:205], v[88:91]
	v_mfma_f32_16x16x32_bf16 v[88:91], v[182:185], v[206:209], v[88:91]
	v_mfma_f32_16x16x32_bf16 v[72:75], v[182:185], v[214:217], v[72:75]
	v_mfma_f32_16x16x32_bf16 v[72:75], v[178:181], v[210:213], v[72:75]
	s_setprio 0
	s_barrier
	s_add_i32 s13, s13, s31
	s_mov_b32 m0, s13
	ds_read_b128 v[186:189], v161 offset:16384
	ds_read_b128 v[190:193], v161 offset:17408
	ds_read_b128 v[194:197], v161 offset:18432
	ds_read_b128 v[198:201], v161 offset:19456
	ds_read_b128 v[202:205], v161 offset:20480
	ds_read_b128 v[206:209], v161 offset:21504
	ds_read_b128 v[210:213], v161 offset:22528
	ds_read_b128 v[214:217], v161 offset:23552
	global_load_lds_dwordx4 v140, s[24:25]
	s_add_i32 m0, s13, 0x2000
	s_add_u32 s68, s24, 0x4000
	s_addc_u32 s69, s25, 0
	s_add_i32 s13, s88, s31
	global_load_lds_dwordx4 v136, s[24:25]
	s_mov_b32 m0, s13
	s_nop 0
	global_load_lds_dwordx4 v140, s[68:69]
	s_add_i32 m0, s13, 0x2000
	s_nop 0
	global_load_lds_dwordx4 v136, s[68:69]
	s_mov_b32 m0, s19
	s_nop 0
	global_load_lds_dwordx4 v142, s[26:27]
	s_mov_b32 m0, s35
	s_nop 0
	global_load_lds_dwordx4 v138, s[26:27]
	s_waitcnt lgkmcnt(0)
	v_mfma_f32_16x16x32_bf16 v[68:71], v[152:155], v[186:189], v[68:71]
	v_mfma_f32_16x16x32_bf16 v[68:71], v[156:159], v[190:193], v[68:71]
	v_mfma_f32_16x16x32_bf16 v[64:67], v[166:169], v[190:193], v[64:67]
	v_mfma_f32_16x16x32_bf16 v[64:67], v[162:165], v[186:189], v[64:67]
	s_waitcnt vmcnt(8)
	s_barrier
	s_setprio 1
	v_mfma_f32_16x16x32_bf16 v[48:51], v[162:165], v[194:197], v[48:51]
	v_mfma_f32_16x16x32_bf16 v[48:51], v[166:169], v[198:201], v[48:51]
	v_mfma_f32_16x16x32_bf16 v[52:55], v[156:159], v[198:201], v[52:55]
	v_mfma_f32_16x16x32_bf16 v[52:55], v[152:155], v[194:197], v[52:55]
	v_mfma_f32_16x16x32_bf16 v[32:35], v[152:155], v[202:205], v[32:35]
	v_mfma_f32_16x16x32_bf16 v[32:35], v[156:159], v[206:209], v[32:35]
	v_mfma_f32_16x16x32_bf16 v[28:31], v[166:169], v[206:209], v[28:31]
	v_mfma_f32_16x16x32_bf16 v[28:31], v[162:165], v[202:205], v[28:31]
	v_mfma_f32_16x16x32_bf16 v[12:15], v[162:165], v[210:213], v[12:15]
	v_mfma_f32_16x16x32_bf16 v[12:15], v[166:169], v[214:217], v[12:15]
	v_mfma_f32_16x16x32_bf16 v[16:19], v[156:159], v[214:217], v[16:19]
	v_mfma_f32_16x16x32_bf16 v[16:19], v[152:155], v[210:213], v[16:19]
	v_mfma_f32_16x16x32_bf16 v[8:11], v[170:173], v[210:213], v[8:11]
	v_mfma_f32_16x16x32_bf16 v[8:11], v[174:177], v[214:217], v[8:11]
	v_mfma_f32_16x16x32_bf16 v[60:63], v[174:177], v[190:193], v[60:63]
	v_mfma_f32_16x16x32_bf16 v[60:63], v[170:173], v[186:189], v[60:63]
	v_mfma_f32_16x16x32_bf16 v[56:59], v[178:181], v[186:189], v[56:59]
	v_mfma_f32_16x16x32_bf16 v[56:59], v[182:185], v[190:193], v[56:59]
	v_mfma_f32_16x16x32_bf16 v[40:43], v[182:185], v[198:201], v[40:43]
	v_mfma_f32_16x16x32_bf16 v[40:43], v[178:181], v[194:197], v[40:43]
	v_mfma_f32_16x16x32_bf16 v[44:47], v[170:173], v[194:197], v[44:47]
	v_mfma_f32_16x16x32_bf16 v[44:47], v[174:177], v[198:201], v[44:47]
	v_mfma_f32_16x16x32_bf16 v[24:27], v[174:177], v[206:209], v[24:27]
	v_mfma_f32_16x16x32_bf16 v[24:27], v[170:173], v[202:205], v[24:27]
	v_mfma_f32_16x16x32_bf16 v[20:23], v[178:181], v[202:205], v[20:23]
	v_mfma_f32_16x16x32_bf16 v[20:23], v[182:185], v[206:209], v[20:23]
	v_mfma_f32_16x16x32_bf16 v[4:7], v[182:185], v[214:217], v[4:7]
	v_mfma_f32_16x16x32_bf16 v[4:7], v[178:181], v[210:213], v[4:7]
	s_setprio 0
	s_barrier
; #define PG8_STAGE(bufoff, gbase, voff) do { _Pragma("unroll") for (int _i = 0; _i < 2; ++_i) \
;         __builtin_amdgcn_global_load_lds((const unsigned*)((const char*)(gbase) + (voff)[_i]), (PG8_LAS unsigned*)(lds + (bufoff) + ldsw + _i * 8192), 16, 0, 0); } while (0)
; #define PG8_LDA(dst, b, h) do { _Pragma("unroll") for (int m = 0; m < 4; ++m) _Pragma("unroll") for (int k = 0; k < 2; ++k) dst[m][k] = *(const PG8_LAS bf16x8*)(lds + PG8_SA(b, h) + aoff + m * 2048 + k * 1024); } while (0)
; #define PG8_LDB(dst, b, h) do { _Pragma("unroll") for (int n = 0; n < 2; ++n) _Pragma("unroll") for (int k = 0; k < 2; ++k) dst[n][k] = *(const PG8_LAS bf16x8*)(lds + PG8_SB(b, h) + boff + n * 2048 + k * 1024); } while (0)
; #define PG8_MMA(ai, bj, At, Bt) do { __builtin_amdgcn_s_setprio(1); _Pragma("unroll") for (int m = 0; m < 4; ++m) _Pragma("unroll") for (int n = 0; n < 2; ++n) _Pragma("unroll") for (int k = 0; k < 2; ++k) \
;         acc[ai][bj][m][n] = __builtin_amdgcn_mfma_f32_16x16x32_bf16(Bt[n][k], At[m][k], acc[ai][bj][m][n], 0, 0, 0); __builtin_amdgcn_s_setprio(0); } while (0)
; #define PG8_WAIT_V(n) asm volatile("s_waitcnt vmcnt(" #n ")" ::: "memory")
; #define PG8_BAR __builtin_amdgcn_s_barrier()
; template <class Epi, class Sched, bool ALIGN_EPI = false, bool SP2 = false, bool ABLK = false, bool BBLK = false>
; __device__ __forceinline__ void gemm_phase(PG8_LAS unsigned char* lds, const Gemm g, const Sched& S, const Epi& E) {
;     ...
;         for (int t = 0; t < nt; t += 2) {
;             const bool last = (t == nt - 2);
;             const char* a1 = cA + (size_t)(t + 1) * kstepA;
;             const char* a2 = last ? nA : cA + (size_t)(t + 2) * kstepA; const char* b2 = last ? nB : cB + (size_t)(t + 2) * kstepB;
;             const char* a3 = a2 + kstepA; const char* b3 = b2 + kstepB;
;     ...
;             PG8_LDB(B0, 1, 0); PG8_LDB(B1, 1, 1); PG8_SCHED; PG8_LDA(At, 1, 0); PG8_STAGE(PG8_SA(0, 1), a2 + hstepA, voffA);
;             PG8_WAIT_V(8); PG8_WAIT_L(0); PG8_BAR; PG8_MMA(0, 0, At, B0); PG8_MMA(0, 1, At, B1); PG8_BAR; PG8_SCHED;
;             PG8_LDA(At, 1, 1); PG8_STAGE(PG8_SB(1, 0), b3, voffB); PG8_STAGE(PG8_SB(1, 1), b3 + hstepB, voffB); PG8_STAGE(PG8_SA(1, 0), a3, voffA);
;             PG8_WAIT_V(8); PG8_WAIT_L(0); PG8_BAR; PG8_MMA(1, 0, At, B0); PG8_MMA(1, 1, At, B1); PG8_BAR; PG8_SCHED;
;     ...
;         if constexpr (ALIGN_EPI) { if (wr == 0) PG8_BAR; }
	s_add_i32 s13, 0, 0x18000
	v_add_u32_e32 v36, s13, v160
	s_add_i32 s68, 0, 0x1c000
	ds_read_b128 v[152:155], v36
	ds_read_b128 v[156:159], v36 offset:1024
	ds_read_b128 v[162:165], v36 offset:2048
	ds_read_b128 v[166:169], v36 offset:3072
	v_add_u32_e32 v36, s68, v160
	ds_read_b128 v[170:173], v36
	ds_read_b128 v[174:177], v36 offset:1024
	ds_read_b128 v[178:181], v36 offset:2048
	ds_read_b128 v[182:185], v36 offset:3072
	s_add_u32 s26, s26, 0x4000
	s_addc_u32 s27, s27, 0
	s_mov_b32 m0, s36
	ds_read_b128 v[186:189], v161 offset:32768
	ds_read_b128 v[190:193], v161 offset:33792
	ds_read_b128 v[194:197], v161 offset:34816
	ds_read_b128 v[198:201], v161 offset:35840
	ds_read_b128 v[202:205], v161 offset:36864
	ds_read_b128 v[206:209], v161 offset:37888
	ds_read_b128 v[210:213], v161 offset:38912
	ds_read_b128 v[214:217], v161 offset:39936
	global_load_lds_dwordx4 v142, s[26:27]
	s_mov_b32 m0, s37
	s_nop 0
	global_load_lds_dwordx4 v138, s[26:27]
	s_waitcnt lgkmcnt(0)
	v_mfma_f32_16x16x32_bf16 v[132:135], v[152:155], v[186:189], v[132:135]
	v_mfma_f32_16x16x32_bf16 v[132:135], v[156:159], v[190:193], v[132:135]
	v_mfma_f32_16x16x32_bf16 v[128:131], v[166:169], v[190:193], v[128:131]
	v_mfma_f32_16x16x32_bf16 v[128:131], v[162:165], v[186:189], v[128:131]
	s_waitcnt vmcnt(8)
	s_barrier
	s_setprio 1
	v_mfma_f32_16x16x32_bf16 v[112:115], v[162:165], v[194:197], v[112:115]
	v_mfma_f32_16x16x32_bf16 v[112:115], v[166:169], v[198:201], v[112:115]
	v_mfma_f32_16x16x32_bf16 v[116:119], v[156:159], v[198:201], v[116:119]
	v_mfma_f32_16x16x32_bf16 v[116:119], v[152:155], v[194:197], v[116:119]
	v_mfma_f32_16x16x32_bf16 v[100:103], v[152:155], v[202:205], v[100:103]
	v_mfma_f32_16x16x32_bf16 v[100:103], v[156:159], v[206:209], v[100:103]
	v_mfma_f32_16x16x32_bf16 v[96:99], v[166:169], v[206:209], v[96:99]
	v_mfma_f32_16x16x32_bf16 v[96:99], v[162:165], v[202:205], v[96:99]
	v_mfma_f32_16x16x32_bf16 v[80:83], v[162:165], v[210:213], v[80:83]
	v_mfma_f32_16x16x32_bf16 v[80:83], v[166:169], v[214:217], v[80:83]
	v_mfma_f32_16x16x32_bf16 v[84:87], v[156:159], v[214:217], v[84:87]
	v_mfma_f32_16x16x32_bf16 v[84:87], v[152:155], v[210:213], v[84:87]
	v_mfma_f32_16x16x32_bf16 v[76:79], v[170:173], v[210:213], v[76:79]
	v_mfma_f32_16x16x32_bf16 v[76:79], v[174:177], v[214:217], v[76:79]
	v_mfma_f32_16x16x32_bf16 v[124:127], v[174:177], v[190:193], v[124:127]
	v_mfma_f32_16x16x32_bf16 v[124:127], v[170:173], v[186:189], v[124:127]
	v_mfma_f32_16x16x32_bf16 v[120:123], v[178:181], v[186:189], v[120:123]
	v_mfma_f32_16x16x32_bf16 v[120:123], v[182:185], v[190:193], v[120:123]
	v_mfma_f32_16x16x32_bf16 v[104:107], v[182:185], v[198:201], v[104:107]
	v_mfma_f32_16x16x32_bf16 v[104:107], v[178:181], v[194:197], v[104:107]
	v_mfma_f32_16x16x32_bf16 v[108:111], v[170:173], v[194:197], v[108:111]
	v_mfma_f32_16x16x32_bf16 v[108:111], v[174:177], v[198:201], v[108:111]
	v_mfma_f32_16x16x32_bf16 v[92:95], v[174:177], v[206:209], v[92:95]
	v_mfma_f32_16x16x32_bf16 v[92:95], v[170:173], v[202:205], v[92:95]
	v_mfma_f32_16x16x32_bf16 v[88:91], v[178:181], v[202:205], v[88:91]
	v_mfma_f32_16x16x32_bf16 v[88:91], v[182:185], v[206:209], v[88:91]
	v_mfma_f32_16x16x32_bf16 v[72:75], v[182:185], v[214:217], v[72:75]
	v_mfma_f32_16x16x32_bf16 v[72:75], v[178:181], v[210:213], v[72:75]
	s_setprio 0
	s_barrier
	s_add_u32 s26, s24, 0x8000
	s_addc_u32 s27, s25, 0
	s_add_i32 s13, s13, s31
	s_mov_b32 m0, s13
	ds_read_b128 v[186:189], v161 offset:49152
	ds_read_b128 v[190:193], v161 offset:50176
	ds_read_b128 v[194:197], v161 offset:51200
	ds_read_b128 v[198:201], v161 offset:52224
	ds_read_b128 v[202:205], v161 offset:53248
	ds_read_b128 v[206:209], v161 offset:54272
	ds_read_b128 v[210:213], v161 offset:55296
	ds_read_b128 v[214:217], v161 offset:56320
	global_load_lds_dwordx4 v140, s[26:27]
	s_add_i32 m0, s13, 0x2000
	s_add_u32 s24, s24, 0xc000
	s_addc_u32 s25, s25, 0
	s_add_i32 s13, s68, s31
	global_load_lds_dwordx4 v136, s[26:27]
	s_mov_b32 m0, s13
	s_nop 0
	global_load_lds_dwordx4 v140, s[24:25]
	s_add_i32 m0, s13, 0x2000
	s_nop 0
	global_load_lds_dwordx4 v136, s[24:25]
	s_mov_b32 m0, s62
	s_nop 0
	global_load_lds_dwordx4 v142, s[22:23]
	s_mov_b32 m0, s63
	s_nop 0
	global_load_lds_dwordx4 v138, s[22:23]
	s_waitcnt lgkmcnt(0)
	v_mfma_f32_16x16x32_bf16 v[68:71], v[152:155], v[186:189], v[68:71]
	v_mfma_f32_16x16x32_bf16 v[68:71], v[156:159], v[190:193], v[68:71]
	v_mfma_f32_16x16x32_bf16 v[64:67], v[166:169], v[190:193], v[64:67]
	v_mfma_f32_16x16x32_bf16 v[64:67], v[162:165], v[186:189], v[64:67]
	s_waitcnt vmcnt(8)
	s_barrier
	s_setprio 1
	v_mfma_f32_16x16x32_bf16 v[48:51], v[162:165], v[194:197], v[48:51]
	v_mfma_f32_16x16x32_bf16 v[48:51], v[166:169], v[198:201], v[48:51]
	v_mfma_f32_16x16x32_bf16 v[52:55], v[156:159], v[198:201], v[52:55]
	v_mfma_f32_16x16x32_bf16 v[52:55], v[152:155], v[194:197], v[52:55]
	v_mfma_f32_16x16x32_bf16 v[32:35], v[152:155], v[202:205], v[32:35]
	v_mfma_f32_16x16x32_bf16 v[32:35], v[156:159], v[206:209], v[32:35]
	v_mfma_f32_16x16x32_bf16 v[28:31], v[166:169], v[206:209], v[28:31]
	v_mfma_f32_16x16x32_bf16 v[28:31], v[162:165], v[202:205], v[28:31]
	v_mfma_f32_16x16x32_bf16 v[12:15], v[162:165], v[210:213], v[12:15]
	v_mfma_f32_16x16x32_bf16 v[12:15], v[166:169], v[214:217], v[12:15]
	v_mfma_f32_16x16x32_bf16 v[16:19], v[156:159], v[214:217], v[16:19]
	v_mfma_f32_16x16x32_bf16 v[16:19], v[152:155], v[210:213], v[16:19]
	v_mfma_f32_16x16x32_bf16 v[8:11], v[170:173], v[210:213], v[8:11]
	v_mfma_f32_16x16x32_bf16 v[8:11], v[174:177], v[214:217], v[8:11]
	v_mfma_f32_16x16x32_bf16 v[60:63], v[174:177], v[190:193], v[60:63]
	v_mfma_f32_16x16x32_bf16 v[60:63], v[170:173], v[186:189], v[60:63]
	v_mfma_f32_16x16x32_bf16 v[56:59], v[178:181], v[186:189], v[56:59]
	v_mfma_f32_16x16x32_bf16 v[56:59], v[182:185], v[190:193], v[56:59]
	v_mfma_f32_16x16x32_bf16 v[40:43], v[182:185], v[198:201], v[40:43]
	v_mfma_f32_16x16x32_bf16 v[40:43], v[178:181], v[194:197], v[40:43]
	v_mfma_f32_16x16x32_bf16 v[44:47], v[170:173], v[194:197], v[44:47]
	v_mfma_f32_16x16x32_bf16 v[44:47], v[174:177], v[198:201], v[44:47]
	v_mfma_f32_16x16x32_bf16 v[24:27], v[174:177], v[206:209], v[24:27]
	v_mfma_f32_16x16x32_bf16 v[24:27], v[170:173], v[202:205], v[24:27]
	v_mfma_f32_16x16x32_bf16 v[20:23], v[178:181], v[202:205], v[20:23]
	v_mfma_f32_16x16x32_bf16 v[20:23], v[182:185], v[206:209], v[20:23]
	v_mfma_f32_16x16x32_bf16 v[4:7], v[182:185], v[214:217], v[4:7]
	v_mfma_f32_16x16x32_bf16 v[4:7], v[178:181], v[210:213], v[4:7]
	s_setprio 0
	s_barrier
	s_add_i32 vcc_hi, vcc_hi, 2
	s_add_u32 s20, s20, 0x10000
	s_addc_u32 s21, s21, 0
	s_add_u32 s77, s77, 0x10000
	s_addc_u32 vcc_lo, vcc_lo, 0
	s_cmp_gt_u32 vcc_hi, 29
	s_cbranch_scc0 .LBB0_185
	s_and_b64 vcc, exec, s[4:5]
	s_cbranch_vccz .LBB0_188
	s_barrier

; #define PG8_STAGE(bufoff, gbase, voff) do { _Pragma("unroll") for (int _i = 0; _i < 2; ++_i) \
;         __builtin_amdgcn_global_load_lds((const unsigned*)((const char*)(gbase) + (voff)[_i]), (PG8_LAS unsigned*)(lds + (bufoff) + ldsw + _i * 8192), 16, 0, 0); } while (0)
; #define PG8_LDA(dst, b, h) do { _Pragma("unroll") for (int m = 0; m < 4; ++m) _Pragma("unroll") for (int k = 0; k < 2; ++k) dst[m][k] = *(const PG8_LAS bf16x8*)(lds + PG8_SA(b, h) + aoff + m * 2048 + k * 1024); } while (0)
; #define PG8_LDB(dst, b, h) do { _Pragma("unroll") for (int n = 0; n < 2; ++n) _Pragma("unroll") for (int k = 0; k < 2; ++k) dst[n][k] = *(const PG8_LAS bf16x8*)(lds + PG8_SB(b, h) + boff + n * 2048 + k * 1024); } while (0)
; #define PG8_WAIT_V(n) asm volatile("s_waitcnt vmcnt(" #n ")" ::: "memory")
; #define PG8_WAIT_L(n) asm volatile("s_waitcnt lgkmcnt(" #n ")" ::: "memory")
; #define PG8_BAR __builtin_amdgcn_s_barrier()
; #define PG8_SCHED __builtin_amdgcn_sched_barrier(0)
; template <class Epi, class Sched, bool ALIGN_EPI = false, bool SP2 = false, bool ABLK = false, bool BBLK = false>
; __device__ __forceinline__ void gemm_phase(PG8_LAS unsigned char* lds, const Gemm g, const Sched& S, const Epi& E) {
;     ...
;         const char* nA = has_next ? (const char*)g.A + (size_t)nxt.pm * tstep : cA; const char* nB = has_next ? (const char*)g.Bt + (size_t)nxt.pn * tstep : cB;
;         for (int t = 0; t < nt; t += 2) {
;             const bool last = (t == nt - 2);
;             const char* a1 = cA + (size_t)(t + 1) * kstepA;
;             const char* a2 = last ? nA : cA + (size_t)(t + 2) * kstepA; const char* b2 = last ? nB : cB + (size_t)(t + 2) * kstepB;
;             const char* a3 = a2 + kstepA; const char* b3 = b2 + kstepB;
;             if (last && has_next) S.a_ready(nxt);
;             if constexpr (SP2) {
;             PG8_LDB(B0, 0, 0); PG8_LDB(B1, 0, 1); PG8_SCHED; PG8_LDA(At, 0, 0); PG8_STAGE(PG8_SA(1, 1), a1 + hstepA, voffA);
;             PG8_WAIT_V(8); PG8_WAIT_L(0); PG8_BAR; PG8_MMA(0, 0, At, B0); PG8_MMA(0, 1, At, B1); PG8_BAR; PG8_SCHED;
;             PG8_LDA(At, 0, 1); PG8_STAGE(PG8_SB(0, 0), b2, voffB); PG8_STAGE(PG8_SB(0, 1), b2 + hstepB, voffB); PG8_STAGE(PG8_SA(0, 0), a2, voffA);
;             PG8_WAIT_V(8); PG8_WAIT_L(0); PG8_BAR; PG8_MMA(1, 0, At, B0); PG8_MMA(1, 1, At, B1); PG8_BAR; PG8_SCHED;
.LBB0_438:
	s_add_u32 s10, s10, 0xc000
	s_addc_u32 s11, s11, 0
	s_add_u32 vcc_lo, s16, 0x10000
	s_addc_u32 vcc_hi, s17, 0
	s_mov_b32 s13, -2
	s_add_u32 s16, s10, 0x4000
	s_addc_u32 s17, s11, 0
	s_cmpk_eq_i32 s13, 0x54
	s_cselect_b32 s20, s0, s16
	s_cselect_b32 s21, s1, s17
	s_cselect_b32 s18, s8, vcc_lo
	s_cselect_b32 s19, s9, vcc_hi
	s_add_u32 s16, s20, 0x8000
	s_addc_u32 s17, s21, 0
	s_add_i32 s68, 0, 0x10000
	v_add_u32_e32 v36, s68, v148
	s_add_i32 s88, 0, 0x14000
	ds_read_b128 v[152:155], v36
	ds_read_b128 v[156:159], v36 offset:1024
	ds_read_b128 v[160:163], v36 offset:2048
	ds_read_b128 v[164:167], v36 offset:3072
	v_add_u32_e32 v36, s88, v148
	ds_read_b128 v[168:171], v36
	ds_read_b128 v[172:175], v36 offset:1024
	ds_read_b128 v[176:179], v36 offset:2048
	ds_read_b128 v[180:183], v36 offset:3072
	s_add_i32 m0, s27, 0xc000
	ds_read_b128 v[184:187], v150
	ds_read_b128 v[188:191], v150 offset:1024
	ds_read_b128 v[192:195], v150 offset:2048
	ds_read_b128 v[196:199], v150 offset:3072
	ds_read_b128 v[200:203], v150 offset:4096
	ds_read_b128 v[204:207], v150 offset:5120
	ds_read_b128 v[208:211], v150 offset:6144
	ds_read_b128 v[212:215], v150 offset:7168
	global_load_lds_dwordx4 v144, s[10:11]
	s_add_i32 m0, s27, 0xe000
	s_nop 0
	global_load_lds_dwordx4 v146, s[10:11]
	s_waitcnt lgkmcnt(0)
	v_mfma_f32_16x16x32_bf16 v[132:135], v[152:155], v[184:187], 0
	v_mfma_f32_16x16x32_bf16 v[132:135], v[156:159], v[188:191], v[132:135]
	v_mfma_f32_16x16x32_bf16 v[128:131], v[164:167], v[188:191], 0
	v_mfma_f32_16x16x32_bf16 v[128:131], v[160:163], v[184:187], v[128:131]
	s_waitcnt vmcnt(8)
	s_barrier
	s_setprio 1
	v_mfma_f32_16x16x32_bf16 v[120:123], v[160:163], v[192:195], 0
	v_mfma_f32_16x16x32_bf16 v[120:123], v[164:167], v[196:199], v[120:123]
	v_mfma_f32_16x16x32_bf16 v[124:127], v[156:159], v[196:199], 0
	v_mfma_f32_16x16x32_bf16 v[124:127], v[152:155], v[192:195], v[124:127]
	v_mfma_f32_16x16x32_bf16 v[108:111], v[152:155], v[200:203], 0
	v_mfma_f32_16x16x32_bf16 v[108:111], v[156:159], v[204:207], v[108:111]
	v_mfma_f32_16x16x32_bf16 v[104:107], v[164:167], v[204:207], 0
	v_mfma_f32_16x16x32_bf16 v[104:107], v[160:163], v[200:203], v[104:107]
	v_mfma_f32_16x16x32_bf16 v[88:91], v[160:163], v[208:211], 0
	v_mfma_f32_16x16x32_bf16 v[88:91], v[164:167], v[212:215], v[88:91]
	v_mfma_f32_16x16x32_bf16 v[92:95], v[156:159], v[212:215], 0
	v_mfma_f32_16x16x32_bf16 v[92:95], v[152:155], v[208:211], v[92:95]
	v_mfma_f32_16x16x32_bf16 v[76:79], v[168:171], v[208:211], 0
	v_mfma_f32_16x16x32_bf16 v[76:79], v[172:175], v[212:215], v[76:79]
	v_mfma_f32_16x16x32_bf16 v[116:119], v[172:175], v[188:191], 0
	v_mfma_f32_16x16x32_bf16 v[116:119], v[168:171], v[184:187], v[116:119]
	v_mfma_f32_16x16x32_bf16 v[112:115], v[176:179], v[184:187], 0
	v_mfma_f32_16x16x32_bf16 v[112:115], v[180:183], v[188:191], v[112:115]
	v_mfma_f32_16x16x32_bf16 v[96:99], v[180:183], v[196:199], 0
	v_mfma_f32_16x16x32_bf16 v[96:99], v[176:179], v[192:195], v[96:99]
	v_mfma_f32_16x16x32_bf16 v[100:103], v[168:171], v[192:195], 0
	v_mfma_f32_16x16x32_bf16 v[100:103], v[172:175], v[196:199], v[100:103]
	v_mfma_f32_16x16x32_bf16 v[84:87], v[172:175], v[204:207], 0
	v_mfma_f32_16x16x32_bf16 v[84:87], v[168:171], v[200:203], v[84:87]
	v_mfma_f32_16x16x32_bf16 v[80:83], v[176:179], v[200:203], 0
	v_mfma_f32_16x16x32_bf16 v[80:83], v[180:183], v[204:207], v[80:83]
	v_mfma_f32_16x16x32_bf16 v[72:75], v[180:183], v[212:215], 0
	v_mfma_f32_16x16x32_bf16 v[72:75], v[176:179], v[208:211], v[72:75]
	s_setprio 0
	s_barrier
	s_add_i32 s68, s68, s24
	s_mov_b32 m0, s68
	ds_read_b128 v[184:187], v150 offset:16384
	ds_read_b128 v[188:191], v150 offset:17408
	ds_read_b128 v[192:195], v150 offset:18432
	ds_read_b128 v[196:199], v150 offset:19456
	ds_read_b128 v[200:203], v150 offset:20480
	ds_read_b128 v[204:207], v150 offset:21504
	ds_read_b128 v[208:211], v150 offset:22528
	ds_read_b128 v[212:215], v150 offset:23552
	global_load_lds_dwordx4 v138, s[18:19]
	s_add_i32 m0, s68, 0x2000
	s_add_u32 s68, s18, 0x4000
	s_addc_u32 s69, s19, 0
	s_add_i32 s88, s88, s24
	global_load_lds_dwordx4 v142, s[18:19]
	s_mov_b32 m0, s88
	s_nop 0
	global_load_lds_dwordx4 v138, s[68:69]
	s_add_i32 m0, s88, 0x2000
	s_nop 0
	global_load_lds_dwordx4 v142, s[68:69]
	s_mov_b32 m0, s27
	s_nop 0
	global_load_lds_dwordx4 v136, s[20:21]
	s_mov_b32 m0, s28
	s_nop 0
	global_load_lds_dwordx4 v140, s[20:21]
	s_waitcnt lgkmcnt(0)
	v_mfma_f32_16x16x32_bf16 v[68:71], v[152:155], v[184:187], 0
	v_mfma_f32_16x16x32_bf16 v[68:71], v[156:159], v[188:191], v[68:71]
	v_mfma_f32_16x16x32_bf16 v[64:67], v[164:167], v[188:191], 0
	v_mfma_f32_16x16x32_bf16 v[64:67], v[160:163], v[184:187], v[64:67]
	s_waitcnt vmcnt(8)
	s_barrier
	s_setprio 1
	v_mfma_f32_16x16x32_bf16 v[56:59], v[160:163], v[192:195], 0
	v_mfma_f32_16x16x32_bf16 v[56:59], v[164:167], v[196:199], v[56:59]
	v_mfma_f32_16x16x32_bf16 v[60:63], v[156:159], v[196:199], 0
	v_mfma_f32_16x16x32_bf16 v[60:63], v[152:155], v[192:195], v[60:63]
	v_mfma_f32_16x16x32_bf16 v[44:47], v[152:155], v[200:203], 0
	v_mfma_f32_16x16x32_bf16 v[44:47], v[156:159], v[204:207], v[44:47]
	v_mfma_f32_16x16x32_bf16 v[40:43], v[164:167], v[204:207], 0
	v_mfma_f32_16x16x32_bf16 v[40:43], v[160:163], v[200:203], v[40:43]
	v_mfma_f32_16x16x32_bf16 v[20:23], v[160:163], v[208:211], 0
	v_mfma_f32_16x16x32_bf16 v[20:23], v[164:167], v[212:215], v[20:23]
	v_mfma_f32_16x16x32_bf16 v[24:27], v[156:159], v[212:215], 0
	v_mfma_f32_16x16x32_bf16 v[24:27], v[152:155], v[208:211], v[24:27]
	v_mfma_f32_16x16x32_bf16 v[8:11], v[168:171], v[208:211], 0
	v_mfma_f32_16x16x32_bf16 v[8:11], v[172:175], v[212:215], v[8:11]
	v_mfma_f32_16x16x32_bf16 v[52:55], v[172:175], v[188:191], 0
	v_mfma_f32_16x16x32_bf16 v[52:55], v[168:171], v[184:187], v[52:55]
	v_mfma_f32_16x16x32_bf16 v[48:51], v[176:179], v[184:187], 0
	v_mfma_f32_16x16x32_bf16 v[48:51], v[180:183], v[188:191], v[48:51]
	v_mfma_f32_16x16x32_bf16 v[28:31], v[180:183], v[196:199], 0
	v_mfma_f32_16x16x32_bf16 v[28:31], v[176:179], v[192:195], v[28:31]
	v_mfma_f32_16x16x32_bf16 v[32:35], v[168:171], v[192:195], 0
	v_mfma_f32_16x16x32_bf16 v[32:35], v[172:175], v[196:199], v[32:35]
	v_mfma_f32_16x16x32_bf16 v[16:19], v[172:175], v[204:207], 0
	v_mfma_f32_16x16x32_bf16 v[16:19], v[168:171], v[200:203], v[16:19]
	v_mfma_f32_16x16x32_bf16 v[12:15], v[176:179], v[200:203], 0
	v_mfma_f32_16x16x32_bf16 v[12:15], v[180:183], v[204:207], v[12:15]
	v_mfma_f32_16x16x32_bf16 v[4:7], v[180:183], v[212:215], 0
	v_mfma_f32_16x16x32_bf16 v[4:7], v[176:179], v[208:211], v[4:7]
	s_setprio 0
	s_barrier
; #define PG8_STAGE(bufoff, gbase, voff) do { _Pragma("unroll") for (int _i = 0; _i < 2; ++_i) \
;         __builtin_amdgcn_global_load_lds((const unsigned*)((const char*)(gbase) + (voff)[_i]), (PG8_LAS unsigned*)(lds + (bufoff) + ldsw + _i * 8192), 16, 0, 0); } while (0)
; #define PG8_LDA(dst, b, h) do { _Pragma("unroll") for (int m = 0; m < 4; ++m) _Pragma("unroll") for (int k = 0; k < 2; ++k) dst[m][k] = *(const PG8_LAS bf16x8*)(lds + PG8_SA(b, h) + aoff + m * 2048 + k * 1024); } while (0)
; #define PG8_LDB(dst, b, h) do { _Pragma("unroll") for (int n = 0; n < 2; ++n) _Pragma("unroll") for (int k = 0; k < 2; ++k) dst[n][k] = *(const PG8_LAS bf16x8*)(lds + PG8_SB(b, h) + boff + n * 2048 + k * 1024); } while (0)
; #define PG8_MMA(ai, bj, At, Bt) do { __builtin_amdgcn_s_setprio(1); _Pragma("unroll") for (int m = 0; m < 4; ++m) _Pragma("unroll") for (int n = 0; n < 2; ++n) _Pragma("unroll") for (int k = 0; k < 2; ++k) \
;         acc[ai][bj][m][n] = __builtin_amdgcn_mfma_f32_16x16x32_bf16(Bt[n][k], At[m][k], acc[ai][bj][m][n], 0, 0, 0); __builtin_amdgcn_s_setprio(0); } while (0)
; #define PG8_WAIT_V(n) asm volatile("s_waitcnt vmcnt(" #n ")" ::: "memory")
; #define PG8_WAIT_L(n) asm volatile("s_waitcnt lgkmcnt(" #n ")" ::: "memory")
; template <class Epi, class Sched, bool ALIGN_EPI = false, bool SP2 = false, bool ABLK = false, bool BBLK = false>
; __device__ __forceinline__ void gemm_phase(PG8_LAS unsigned char* lds, const Gemm g, const Sched& S, const Epi& E) {
;     ...
;         for (int t = 0; t < nt; t += 2) {
;             const bool last = (t == nt - 2);
;             const char* a1 = cA + (size_t)(t + 1) * kstepA;
;             const char* a2 = last ? nA : cA + (size_t)(t + 2) * kstepA; const char* b2 = last ? nB : cB + (size_t)(t + 2) * kstepB;
;             const char* a3 = a2 + kstepA; const char* b3 = b2 + kstepB;
;     ...
;             PG8_LDB(B0, 1, 0); PG8_LDB(B1, 1, 1); PG8_SCHED; PG8_LDA(At, 1, 0); PG8_STAGE(PG8_SA(0, 1), a2 + hstepA, voffA);
;             PG8_WAIT_V(8); PG8_WAIT_L(0); PG8_BAR; PG8_MMA(0, 0, At, B0); PG8_MMA(0, 1, At, B1); PG8_BAR; PG8_SCHED;
;             PG8_LDA(At, 1, 1); PG8_STAGE(PG8_SB(1, 0), b3, voffB); PG8_STAGE(PG8_SB(1, 1), b3 + hstepB, voffB); PG8_STAGE(PG8_SA(1, 0), a3, voffA);
;             PG8_WAIT_V(8); PG8_WAIT_L(0); PG8_BAR; PG8_MMA(1, 0, At, B0); PG8_MMA(1, 1, At, B1); PG8_BAR; PG8_SCHED;
	s_add_i32 s68, 0, 0x18000
	v_add_u32_e32 v36, s68, v148
	s_add_i32 s69, 0, 0x1c000
	ds_read_b128 v[152:155], v36
	ds_read_b128 v[156:159], v36 offset:1024
	ds_read_b128 v[160:163], v36 offset:2048
	ds_read_b128 v[164:167], v36 offset:3072
	v_add_u32_e32 v36, s69, v148
	ds_read_b128 v[168:171], v36
	ds_read_b128 v[172:175], v36 offset:1024
	ds_read_b128 v[176:179], v36 offset:2048
	ds_read_b128 v[180:183], v36 offset:3072
	s_add_u32 s20, s20, 0x4000
	s_addc_u32 s21, s21, 0
	s_mov_b32 m0, s29
	ds_read_b128 v[184:187], v150 offset:32768
	ds_read_b128 v[188:191], v150 offset:33792
	ds_read_b128 v[192:195], v150 offset:34816
	ds_read_b128 v[196:199], v150 offset:35840
	ds_read_b128 v[200:203], v150 offset:36864
	ds_read_b128 v[204:207], v150 offset:37888
	ds_read_b128 v[208:211], v150 offset:38912
	ds_read_b128 v[212:215], v150 offset:39936
	global_load_lds_dwordx4 v136, s[20:21]
	s_mov_b32 m0, s30
	s_nop 0
	global_load_lds_dwordx4 v140, s[20:21]
	s_waitcnt lgkmcnt(0)
	v_mfma_f32_16x16x32_bf16 v[132:135], v[152:155], v[184:187], v[132:135]
	v_mfma_f32_16x16x32_bf16 v[132:135], v[156:159], v[188:191], v[132:135]
	v_mfma_f32_16x16x32_bf16 v[128:131], v[164:167], v[188:191], v[128:131]
	v_mfma_f32_16x16x32_bf16 v[128:131], v[160:163], v[184:187], v[128:131]
	s_waitcnt vmcnt(8)
	s_barrier
	s_setprio 1
	v_mfma_f32_16x16x32_bf16 v[120:123], v[160:163], v[192:195], v[120:123]
	v_mfma_f32_16x16x32_bf16 v[120:123], v[164:167], v[196:199], v[120:123]
	v_mfma_f32_16x16x32_bf16 v[124:127], v[156:159], v[196:199], v[124:127]
	v_mfma_f32_16x16x32_bf16 v[124:127], v[152:155], v[192:195], v[124:127]
	v_mfma_f32_16x16x32_bf16 v[108:111], v[152:155], v[200:203], v[108:111]
	v_mfma_f32_16x16x32_bf16 v[108:111], v[156:159], v[204:207], v[108:111]
	v_mfma_f32_16x16x32_bf16 v[104:107], v[164:167], v[204:207], v[104:107]
	v_mfma_f32_16x16x32_bf16 v[104:107], v[160:163], v[200:203], v[104:107]
	v_mfma_f32_16x16x32_bf16 v[88:91], v[160:163], v[208:211], v[88:91]
	v_mfma_f32_16x16x32_bf16 v[88:91], v[164:167], v[212:215], v[88:91]
	v_mfma_f32_16x16x32_bf16 v[92:95], v[156:159], v[212:215], v[92:95]
	v_mfma_f32_16x16x32_bf16 v[92:95], v[152:155], v[208:211], v[92:95]
	v_mfma_f32_16x16x32_bf16 v[76:79], v[168:171], v[208:211], v[76:79]
	v_mfma_f32_16x16x32_bf16 v[76:79], v[172:175], v[212:215], v[76:79]
	v_mfma_f32_16x16x32_bf16 v[116:119], v[172:175], v[188:191], v[116:119]
	v_mfma_f32_16x16x32_bf16 v[116:119], v[168:171], v[184:187], v[116:119]
	v_mfma_f32_16x16x32_bf16 v[112:115], v[176:179], v[184:187], v[112:115]
	v_mfma_f32_16x16x32_bf16 v[112:115], v[180:183], v[188:191], v[112:115]
	v_mfma_f32_16x16x32_bf16 v[96:99], v[180:183], v[196:199], v[96:99]
	v_mfma_f32_16x16x32_bf16 v[96:99], v[176:179], v[192:195], v[96:99]
	v_mfma_f32_16x16x32_bf16 v[100:103], v[168:171], v[192:195], v[100:103]
	v_mfma_f32_16x16x32_bf16 v[100:103], v[172:175], v[196:199], v[100:103]
	v_mfma_f32_16x16x32_bf16 v[84:87], v[172:175], v[204:207], v[84:87]
	v_mfma_f32_16x16x32_bf16 v[84:87], v[168:171], v[200:203], v[84:87]
	v_mfma_f32_16x16x32_bf16 v[80:83], v[176:179], v[200:203], v[80:83]
	v_mfma_f32_16x16x32_bf16 v[80:83], v[180:183], v[204:207], v[80:83]
	v_mfma_f32_16x16x32_bf16 v[72:75], v[180:183], v[212:215], v[72:75]
	v_mfma_f32_16x16x32_bf16 v[72:75], v[176:179], v[208:211], v[72:75]
	s_setprio 0
	s_barrier
	s_add_u32 s20, s18, 0x8000
	s_addc_u32 s21, s19, 0
	s_add_i32 s68, s68, s24
	s_mov_b32 m0, s68
	ds_read_b128 v[184:187], v150 offset:49152
	ds_read_b128 v[188:191], v150 offset:50176
	ds_read_b128 v[192:195], v150 offset:51200
	ds_read_b128 v[196:199], v150 offset:52224
	ds_read_b128 v[200:203], v150 offset:53248
	ds_read_b128 v[204:207], v150 offset:54272
	ds_read_b128 v[208:211], v150 offset:55296
	ds_read_b128 v[212:215], v150 offset:56320
	global_load_lds_dwordx4 v138, s[20:21]
	s_add_i32 m0, s68, 0x2000
	s_add_u32 s18, s18, 0xc000
	s_addc_u32 s19, s19, 0
	global_load_lds_dwordx4 v142, s[20:21]
	s_add_i32 s20, s69, s24
	s_mov_b32 m0, s20
	s_nop 0
	global_load_lds_dwordx4 v138, s[18:19]
	s_add_i32 m0, s20, 0x2000
	s_nop 0
	global_load_lds_dwordx4 v142, s[18:19]
	s_mov_b32 m0, s35
	s_nop 0
	global_load_lds_dwordx4 v136, s[16:17]
	s_mov_b32 m0, s70
	s_nop 0
	global_load_lds_dwordx4 v140, s[16:17]
	s_waitcnt lgkmcnt(0)
	v_mfma_f32_16x16x32_bf16 v[68:71], v[152:155], v[184:187], v[68:71]
	v_mfma_f32_16x16x32_bf16 v[68:71], v[156:159], v[188:191], v[68:71]
	v_mfma_f32_16x16x32_bf16 v[64:67], v[164:167], v[188:191], v[64:67]
	v_mfma_f32_16x16x32_bf16 v[64:67], v[160:163], v[184:187], v[64:67]
	s_waitcnt vmcnt(8)
	s_barrier
	s_setprio 1
	v_mfma_f32_16x16x32_bf16 v[56:59], v[160:163], v[192:195], v[56:59]
	v_mfma_f32_16x16x32_bf16 v[56:59], v[164:167], v[196:199], v[56:59]
	v_mfma_f32_16x16x32_bf16 v[60:63], v[156:159], v[196:199], v[60:63]
	v_mfma_f32_16x16x32_bf16 v[60:63], v[152:155], v[192:195], v[60:63]
	v_mfma_f32_16x16x32_bf16 v[44:47], v[152:155], v[200:203], v[44:47]
	v_mfma_f32_16x16x32_bf16 v[44:47], v[156:159], v[204:207], v[44:47]
	v_mfma_f32_16x16x32_bf16 v[40:43], v[164:167], v[204:207], v[40:43]
	v_mfma_f32_16x16x32_bf16 v[40:43], v[160:163], v[200:203], v[40:43]
	v_mfma_f32_16x16x32_bf16 v[20:23], v[160:163], v[208:211], v[20:23]
	v_mfma_f32_16x16x32_bf16 v[20:23], v[164:167], v[212:215], v[20:23]
	v_mfma_f32_16x16x32_bf16 v[24:27], v[156:159], v[212:215], v[24:27]
	v_mfma_f32_16x16x32_bf16 v[24:27], v[152:155], v[208:211], v[24:27]
	v_mfma_f32_16x16x32_bf16 v[8:11], v[168:171], v[208:211], v[8:11]
	v_mfma_f32_16x16x32_bf16 v[8:11], v[172:175], v[212:215], v[8:11]
	v_mfma_f32_16x16x32_bf16 v[52:55], v[172:175], v[188:191], v[52:55]
	v_mfma_f32_16x16x32_bf16 v[52:55], v[168:171], v[184:187], v[52:55]
	v_mfma_f32_16x16x32_bf16 v[48:51], v[176:179], v[184:187], v[48:51]
	v_mfma_f32_16x16x32_bf16 v[48:51], v[180:183], v[188:191], v[48:51]
	v_mfma_f32_16x16x32_bf16 v[28:31], v[180:183], v[196:199], v[28:31]
	v_mfma_f32_16x16x32_bf16 v[28:31], v[176:179], v[192:195], v[28:31]
	v_mfma_f32_16x16x32_bf16 v[32:35], v[168:171], v[192:195], v[32:35]
	v_mfma_f32_16x16x32_bf16 v[32:35], v[172:175], v[196:199], v[32:35]
	v_mfma_f32_16x16x32_bf16 v[16:19], v[172:175], v[204:207], v[16:19]
	v_mfma_f32_16x16x32_bf16 v[16:19], v[168:171], v[200:203], v[16:19]
	v_mfma_f32_16x16x32_bf16 v[12:15], v[176:179], v[200:203], v[12:15]
	v_mfma_f32_16x16x32_bf16 v[12:15], v[180:183], v[204:207], v[12:15]
	v_mfma_f32_16x16x32_bf16 v[4:7], v[180:183], v[212:215], v[4:7]
	v_mfma_f32_16x16x32_bf16 v[4:7], v[176:179], v[208:211], v[4:7]
	s_setprio 0
	s_barrier
	s_add_i32 s13, s13, 2
	s_add_u32 s10, s10, 0x10000
	s_addc_u32 s11, s11, 0
	s_add_u32 vcc_lo, vcc_lo, 0x10000
	s_addc_u32 vcc_hi, vcc_hi, 0
	s_cmpk_gt_u32 s13, 0x55
; #define PG8_STAGE(bufoff, gbase, voff) do { _Pragma("unroll") for (int _i = 0; _i < 2; ++_i) \
;         __builtin_amdgcn_global_load_lds((const unsigned*)((const char*)(gbase) + (voff)[_i]), (PG8_LAS unsigned*)(lds + (bufoff) + ldsw + _i * 8192), 16, 0, 0); } while (0)
; #define PG8_LDA(dst, b, h) do { _Pragma("unroll") for (int m = 0; m < 4; ++m) _Pragma("unroll") for (int k = 0; k < 2; ++k) dst[m][k] = *(const PG8_LAS bf16x8*)(lds + PG8_SA(b, h) + aoff + m * 2048 + k * 1024); } while (0)
; #define PG8_LDB(dst, b, h) do { _Pragma("unroll") for (int n = 0; n < 2; ++n) _Pragma("unroll") for (int k = 0; k < 2; ++k) dst[n][k] = *(const PG8_LAS bf16x8*)(lds + PG8_SB(b, h) + boff + n * 2048 + k * 1024); } while (0)
; #define PG8_MMA(ai, bj, At, Bt) do { __builtin_amdgcn_s_setprio(1); _Pragma("unroll") for (int m = 0; m < 4; ++m) _Pragma("unroll") for (int n = 0; n < 2; ++n) _Pragma("unroll") for (int k = 0; k < 2; ++k) \
;         acc[ai][bj][m][n] = __builtin_amdgcn_mfma_f32_16x16x32_bf16(Bt[n][k], At[m][k], acc[ai][bj][m][n], 0, 0, 0); __builtin_amdgcn_s_setprio(0); } while (0)
; #define PG8_WAIT_V(n) asm volatile("s_waitcnt vmcnt(" #n ")" ::: "memory")
; template <class Epi, class Sched, bool ALIGN_EPI = false, bool SP2 = false, bool ABLK = false, bool BBLK = false>
; __device__ __forceinline__ void gemm_phase(PG8_LAS unsigned char* lds, const Gemm g, const Sched& S, const Epi& E) {
;     ...
;         for (int t = 0; t < nt; t += 2) {
;             const bool last = (t == nt - 2);
;             const char* a1 = cA + (size_t)(t + 1) * kstepA;
;             const char* a2 = last ? nA : cA + (size_t)(t + 2) * kstepA; const char* b2 = last ? nB : cB + (size_t)(t + 2) * kstepB;
;             const char* a3 = a2 + kstepA; const char* b3 = b2 + kstepB;
;             if (last && has_next) S.a_ready(nxt);
;             if constexpr (SP2) {
;             PG8_LDB(B0, 0, 0); PG8_LDB(B1, 0, 1); PG8_SCHED; PG8_LDA(At, 0, 0); PG8_STAGE(PG8_SA(1, 1), a1 + hstepA, voffA);
;             PG8_WAIT_V(8); PG8_WAIT_L(0); PG8_BAR; PG8_MMA(0, 0, At, B0); PG8_MMA(0, 1, At, B1); PG8_BAR; PG8_SCHED;
;             PG8_LDA(At, 0, 1); PG8_STAGE(PG8_SB(0, 0), b2, voffB); PG8_STAGE(PG8_SB(0, 1), b2 + hstepB, voffB); PG8_STAGE(PG8_SA(0, 0), a2, voffA);
;             PG8_WAIT_V(8); PG8_WAIT_L(0); PG8_BAR; PG8_MMA(1, 0, At, B0); PG8_MMA(1, 1, At, B1); PG8_BAR; PG8_SCHED;
.LBB0_439:
	s_add_u32 s16, s10, 0x4000
	s_addc_u32 s17, s11, 0
	s_cmpk_eq_i32 s13, 0x54
	s_cselect_b32 s20, s0, s16
	s_cselect_b32 s21, s1, s17
	s_cselect_b32 s18, s8, vcc_lo
	s_cselect_b32 s19, s9, vcc_hi
	s_add_u32 s16, s20, 0x8000
	s_addc_u32 s17, s21, 0
	s_add_i32 s68, 0, 0x10000
	v_add_u32_e32 v36, s68, v148
	s_add_i32 s88, 0, 0x14000
	ds_read_b128 v[152:155], v36
	ds_read_b128 v[156:159], v36 offset:1024
	ds_read_b128 v[160:163], v36 offset:2048
	ds_read_b128 v[164:167], v36 offset:3072
	v_add_u32_e32 v36, s88, v148
	ds_read_b128 v[168:171], v36
	ds_read_b128 v[172:175], v36 offset:1024
	ds_read_b128 v[176:179], v36 offset:2048
	ds_read_b128 v[180:183], v36 offset:3072
	s_add_i32 m0, s27, 0xc000
	ds_read_b128 v[184:187], v150
	ds_read_b128 v[188:191], v150 offset:1024
	ds_read_b128 v[192:195], v150 offset:2048
	ds_read_b128 v[196:199], v150 offset:3072
	ds_read_b128 v[200:203], v150 offset:4096
	ds_read_b128 v[204:207], v150 offset:5120
	ds_read_b128 v[208:211], v150 offset:6144
	ds_read_b128 v[212:215], v150 offset:7168
	global_load_lds_dwordx4 v144, s[10:11]
	s_add_i32 m0, s27, 0xe000
	s_nop 0
	global_load_lds_dwordx4 v146, s[10:11]
	s_waitcnt lgkmcnt(0)
	v_mfma_f32_16x16x32_bf16 v[132:135], v[152:155], v[184:187], v[132:135]
	v_mfma_f32_16x16x32_bf16 v[132:135], v[156:159], v[188:191], v[132:135]
	v_mfma_f32_16x16x32_bf16 v[128:131], v[164:167], v[188:191], v[128:131]
	v_mfma_f32_16x16x32_bf16 v[128:131], v[160:163], v[184:187], v[128:131]
	s_waitcnt vmcnt(8)
	s_barrier
	s_setprio 1
	v_mfma_f32_16x16x32_bf16 v[120:123], v[160:163], v[192:195], v[120:123]
	v_mfma_f32_16x16x32_bf16 v[120:123], v[164:167], v[196:199], v[120:123]
	v_mfma_f32_16x16x32_bf16 v[124:127], v[156:159], v[196:199], v[124:127]
	v_mfma_f32_16x16x32_bf16 v[124:127], v[152:155], v[192:195], v[124:127]
	v_mfma_f32_16x16x32_bf16 v[108:111], v[152:155], v[200:203], v[108:111]
	v_mfma_f32_16x16x32_bf16 v[108:111], v[156:159], v[204:207], v[108:111]
	v_mfma_f32_16x16x32_bf16 v[104:107], v[164:167], v[204:207], v[104:107]
	v_mfma_f32_16x16x32_bf16 v[104:107], v[160:163], v[200:203], v[104:107]
	v_mfma_f32_16x16x32_bf16 v[88:91], v[160:163], v[208:211], v[88:91]
	v_mfma_f32_16x16x32_bf16 v[88:91], v[164:167], v[212:215], v[88:91]
	v_mfma_f32_16x16x32_bf16 v[92:95], v[156:159], v[212:215], v[92:95]
	v_mfma_f32_16x16x32_bf16 v[92:95], v[152:155], v[208:211], v[92:95]
	v_mfma_f32_16x16x32_bf16 v[76:79], v[168:171], v[208:211], v[76:79]
	v_mfma_f32_16x16x32_bf16 v[76:79], v[172:175], v[212:215], v[76:79]
	v_mfma_f32_16x16x32_bf16 v[116:119], v[172:175], v[188:191], v[116:119]
	v_mfma_f32_16x16x32_bf16 v[116:119], v[168:171], v[184:187], v[116:119]
	v_mfma_f32_16x16x32_bf16 v[112:115], v[176:179], v[184:187], v[112:115]
	v_mfma_f32_16x16x32_bf16 v[112:115], v[180:183], v[188:191], v[112:115]
	v_mfma_f32_16x16x32_bf16 v[96:99], v[180:183], v[196:199], v[96:99]
	v_mfma_f32_16x16x32_bf16 v[96:99], v[176:179], v[192:195], v[96:99]
	v_mfma_f32_16x16x32_bf16 v[100:103], v[168:171], v[192:195], v[100:103]
	v_mfma_f32_16x16x32_bf16 v[100:103], v[172:175], v[196:199], v[100:103]
	v_mfma_f32_16x16x32_bf16 v[84:87], v[172:175], v[204:207], v[84:87]
	v_mfma_f32_16x16x32_bf16 v[84:87], v[168:171], v[200:203], v[84:87]
	v_mfma_f32_16x16x32_bf16 v[80:83], v[176:179], v[200:203], v[80:83]
	v_mfma_f32_16x16x32_bf16 v[80:83], v[180:183], v[204:207], v[80:83]
	v_mfma_f32_16x16x32_bf16 v[72:75], v[180:183], v[212:215], v[72:75]
	v_mfma_f32_16x16x32_bf16 v[72:75], v[176:179], v[208:211], v[72:75]
	s_setprio 0
	s_barrier
	s_add_i32 s68, s68, s24
	s_mov_b32 m0, s68
	ds_read_b128 v[184:187], v150 offset:16384
	ds_read_b128 v[188:191], v150 offset:17408
	ds_read_b128 v[192:195], v150 offset:18432
	ds_read_b128 v[196:199], v150 offset:19456
	ds_read_b128 v[200:203], v150 offset:20480
	ds_read_b128 v[204:207], v150 offset:21504
	ds_read_b128 v[208:211], v150 offset:22528
	ds_read_b128 v[212:215], v150 offset:23552
	global_load_lds_dwordx4 v138, s[18:19]
	s_add_i32 m0, s68, 0x2000
	s_add_u32 s68, s18, 0x4000
	s_addc_u32 s69, s19, 0
	s_add_i32 s88, s88, s24
	global_load_lds_dwordx4 v142, s[18:19]
	s_mov_b32 m0, s88
	s_nop 0
	global_load_lds_dwordx4 v138, s[68:69]
	s_add_i32 m0, s88, 0x2000
	s_nop 0
	global_load_lds_dwordx4 v142, s[68:69]
	s_mov_b32 m0, s27
	s_nop 0
	global_load_lds_dwordx4 v136, s[20:21]
	s_mov_b32 m0, s28
	s_nop 0
	global_load_lds_dwordx4 v140, s[20:21]
	s_waitcnt lgkmcnt(0)
	v_mfma_f32_16x16x32_bf16 v[68:71], v[152:155], v[184:187], v[68:71]
	v_mfma_f32_16x16x32_bf16 v[68:71], v[156:159], v[188:191], v[68:71]
	v_mfma_f32_16x16x32_bf16 v[64:67], v[164:167], v[188:191], v[64:67]
	v_mfma_f32_16x16x32_bf16 v[64:67], v[160:163], v[184:187], v[64:67]
	s_waitcnt vmcnt(8)
	s_barrier
; #define PG8_STAGE(bufoff, gbase, voff) do { _Pragma("unroll") for (int _i = 0; _i < 2; ++_i) \
;         __builtin_amdgcn_global_load_lds((const unsigned*)((const char*)(gbase) + (voff)[_i]), (PG8_LAS unsigned*)(lds + (bufoff) + ldsw + _i * 8192), 16, 0, 0); } while (0)
; #define PG8_LDA(dst, b, h) do { _Pragma("unroll") for (int m = 0; m < 4; ++m) _Pragma("unroll") for (int k = 0; k < 2; ++k) dst[m][k] = *(const PG8_LAS bf16x8*)(lds + PG8_SA(b, h) + aoff + m * 2048 + k * 1024); } while (0)
; #define PG8_LDB(dst, b, h) do { _Pragma("unroll") for (int n = 0; n < 2; ++n) _Pragma("unroll") for (int k = 0; k < 2; ++k) dst[n][k] = *(const PG8_LAS bf16x8*)(lds + PG8_SB(b, h) + boff + n * 2048 + k * 1024); } while (0)
; #define PG8_MMA(ai, bj, At, Bt) do { __builtin_amdgcn_s_setprio(1); _Pragma("unroll") for (int m = 0; m < 4; ++m) _Pragma("unroll") for (int n = 0; n < 2; ++n) _Pragma("unroll") for (int k = 0; k < 2; ++k) \
;         acc[ai][bj][m][n] = __builtin_amdgcn_mfma_f32_16x16x32_bf16(Bt[n][k], At[m][k], acc[ai][bj][m][n], 0, 0, 0); __builtin_amdgcn_s_setprio(0); } while (0)
; #define PG8_WAIT_V(n) asm volatile("s_waitcnt vmcnt(" #n ")" ::: "memory")
; #define PG8_WAIT_L(n) asm volatile("s_waitcnt lgkmcnt(" #n ")" ::: "memory")
; #define PG8_BAR __builtin_amdgcn_s_barrier()
; #define PG8_SCHED __builtin_amdgcn_sched_barrier(0)
; template <class Epi, class Sched, bool ALIGN_EPI = false, bool SP2 = false, bool ABLK = false, bool BBLK = false>
; __device__ __forceinline__ void gemm_phase(PG8_LAS unsigned char* lds, const Gemm g, const Sched& S, const Epi& E) {
;     ...
;             PG8_WAIT_V(8); PG8_WAIT_L(0); PG8_BAR; PG8_MMA(1, 0, At, B0); PG8_MMA(1, 1, At, B1); PG8_BAR; PG8_SCHED;
;             PG8_LDB(B0, 1, 0); PG8_LDB(B1, 1, 1); PG8_SCHED; PG8_LDA(At, 1, 0); PG8_STAGE(PG8_SA(0, 1), a2 + hstepA, voffA);
;             PG8_WAIT_V(8); PG8_WAIT_L(0); PG8_BAR; PG8_MMA(0, 0, At, B0); PG8_MMA(0, 1, At, B1); PG8_BAR; PG8_SCHED;
	s_setprio 1
	v_mfma_f32_16x16x32_bf16 v[56:59], v[160:163], v[192:195], v[56:59]
	v_mfma_f32_16x16x32_bf16 v[56:59], v[164:167], v[196:199], v[56:59]
	v_mfma_f32_16x16x32_bf16 v[60:63], v[156:159], v[196:199], v[60:63]
	v_mfma_f32_16x16x32_bf16 v[60:63], v[152:155], v[192:195], v[60:63]
	v_mfma_f32_16x16x32_bf16 v[44:47], v[152:155], v[200:203], v[44:47]
	v_mfma_f32_16x16x32_bf16 v[44:47], v[156:159], v[204:207], v[44:47]
	v_mfma_f32_16x16x32_bf16 v[40:43], v[164:167], v[204:207], v[40:43]
	v_mfma_f32_16x16x32_bf16 v[40:43], v[160:163], v[200:203], v[40:43]
	v_mfma_f32_16x16x32_bf16 v[20:23], v[160:163], v[208:211], v[20:23]
	v_mfma_f32_16x16x32_bf16 v[20:23], v[164:167], v[212:215], v[20:23]
	v_mfma_f32_16x16x32_bf16 v[24:27], v[156:159], v[212:215], v[24:27]
	v_mfma_f32_16x16x32_bf16 v[24:27], v[152:155], v[208:211], v[24:27]
	v_mfma_f32_16x16x32_bf16 v[8:11], v[168:171], v[208:211], v[8:11]
	v_mfma_f32_16x16x32_bf16 v[8:11], v[172:175], v[212:215], v[8:11]
	v_mfma_f32_16x16x32_bf16 v[52:55], v[172:175], v[188:191], v[52:55]
	v_mfma_f32_16x16x32_bf16 v[52:55], v[168:171], v[184:187], v[52:55]
	v_mfma_f32_16x16x32_bf16 v[48:51], v[176:179], v[184:187], v[48:51]
	v_mfma_f32_16x16x32_bf16 v[48:51], v[180:183], v[188:191], v[48:51]
	v_mfma_f32_16x16x32_bf16 v[28:31], v[180:183], v[196:199], v[28:31]
	v_mfma_f32_16x16x32_bf16 v[28:31], v[176:179], v[192:195], v[28:31]
	v_mfma_f32_16x16x32_bf16 v[32:35], v[168:171], v[192:195], v[32:35]
	v_mfma_f32_16x16x32_bf16 v[32:35], v[172:175], v[196:199], v[32:35]
	v_mfma_f32_16x16x32_bf16 v[16:19], v[172:175], v[204:207], v[16:19]
	v_mfma_f32_16x16x32_bf16 v[16:19], v[168:171], v[200:203], v[16:19]
	v_mfma_f32_16x16x32_bf16 v[12:15], v[176:179], v[200:203], v[12:15]
	v_mfma_f32_16x16x32_bf16 v[12:15], v[180:183], v[204:207], v[12:15]
	v_mfma_f32_16x16x32_bf16 v[4:7], v[180:183], v[212:215], v[4:7]
	v_mfma_f32_16x16x32_bf16 v[4:7], v[176:179], v[208:211], v[4:7]
	s_setprio 0
	s_barrier
	s_add_i32 s68, 0, 0x18000
	v_add_u32_e32 v36, s68, v148
	s_add_i32 s69, 0, 0x1c000
	ds_read_b128 v[152:155], v36
	ds_read_b128 v[156:159], v36 offset:1024
	ds_read_b128 v[160:163], v36 offset:2048
	ds_read_b128 v[164:167], v36 offset:3072
	v_add_u32_e32 v36, s69, v148
	ds_read_b128 v[168:171], v36
	ds_read_b128 v[172:175], v36 offset:1024
	ds_read_b128 v[176:179], v36 offset:2048
	ds_read_b128 v[180:183], v36 offset:3072
	s_add_u32 s20, s20, 0x4000
	s_addc_u32 s21, s21, 0
	s_mov_b32 m0, s29
	ds_read_b128 v[184:187], v150 offset:32768
	ds_read_b128 v[188:191], v150 offset:33792
	ds_read_b128 v[192:195], v150 offset:34816
	ds_read_b128 v[196:199], v150 offset:35840
	ds_read_b128 v[200:203], v150 offset:36864
	ds_read_b128 v[204:207], v150 offset:37888
	ds_read_b128 v[208:211], v150 offset:38912
	ds_read_b128 v[212:215], v150 offset:39936
	global_load_lds_dwordx4 v136, s[20:21]
	s_mov_b32 m0, s30
	s_nop 0
	global_load_lds_dwordx4 v140, s[20:21]
	s_waitcnt lgkmcnt(0)
	v_mfma_f32_16x16x32_bf16 v[132:135], v[152:155], v[184:187], v[132:135]
	v_mfma_f32_16x16x32_bf16 v[132:135], v[156:159], v[188:191], v[132:135]
	v_mfma_f32_16x16x32_bf16 v[128:131], v[164:167], v[188:191], v[128:131]
	v_mfma_f32_16x16x32_bf16 v[128:131], v[160:163], v[184:187], v[128:131]
	s_waitcnt vmcnt(8)
	s_barrier
	s_setprio 1
	v_mfma_f32_16x16x32_bf16 v[120:123], v[160:163], v[192:195], v[120:123]
	v_mfma_f32_16x16x32_bf16 v[120:123], v[164:167], v[196:199], v[120:123]
	v_mfma_f32_16x16x32_bf16 v[124:127], v[156:159], v[196:199], v[124:127]
	v_mfma_f32_16x16x32_bf16 v[124:127], v[152:155], v[192:195], v[124:127]
	v_mfma_f32_16x16x32_bf16 v[108:111], v[152:155], v[200:203], v[108:111]
	v_mfma_f32_16x16x32_bf16 v[108:111], v[156:159], v[204:207], v[108:111]
	v_mfma_f32_16x16x32_bf16 v[104:107], v[164:167], v[204:207], v[104:107]
	v_mfma_f32_16x16x32_bf16 v[104:107], v[160:163], v[200:203], v[104:107]
	v_mfma_f32_16x16x32_bf16 v[88:91], v[160:163], v[208:211], v[88:91]
	v_mfma_f32_16x16x32_bf16 v[88:91], v[164:167], v[212:215], v[88:91]
	v_mfma_f32_16x16x32_bf16 v[92:95], v[156:159], v[212:215], v[92:95]
	v_mfma_f32_16x16x32_bf16 v[92:95], v[152:155], v[208:211], v[92:95]
	v_mfma_f32_16x16x32_bf16 v[76:79], v[168:171], v[208:211], v[76:79]
	v_mfma_f32_16x16x32_bf16 v[76:79], v[172:175], v[212:215], v[76:79]
	v_mfma_f32_16x16x32_bf16 v[116:119], v[172:175], v[188:191], v[116:119]
	v_mfma_f32_16x16x32_bf16 v[116:119], v[168:171], v[184:187], v[116:119]
	v_mfma_f32_16x16x32_bf16 v[112:115], v[176:179], v[184:187], v[112:115]
	v_mfma_f32_16x16x32_bf16 v[112:115], v[180:183], v[188:191], v[112:115]
	v_mfma_f32_16x16x32_bf16 v[96:99], v[180:183], v[196:199], v[96:99]
	v_mfma_f32_16x16x32_bf16 v[96:99], v[176:179], v[192:195], v[96:99]
	v_mfma_f32_16x16x32_bf16 v[100:103], v[168:171], v[192:195], v[100:103]
	v_mfma_f32_16x16x32_bf16 v[100:103], v[172:175], v[196:199], v[100:103]
	v_mfma_f32_16x16x32_bf16 v[84:87], v[172:175], v[204:207], v[84:87]
	v_mfma_f32_16x16x32_bf16 v[84:87], v[168:171], v[200:203], v[84:87]
	v_mfma_f32_16x16x32_bf16 v[80:83], v[176:179], v[200:203], v[80:83]
	v_mfma_f32_16x16x32_bf16 v[80:83], v[180:183], v[204:207], v[80:83]
	v_mfma_f32_16x16x32_bf16 v[72:75], v[180:183], v[212:215], v[72:75]
	v_mfma_f32_16x16x32_bf16 v[72:75], v[176:179], v[208:211], v[72:75]
	s_setprio 0
	s_barrier
; #define PG8_STAGE(bufoff, gbase, voff) do { _Pragma("unroll") for (int _i = 0; _i < 2; ++_i) \
;         __builtin_amdgcn_global_load_lds((const unsigned*)((const char*)(gbase) + (voff)[_i]), (PG8_LAS unsigned*)(lds + (bufoff) + ldsw + _i * 8192), 16, 0, 0); } while (0)
; #define PG8_LDA(dst, b, h) do { _Pragma("unroll") for (int m = 0; m < 4; ++m) _Pragma("unroll") for (int k = 0; k < 2; ++k) dst[m][k] = *(const PG8_LAS bf16x8*)(lds + PG8_SA(b, h) + aoff + m * 2048 + k * 1024); } while (0)
; #define PG8_MMA(ai, bj, At, Bt) do { __builtin_amdgcn_s_setprio(1); _Pragma("unroll") for (int m = 0; m < 4; ++m) _Pragma("unroll") for (int n = 0; n < 2; ++n) _Pragma("unroll") for (int k = 0; k < 2; ++k) \
;         acc[ai][bj][m][n] = __builtin_amdgcn_mfma_f32_16x16x32_bf16(Bt[n][k], At[m][k], acc[ai][bj][m][n], 0, 0, 0); __builtin_amdgcn_s_setprio(0); } while (0)
; #define PG8_WAIT_V(n) asm volatile("s_waitcnt vmcnt(" #n ")" ::: "memory")
; #define PG8_WAIT_L(n) asm volatile("s_waitcnt lgkmcnt(" #n ")" ::: "memory")
; #define PG8_BAR __builtin_amdgcn_s_barrier()
; #define PG8_SCHED __builtin_amdgcn_sched_barrier(0)
; template <class Epi, class Sched, bool ALIGN_EPI = false, bool SP2 = false, bool ABLK = false, bool BBLK = false>
; __device__ __forceinline__ void gemm_phase(PG8_LAS unsigned char* lds, const Gemm g, const Sched& S, const Epi& E) {
;     ...
;         for (int t = 0; t < nt; t += 2) {
;             const bool last = (t == nt - 2);
;             const char* a1 = cA + (size_t)(t + 1) * kstepA;
;             const char* a2 = last ? nA : cA + (size_t)(t + 2) * kstepA; const char* b2 = last ? nB : cB + (size_t)(t + 2) * kstepB;
;             const char* a3 = a2 + kstepA; const char* b3 = b2 + kstepB;
;     ...
;             PG8_LDA(At, 1, 1); PG8_STAGE(PG8_SB(1, 0), b3, voffB); PG8_STAGE(PG8_SB(1, 1), b3 + hstepB, voffB); PG8_STAGE(PG8_SA(1, 0), a3, voffA);
;             PG8_WAIT_V(8); PG8_WAIT_L(0); PG8_BAR; PG8_MMA(1, 0, At, B0); PG8_MMA(1, 1, At, B1); PG8_BAR; PG8_SCHED;
;     ...
;         if constexpr (ALIGN_EPI) { if (wr == 0) PG8_BAR; }
	s_add_u32 s20, s18, 0x8000
	s_addc_u32 s21, s19, 0
	s_add_i32 s68, s68, s24
	s_mov_b32 m0, s68
	ds_read_b128 v[184:187], v150 offset:49152
	ds_read_b128 v[188:191], v150 offset:50176
	ds_read_b128 v[192:195], v150 offset:51200
	ds_read_b128 v[196:199], v150 offset:52224
	ds_read_b128 v[200:203], v150 offset:53248
	ds_read_b128 v[204:207], v150 offset:54272
	ds_read_b128 v[208:211], v150 offset:55296
	ds_read_b128 v[212:215], v150 offset:56320
	global_load_lds_dwordx4 v138, s[20:21]
	s_add_i32 m0, s68, 0x2000
	s_add_u32 s18, s18, 0xc000
	s_addc_u32 s19, s19, 0
	global_load_lds_dwordx4 v142, s[20:21]
	s_add_i32 s20, s69, s24
	s_mov_b32 m0, s20
	s_nop 0
	global_load_lds_dwordx4 v138, s[18:19]
	s_add_i32 m0, s20, 0x2000
	s_nop 0
	global_load_lds_dwordx4 v142, s[18:19]
	s_mov_b32 m0, s35
	s_nop 0
	global_load_lds_dwordx4 v136, s[16:17]
	s_mov_b32 m0, s70
	s_nop 0
	global_load_lds_dwordx4 v140, s[16:17]
	s_waitcnt lgkmcnt(0)
	v_mfma_f32_16x16x32_bf16 v[68:71], v[152:155], v[184:187], v[68:71]
	v_mfma_f32_16x16x32_bf16 v[68:71], v[156:159], v[188:191], v[68:71]
	v_mfma_f32_16x16x32_bf16 v[64:67], v[164:167], v[188:191], v[64:67]
	v_mfma_f32_16x16x32_bf16 v[64:67], v[160:163], v[184:187], v[64:67]
	s_waitcnt vmcnt(8)
	s_barrier
	s_setprio 1
	v_mfma_f32_16x16x32_bf16 v[56:59], v[160:163], v[192:195], v[56:59]
	v_mfma_f32_16x16x32_bf16 v[56:59], v[164:167], v[196:199], v[56:59]
	v_mfma_f32_16x16x32_bf16 v[60:63], v[156:159], v[196:199], v[60:63]
	v_mfma_f32_16x16x32_bf16 v[60:63], v[152:155], v[192:195], v[60:63]
	v_mfma_f32_16x16x32_bf16 v[44:47], v[152:155], v[200:203], v[44:47]
	v_mfma_f32_16x16x32_bf16 v[44:47], v[156:159], v[204:207], v[44:47]
	v_mfma_f32_16x16x32_bf16 v[40:43], v[164:167], v[204:207], v[40:43]
	v_mfma_f32_16x16x32_bf16 v[40:43], v[160:163], v[200:203], v[40:43]
	v_mfma_f32_16x16x32_bf16 v[20:23], v[160:163], v[208:211], v[20:23]
	v_mfma_f32_16x16x32_bf16 v[20:23], v[164:167], v[212:215], v[20:23]
	v_mfma_f32_16x16x32_bf16 v[24:27], v[156:159], v[212:215], v[24:27]
	v_mfma_f32_16x16x32_bf16 v[24:27], v[152:155], v[208:211], v[24:27]
	v_mfma_f32_16x16x32_bf16 v[8:11], v[168:171], v[208:211], v[8:11]
	v_mfma_f32_16x16x32_bf16 v[8:11], v[172:175], v[212:215], v[8:11]
	v_mfma_f32_16x16x32_bf16 v[52:55], v[172:175], v[188:191], v[52:55]
	v_mfma_f32_16x16x32_bf16 v[52:55], v[168:171], v[184:187], v[52:55]
	v_mfma_f32_16x16x32_bf16 v[48:51], v[176:179], v[184:187], v[48:51]
	v_mfma_f32_16x16x32_bf16 v[48:51], v[180:183], v[188:191], v[48:51]
	v_mfma_f32_16x16x32_bf16 v[28:31], v[180:183], v[196:199], v[28:31]
	v_mfma_f32_16x16x32_bf16 v[28:31], v[176:179], v[192:195], v[28:31]
	v_mfma_f32_16x16x32_bf16 v[32:35], v[168:171], v[192:195], v[32:35]
	v_mfma_f32_16x16x32_bf16 v[32:35], v[172:175], v[196:199], v[32:35]
	v_mfma_f32_16x16x32_bf16 v[16:19], v[172:175], v[204:207], v[16:19]
	v_mfma_f32_16x16x32_bf16 v[16:19], v[168:171], v[200:203], v[16:19]
	v_mfma_f32_16x16x32_bf16 v[12:15], v[176:179], v[200:203], v[12:15]
	v_mfma_f32_16x16x32_bf16 v[12:15], v[180:183], v[204:207], v[12:15]
	v_mfma_f32_16x16x32_bf16 v[4:7], v[180:183], v[212:215], v[4:7]
	v_mfma_f32_16x16x32_bf16 v[4:7], v[176:179], v[208:211], v[4:7]
	s_setprio 0
	s_barrier
	s_add_i32 s13, s13, 2
	s_add_u32 s10, s10, 0x10000
	s_addc_u32 s11, s11, 0
	s_add_u32 vcc_lo, vcc_lo, 0x10000
	s_addc_u32 vcc_hi, vcc_hi, 0
	s_cmpk_gt_u32 s13, 0x55
	s_cbranch_scc0 .LBB0_439
	s_and_b64 vcc, exec, s[6:7]
	s_cbranch_vccz .LBB0_442
	s_barrier

; #define PG8_LAS __attribute__((address_space(3)))
; #define PG8_STAGE(bufoff, gbase, voff) do { _Pragma("unroll") for (int _i = 0; _i < 2; ++_i) \
;         __builtin_amdgcn_global_load_lds((const unsigned*)((const char*)(gbase) + (voff)[_i]), (PG8_LAS unsigned*)(lds + (bufoff) + ldsw + _i * 8192), 16, 0, 0); } while (0)
; #define PG8_WAIT_V(n) asm volatile("s_waitcnt vmcnt(" #n ")" ::: "memory")
; #define PG8_BAR __builtin_amdgcn_s_barrier()
;     __device__ __forceinline__ void stage(const Unit& u, PG8_LAS unsigned char* area, int wr, int lane) const {
;         if (rs) { const float* src = rs + u.pm * BM + wr * 64 + lane;
;             __builtin_amdgcn_global_load_lds((const unsigned*)src, (PG8_LAS unsigned*)area, 4, 0, 0);
;             __builtin_amdgcn_global_load_lds((const unsigned*)(src + HALF), (PG8_LAS unsigned*)(area + 256), 4, 0, 0); }
; template <class Epi, class Sched, bool ALIGN_EPI = false, bool SP2 = false, bool ABLK = false, bool BBLK = false>
; __device__ __forceinline__ void gemm_phase(PG8_LAS unsigned char* lds, const Gemm g, const Sched& S, const Epi& E) {
;     ...
;         const bool has_next = S.next(ui + 1, nxt);
;         PG8_LAS unsigned char* const rs_area = lds + STAGE_BYTES + wid * 512;
;         E.stage(cur, rs_area, wr, lane);
;         const char* nA = has_next ? (const char*)g.A + (size_t)nxt.pm * tstep : cA; const char* nB = has_next ? (const char*)g.Bt + (size_t)nxt.pn * tstep : cB;
;         for (int t = 0; t < nt; t += 2) {
;             const bool last = (t == nt - 2);
;             const char* a1 = cA + (size_t)(t + 1) * kstepA;
;             const char* a2 = last ? nA : cA + (size_t)(t + 2) * kstepA; const char* b2 = last ? nB : cB + (size_t)(t + 2) * kstepB;
;             const char* a3 = a2 + kstepA; const char* b3 = b2 + kstepB;
;             if (last && has_next) S.a_ready(nxt);
;             if constexpr (SP2) {
;             PG8_LDB(B0, 0, 0); PG8_LDB(B1, 0, 1); PG8_SCHED; PG8_LDA(At, 0, 0); PG8_STAGE(PG8_SA(1, 1), a1 + hstepA, voffA);
;             PG8_WAIT_V(8); PG8_WAIT_L(0); PG8_BAR; PG8_MMA(0, 0, At, B0); PG8_MMA(0, 1, At, B1); PG8_BAR; PG8_SCHED;
;             PG8_LDA(At, 0, 1); PG8_STAGE(PG8_SB(0, 0), b2, voffB); PG8_STAGE(PG8_SB(0, 1), b2 + hstepB, voffB); PG8_STAGE(PG8_SA(0, 0), a2, voffA);
;             PG8_WAIT_V(8); PG8_WAIT_L(0); PG8_BAR; PG8_MMA(1, 0, At, B0); PG8_MMA(1, 1, At, B1); PG8_BAR; PG8_SCHED;
.LBB0_915:
	s_lshl_b32 s18, s0, 8
	s_ashr_i32 s19, s18, 31
	s_mov_b32 m0, s63
	v_lshl_add_u64 v[4:5], s[18:19], 2, v[144:145]
	v_lshl_add_u64 v[6:7], v[4:5], 0, s[90:91]
	global_load_lds_dword v[4:5], off
	s_add_i32 m0, s63, 0x100
	s_mov_b32 s0, s1
	global_load_lds_dword v[6:7], off
	s_ashr_i32 s1, s1, 31
	s_lshl_b64 s[10:11], s[0:1], 20
	v_readlane_b32 s16, v252, 27
	v_readlane_b32 s17, v252, 28
	s_add_u32 s10, s16, s10
	s_addc_u32 s11, s17, s11
	s_and_b64 s[16:17], s[2:3], exec
	s_cselect_b32 s1, s11, s21
	s_cselect_b32 s19, s10, s20
	s_ashr_i32 s9, s8, 31
	s_lshl_b64 s[16:17], s[8:9], 20
	v_readlane_b32 s24, v254, 5
	v_readlane_b32 s25, v254, 6
	s_add_u32 s16, s24, s16
	s_addc_u32 s17, s25, s17
	s_and_b64 s[24:25], s[2:3], exec
	s_cselect_b32 s9, s17, s23
	s_cselect_b32 s65, s16, s22
	s_add_u32 s20, s20, 0xc000
	s_addc_u32 s21, s21, 0
	s_add_u32 s70, s22, 0x10000
	s_addc_u32 s71, s23, 0
	s_mov_b32 s13, -2
	s_add_u32 s22, s20, 0x4000
	s_addc_u32 s23, s21, 0
	s_cmp_eq_u32 s13, 28
	s_cselect_b32 s26, s19, s22
	s_cselect_b32 s27, s1, s23
	s_cselect_b32 s24, s65, s70
	s_cselect_b32 s25, s9, s71
	s_add_u32 s22, s26, 0x8000
	s_addc_u32 s23, s27, 0
	s_add_i32 s68, 0, 0x10000
	v_add_u32_e32 v36, s68, v155
	s_add_i32 s77, 0, 0x14000
	ds_read_b128 v[150:153], v36
	ds_read_b128 v[158:161], v36 offset:1024
	ds_read_b128 v[162:165], v36 offset:2048
	ds_read_b128 v[166:169], v36 offset:3072
	v_add_u32_e32 v36, s77, v155
	ds_read_b128 v[170:173], v36
	ds_read_b128 v[174:177], v36 offset:1024
	ds_read_b128 v[178:181], v36 offset:2048
	ds_read_b128 v[182:185], v36 offset:3072
	s_add_i32 m0, s31, 0xc000
	ds_read_b128 v[186:189], v157
	ds_read_b128 v[190:193], v157 offset:1024
	ds_read_b128 v[194:197], v157 offset:2048
	ds_read_b128 v[198:201], v157 offset:3072
	ds_read_b128 v[202:205], v157 offset:4096
	ds_read_b128 v[206:209], v157 offset:5120
	ds_read_b128 v[210:213], v157 offset:6144
	ds_read_b128 v[214:217], v157 offset:7168
	global_load_lds_dwordx4 v146, s[20:21]
	s_add_i32 m0, s31, 0xe000
	s_nop 0
	global_load_lds_dwordx4 v148, s[20:21]
	s_waitcnt lgkmcnt(0)
	v_mfma_f32_16x16x32_bf16 v[132:135], v[150:153], v[186:189], 0
	v_mfma_f32_16x16x32_bf16 v[132:135], v[158:161], v[190:193], v[132:135]
	v_mfma_f32_16x16x32_bf16 v[128:131], v[166:169], v[190:193], 0
	v_mfma_f32_16x16x32_bf16 v[128:131], v[162:165], v[186:189], v[128:131]
	s_waitcnt vmcnt(8)
	s_barrier
	s_setprio 1
	v_mfma_f32_16x16x32_bf16 v[116:119], v[162:165], v[194:197], 0
	v_mfma_f32_16x16x32_bf16 v[116:119], v[166:169], v[198:201], v[116:119]
	v_mfma_f32_16x16x32_bf16 v[124:127], v[158:161], v[198:201], 0
	v_mfma_f32_16x16x32_bf16 v[124:127], v[150:153], v[194:197], v[124:127]
	v_mfma_f32_16x16x32_bf16 v[108:111], v[150:153], v[202:205], 0
	v_mfma_f32_16x16x32_bf16 v[108:111], v[158:161], v[206:209], v[108:111]
	v_mfma_f32_16x16x32_bf16 v[100:103], v[166:169], v[206:209], 0
	v_mfma_f32_16x16x32_bf16 v[100:103], v[162:165], v[202:205], v[100:103]
	v_mfma_f32_16x16x32_bf16 v[84:87], v[162:165], v[210:213], 0
	v_mfma_f32_16x16x32_bf16 v[84:87], v[166:169], v[214:217], v[84:87]
	v_mfma_f32_16x16x32_bf16 v[92:95], v[158:161], v[214:217], 0
	v_mfma_f32_16x16x32_bf16 v[92:95], v[150:153], v[210:213], v[92:95]
	v_mfma_f32_16x16x32_bf16 v[76:79], v[170:173], v[210:213], 0
	v_mfma_f32_16x16x32_bf16 v[76:79], v[174:177], v[214:217], v[76:79]
	v_mfma_f32_16x16x32_bf16 v[120:123], v[174:177], v[190:193], 0
	v_mfma_f32_16x16x32_bf16 v[120:123], v[170:173], v[186:189], v[120:123]
	v_mfma_f32_16x16x32_bf16 v[112:115], v[178:181], v[186:189], 0
	v_mfma_f32_16x16x32_bf16 v[112:115], v[182:185], v[190:193], v[112:115]
	v_mfma_f32_16x16x32_bf16 v[96:99], v[182:185], v[198:201], 0
	v_mfma_f32_16x16x32_bf16 v[96:99], v[178:181], v[194:197], v[96:99]
	v_mfma_f32_16x16x32_bf16 v[104:107], v[170:173], v[194:197], 0
	v_mfma_f32_16x16x32_bf16 v[104:107], v[174:177], v[198:201], v[104:107]
	v_mfma_f32_16x16x32_bf16 v[88:91], v[174:177], v[206:209], 0
	v_mfma_f32_16x16x32_bf16 v[88:91], v[170:173], v[202:205], v[88:91]
	v_mfma_f32_16x16x32_bf16 v[80:83], v[178:181], v[202:205], 0
	v_mfma_f32_16x16x32_bf16 v[80:83], v[182:185], v[206:209], v[80:83]
	v_mfma_f32_16x16x32_bf16 v[72:75], v[182:185], v[214:217], 0
	v_mfma_f32_16x16x32_bf16 v[72:75], v[178:181], v[210:213], v[72:75]
	s_setprio 0
	s_barrier
	s_add_i32 s68, s68, s29
	s_mov_b32 m0, s68
	ds_read_b128 v[186:189], v157 offset:16384
	ds_read_b128 v[190:193], v157 offset:17408
	ds_read_b128 v[194:197], v157 offset:18432
	ds_read_b128 v[198:201], v157 offset:19456
	ds_read_b128 v[202:205], v157 offset:20480
	ds_read_b128 v[206:209], v157 offset:21504
	ds_read_b128 v[210:213], v157 offset:22528
	ds_read_b128 v[214:217], v157 offset:23552
	global_load_lds_dwordx4 v140, s[24:25]
	s_add_i32 m0, s68, 0x2000
	s_add_u32 s68, s24, 0x4000
	s_addc_u32 s69, s25, 0
	s_add_i32 s77, s77, s29
	global_load_lds_dwordx4 v136, s[24:25]
	s_mov_b32 m0, s77
	s_nop 0
	global_load_lds_dwordx4 v140, s[68:69]
	s_add_i32 m0, s77, 0x2000
	s_nop 0
	global_load_lds_dwordx4 v136, s[68:69]
	s_mov_b32 m0, s31
	s_nop 0
	global_load_lds_dwordx4 v142, s[26:27]
	s_mov_b32 m0, s34
	s_nop 0
	global_load_lds_dwordx4 v138, s[26:27]
	s_waitcnt lgkmcnt(0)
	v_mfma_f32_16x16x32_bf16 v[68:71], v[150:153], v[186:189], 0
	v_mfma_f32_16x16x32_bf16 v[68:71], v[158:161], v[190:193], v[68:71]
	v_mfma_f32_16x16x32_bf16 v[64:67], v[166:169], v[190:193], 0
	v_mfma_f32_16x16x32_bf16 v[64:67], v[162:165], v[186:189], v[64:67]
	s_waitcnt vmcnt(8)
	s_barrier
; #define PG8_STAGE(bufoff, gbase, voff) do { _Pragma("unroll") for (int _i = 0; _i < 2; ++_i) \
;         __builtin_amdgcn_global_load_lds((const unsigned*)((const char*)(gbase) + (voff)[_i]), (PG8_LAS unsigned*)(lds + (bufoff) + ldsw + _i * 8192), 16, 0, 0); } while (0)
; #define PG8_LDA(dst, b, h) do { _Pragma("unroll") for (int m = 0; m < 4; ++m) _Pragma("unroll") for (int k = 0; k < 2; ++k) dst[m][k] = *(const PG8_LAS bf16x8*)(lds + PG8_SA(b, h) + aoff + m * 2048 + k * 1024); } while (0)
; #define PG8_LDB(dst, b, h) do { _Pragma("unroll") for (int n = 0; n < 2; ++n) _Pragma("unroll") for (int k = 0; k < 2; ++k) dst[n][k] = *(const PG8_LAS bf16x8*)(lds + PG8_SB(b, h) + boff + n * 2048 + k * 1024); } while (0)
; #define PG8_MMA(ai, bj, At, Bt) do { __builtin_amdgcn_s_setprio(1); _Pragma("unroll") for (int m = 0; m < 4; ++m) _Pragma("unroll") for (int n = 0; n < 2; ++n) _Pragma("unroll") for (int k = 0; k < 2; ++k) \
;         acc[ai][bj][m][n] = __builtin_amdgcn_mfma_f32_16x16x32_bf16(Bt[n][k], At[m][k], acc[ai][bj][m][n], 0, 0, 0); __builtin_amdgcn_s_setprio(0); } while (0)
; #define PG8_WAIT_V(n) asm volatile("s_waitcnt vmcnt(" #n ")" ::: "memory")
; #define PG8_WAIT_L(n) asm volatile("s_waitcnt lgkmcnt(" #n ")" ::: "memory")
; #define PG8_BAR __builtin_amdgcn_s_barrier()
; #define PG8_SCHED __builtin_amdgcn_sched_barrier(0)
; template <class Epi, class Sched, bool ALIGN_EPI = false, bool SP2 = false, bool ABLK = false, bool BBLK = false>
; __device__ __forceinline__ void gemm_phase(PG8_LAS unsigned char* lds, const Gemm g, const Sched& S, const Epi& E) {
;     ...
;             PG8_WAIT_V(8); PG8_WAIT_L(0); PG8_BAR; PG8_MMA(1, 0, At, B0); PG8_MMA(1, 1, At, B1); PG8_BAR; PG8_SCHED;
;             PG8_LDB(B0, 1, 0); PG8_LDB(B1, 1, 1); PG8_SCHED; PG8_LDA(At, 1, 0); PG8_STAGE(PG8_SA(0, 1), a2 + hstepA, voffA);
;             PG8_WAIT_V(8); PG8_WAIT_L(0); PG8_BAR; PG8_MMA(0, 0, At, B0); PG8_MMA(0, 1, At, B1); PG8_BAR; PG8_SCHED;
	s_setprio 1
	v_mfma_f32_16x16x32_bf16 v[52:55], v[162:165], v[194:197], 0
	v_mfma_f32_16x16x32_bf16 v[52:55], v[166:169], v[198:201], v[52:55]
	v_mfma_f32_16x16x32_bf16 v[60:63], v[158:161], v[198:201], 0
	v_mfma_f32_16x16x32_bf16 v[60:63], v[150:153], v[194:197], v[60:63]
	v_mfma_f32_16x16x32_bf16 v[44:47], v[150:153], v[202:205], 0
	v_mfma_f32_16x16x32_bf16 v[44:47], v[158:161], v[206:209], v[44:47]
	v_mfma_f32_16x16x32_bf16 v[32:35], v[166:169], v[206:209], 0
	v_mfma_f32_16x16x32_bf16 v[32:35], v[162:165], v[202:205], v[32:35]
	v_mfma_f32_16x16x32_bf16 v[16:19], v[162:165], v[210:213], 0
	v_mfma_f32_16x16x32_bf16 v[16:19], v[166:169], v[214:217], v[16:19]
	v_mfma_f32_16x16x32_bf16 v[24:27], v[158:161], v[214:217], 0
	v_mfma_f32_16x16x32_bf16 v[24:27], v[150:153], v[210:213], v[24:27]
	v_mfma_f32_16x16x32_bf16 v[8:11], v[170:173], v[210:213], 0
	v_mfma_f32_16x16x32_bf16 v[8:11], v[174:177], v[214:217], v[8:11]
	v_mfma_f32_16x16x32_bf16 v[56:59], v[174:177], v[190:193], 0
	v_mfma_f32_16x16x32_bf16 v[56:59], v[170:173], v[186:189], v[56:59]
	v_mfma_f32_16x16x32_bf16 v[48:51], v[178:181], v[186:189], 0
	v_mfma_f32_16x16x32_bf16 v[48:51], v[182:185], v[190:193], v[48:51]
	v_mfma_f32_16x16x32_bf16 v[28:31], v[182:185], v[198:201], 0
	v_mfma_f32_16x16x32_bf16 v[28:31], v[178:181], v[194:197], v[28:31]
	v_mfma_f32_16x16x32_bf16 v[40:43], v[170:173], v[194:197], 0
	v_mfma_f32_16x16x32_bf16 v[40:43], v[174:177], v[198:201], v[40:43]
	v_mfma_f32_16x16x32_bf16 v[20:23], v[174:177], v[206:209], 0
	v_mfma_f32_16x16x32_bf16 v[20:23], v[170:173], v[202:205], v[20:23]
	v_mfma_f32_16x16x32_bf16 v[12:15], v[178:181], v[202:205], 0
	v_mfma_f32_16x16x32_bf16 v[12:15], v[182:185], v[206:209], v[12:15]
	v_mfma_f32_16x16x32_bf16 v[4:7], v[182:185], v[214:217], 0
	v_mfma_f32_16x16x32_bf16 v[4:7], v[178:181], v[210:213], v[4:7]
	s_setprio 0
	s_barrier
	s_add_i32 s68, 0, 0x18000
	v_add_u32_e32 v36, s68, v155
	s_add_i32 s69, 0, 0x1c000
	ds_read_b128 v[150:153], v36
	ds_read_b128 v[158:161], v36 offset:1024
	ds_read_b128 v[162:165], v36 offset:2048
	ds_read_b128 v[166:169], v36 offset:3072
	v_add_u32_e32 v36, s69, v155
	ds_read_b128 v[170:173], v36
	ds_read_b128 v[174:177], v36 offset:1024
	ds_read_b128 v[178:181], v36 offset:2048
	ds_read_b128 v[182:185], v36 offset:3072
	s_add_u32 s26, s26, 0x4000
	s_addc_u32 s27, s27, 0
	s_mov_b32 m0, s35
	ds_read_b128 v[186:189], v157 offset:32768
	ds_read_b128 v[190:193], v157 offset:33792
	ds_read_b128 v[194:197], v157 offset:34816
	ds_read_b128 v[198:201], v157 offset:35840
	ds_read_b128 v[202:205], v157 offset:36864
	ds_read_b128 v[206:209], v157 offset:37888
	ds_read_b128 v[210:213], v157 offset:38912
	ds_read_b128 v[214:217], v157 offset:39936
	global_load_lds_dwordx4 v142, s[26:27]
	s_mov_b32 m0, s36
	s_nop 0
	global_load_lds_dwordx4 v138, s[26:27]
	s_waitcnt lgkmcnt(0)
	v_mfma_f32_16x16x32_bf16 v[132:135], v[150:153], v[186:189], v[132:135]
	v_mfma_f32_16x16x32_bf16 v[132:135], v[158:161], v[190:193], v[132:135]
	v_mfma_f32_16x16x32_bf16 v[128:131], v[166:169], v[190:193], v[128:131]
	v_mfma_f32_16x16x32_bf16 v[128:131], v[162:165], v[186:189], v[128:131]
	s_waitcnt vmcnt(8)
	s_barrier
	s_setprio 1
	v_mfma_f32_16x16x32_bf16 v[116:119], v[162:165], v[194:197], v[116:119]
	v_mfma_f32_16x16x32_bf16 v[116:119], v[166:169], v[198:201], v[116:119]
	v_mfma_f32_16x16x32_bf16 v[124:127], v[158:161], v[198:201], v[124:127]
	v_mfma_f32_16x16x32_bf16 v[124:127], v[150:153], v[194:197], v[124:127]
	v_mfma_f32_16x16x32_bf16 v[108:111], v[150:153], v[202:205], v[108:111]
	v_mfma_f32_16x16x32_bf16 v[108:111], v[158:161], v[206:209], v[108:111]
	v_mfma_f32_16x16x32_bf16 v[100:103], v[166:169], v[206:209], v[100:103]
	v_mfma_f32_16x16x32_bf16 v[100:103], v[162:165], v[202:205], v[100:103]
	v_mfma_f32_16x16x32_bf16 v[84:87], v[162:165], v[210:213], v[84:87]
	v_mfma_f32_16x16x32_bf16 v[84:87], v[166:169], v[214:217], v[84:87]
	v_mfma_f32_16x16x32_bf16 v[92:95], v[158:161], v[214:217], v[92:95]
	v_mfma_f32_16x16x32_bf16 v[92:95], v[150:153], v[210:213], v[92:95]
	v_mfma_f32_16x16x32_bf16 v[76:79], v[170:173], v[210:213], v[76:79]
	v_mfma_f32_16x16x32_bf16 v[76:79], v[174:177], v[214:217], v[76:79]
	v_mfma_f32_16x16x32_bf16 v[120:123], v[174:177], v[190:193], v[120:123]
	v_mfma_f32_16x16x32_bf16 v[120:123], v[170:173], v[186:189], v[120:123]
	v_mfma_f32_16x16x32_bf16 v[112:115], v[178:181], v[186:189], v[112:115]
	v_mfma_f32_16x16x32_bf16 v[112:115], v[182:185], v[190:193], v[112:115]
	v_mfma_f32_16x16x32_bf16 v[96:99], v[182:185], v[198:201], v[96:99]
	v_mfma_f32_16x16x32_bf16 v[96:99], v[178:181], v[194:197], v[96:99]
	v_mfma_f32_16x16x32_bf16 v[104:107], v[170:173], v[194:197], v[104:107]
	v_mfma_f32_16x16x32_bf16 v[104:107], v[174:177], v[198:201], v[104:107]
	v_mfma_f32_16x16x32_bf16 v[88:91], v[174:177], v[206:209], v[88:91]
	v_mfma_f32_16x16x32_bf16 v[88:91], v[170:173], v[202:205], v[88:91]
	v_mfma_f32_16x16x32_bf16 v[80:83], v[178:181], v[202:205], v[80:83]
	v_mfma_f32_16x16x32_bf16 v[80:83], v[182:185], v[206:209], v[80:83]
	v_mfma_f32_16x16x32_bf16 v[72:75], v[182:185], v[214:217], v[72:75]
	v_mfma_f32_16x16x32_bf16 v[72:75], v[178:181], v[210:213], v[72:75]
	s_setprio 0
	s_barrier
; #define PG8_STAGE(bufoff, gbase, voff) do { _Pragma("unroll") for (int _i = 0; _i < 2; ++_i) \
;         __builtin_amdgcn_global_load_lds((const unsigned*)((const char*)(gbase) + (voff)[_i]), (PG8_LAS unsigned*)(lds + (bufoff) + ldsw + _i * 8192), 16, 0, 0); } while (0)
; #define PG8_LDA(dst, b, h) do { _Pragma("unroll") for (int m = 0; m < 4; ++m) _Pragma("unroll") for (int k = 0; k < 2; ++k) dst[m][k] = *(const PG8_LAS bf16x8*)(lds + PG8_SA(b, h) + aoff + m * 2048 + k * 1024); } while (0)
; #define PG8_LDB(dst, b, h) do { _Pragma("unroll") for (int n = 0; n < 2; ++n) _Pragma("unroll") for (int k = 0; k < 2; ++k) dst[n][k] = *(const PG8_LAS bf16x8*)(lds + PG8_SB(b, h) + boff + n * 2048 + k * 1024); } while (0)
; #define PG8_WAIT_V(n) asm volatile("s_waitcnt vmcnt(" #n ")" ::: "memory")
; #define PG8_WAIT_L(n) asm volatile("s_waitcnt lgkmcnt(" #n ")" ::: "memory")
; #define PG8_BAR __builtin_amdgcn_s_barrier()
; template <class Epi, class Sched, bool ALIGN_EPI = false, bool SP2 = false, bool ABLK = false, bool BBLK = false>
; __device__ __forceinline__ void gemm_phase(PG8_LAS unsigned char* lds, const Gemm g, const Sched& S, const Epi& E) {
;     ...
;         for (int t = 0; t < nt; t += 2) {
;             const bool last = (t == nt - 2);
;             const char* a1 = cA + (size_t)(t + 1) * kstepA;
;             const char* a2 = last ? nA : cA + (size_t)(t + 2) * kstepA; const char* b2 = last ? nB : cB + (size_t)(t + 2) * kstepB;
;             const char* a3 = a2 + kstepA; const char* b3 = b2 + kstepB;
;             if (last && has_next) S.a_ready(nxt);
;             if constexpr (SP2) {
;             PG8_LDB(B0, 0, 0); PG8_LDB(B1, 0, 1); PG8_SCHED; PG8_LDA(At, 0, 0); PG8_STAGE(PG8_SA(1, 1), a1 + hstepA, voffA);
;             PG8_WAIT_V(8); PG8_WAIT_L(0); PG8_BAR; PG8_MMA(0, 0, At, B0); PG8_MMA(0, 1, At, B1); PG8_BAR; PG8_SCHED;
;             PG8_LDA(At, 0, 1); PG8_STAGE(PG8_SB(0, 0), b2, voffB); PG8_STAGE(PG8_SB(0, 1), b2 + hstepB, voffB); PG8_STAGE(PG8_SA(0, 0), a2, voffA);
;             PG8_WAIT_V(8); PG8_WAIT_L(0); PG8_BAR; PG8_MMA(1, 0, At, B0); PG8_MMA(1, 1, At, B1); PG8_BAR; PG8_SCHED;
;     ...
;             PG8_LDA(At, 1, 1); PG8_STAGE(PG8_SB(1, 0), b3, voffB); PG8_STAGE(PG8_SB(1, 1), b3 + hstepB, voffB); PG8_STAGE(PG8_SA(1, 0), a3, voffA);
;             PG8_WAIT_V(8); PG8_WAIT_L(0); PG8_BAR; PG8_MMA(1, 0, At, B0); PG8_MMA(1, 1, At, B1); PG8_BAR; PG8_SCHED;
	s_add_u32 s26, s24, 0x8000
	s_addc_u32 s27, s25, 0
	s_add_i32 s68, s68, s29
	s_mov_b32 m0, s68
	ds_read_b128 v[186:189], v157 offset:49152
	ds_read_b128 v[190:193], v157 offset:50176
	ds_read_b128 v[194:197], v157 offset:51200
	ds_read_b128 v[198:201], v157 offset:52224
	ds_read_b128 v[202:205], v157 offset:53248
	ds_read_b128 v[206:209], v157 offset:54272
	ds_read_b128 v[210:213], v157 offset:55296
	ds_read_b128 v[214:217], v157 offset:56320
	global_load_lds_dwordx4 v140, s[26:27]
	s_add_i32 m0, s68, 0x2000
	s_add_u32 s24, s24, 0xc000
	s_addc_u32 s25, s25, 0
	global_load_lds_dwordx4 v136, s[26:27]
	s_add_i32 s26, s69, s29
	s_mov_b32 m0, s26
	s_nop 0
	global_load_lds_dwordx4 v140, s[24:25]
	s_add_i32 m0, s26, 0x2000
	s_nop 0
	global_load_lds_dwordx4 v136, s[24:25]
	s_mov_b32 m0, s37
	s_nop 0
	global_load_lds_dwordx4 v142, s[22:23]
	s_mov_b32 m0, s62
	s_nop 0
	global_load_lds_dwordx4 v138, s[22:23]
	s_waitcnt lgkmcnt(0)
	v_mfma_f32_16x16x32_bf16 v[68:71], v[150:153], v[186:189], v[68:71]
	v_mfma_f32_16x16x32_bf16 v[68:71], v[158:161], v[190:193], v[68:71]
	v_mfma_f32_16x16x32_bf16 v[64:67], v[166:169], v[190:193], v[64:67]
	v_mfma_f32_16x16x32_bf16 v[64:67], v[162:165], v[186:189], v[64:67]
	s_waitcnt vmcnt(8)
	s_barrier
	s_setprio 1
	v_mfma_f32_16x16x32_bf16 v[52:55], v[162:165], v[194:197], v[52:55]
	v_mfma_f32_16x16x32_bf16 v[52:55], v[166:169], v[198:201], v[52:55]
	v_mfma_f32_16x16x32_bf16 v[60:63], v[158:161], v[198:201], v[60:63]
	v_mfma_f32_16x16x32_bf16 v[60:63], v[150:153], v[194:197], v[60:63]
	v_mfma_f32_16x16x32_bf16 v[44:47], v[150:153], v[202:205], v[44:47]
	v_mfma_f32_16x16x32_bf16 v[44:47], v[158:161], v[206:209], v[44:47]
	v_mfma_f32_16x16x32_bf16 v[32:35], v[166:169], v[206:209], v[32:35]
	v_mfma_f32_16x16x32_bf16 v[32:35], v[162:165], v[202:205], v[32:35]
	v_mfma_f32_16x16x32_bf16 v[16:19], v[162:165], v[210:213], v[16:19]
	v_mfma_f32_16x16x32_bf16 v[16:19], v[166:169], v[214:217], v[16:19]
	v_mfma_f32_16x16x32_bf16 v[24:27], v[158:161], v[214:217], v[24:27]
	v_mfma_f32_16x16x32_bf16 v[24:27], v[150:153], v[210:213], v[24:27]
	v_mfma_f32_16x16x32_bf16 v[8:11], v[170:173], v[210:213], v[8:11]
	v_mfma_f32_16x16x32_bf16 v[8:11], v[174:177], v[214:217], v[8:11]
	v_mfma_f32_16x16x32_bf16 v[56:59], v[174:177], v[190:193], v[56:59]
	v_mfma_f32_16x16x32_bf16 v[56:59], v[170:173], v[186:189], v[56:59]
	v_mfma_f32_16x16x32_bf16 v[48:51], v[178:181], v[186:189], v[48:51]
	v_mfma_f32_16x16x32_bf16 v[48:51], v[182:185], v[190:193], v[48:51]
	v_mfma_f32_16x16x32_bf16 v[28:31], v[182:185], v[198:201], v[28:31]
	v_mfma_f32_16x16x32_bf16 v[28:31], v[178:181], v[194:197], v[28:31]
	v_mfma_f32_16x16x32_bf16 v[40:43], v[170:173], v[194:197], v[40:43]
	v_mfma_f32_16x16x32_bf16 v[40:43], v[174:177], v[198:201], v[40:43]
	v_mfma_f32_16x16x32_bf16 v[20:23], v[174:177], v[206:209], v[20:23]
	v_mfma_f32_16x16x32_bf16 v[20:23], v[170:173], v[202:205], v[20:23]
	v_mfma_f32_16x16x32_bf16 v[12:15], v[178:181], v[202:205], v[12:15]
	v_mfma_f32_16x16x32_bf16 v[12:15], v[182:185], v[206:209], v[12:15]
	v_mfma_f32_16x16x32_bf16 v[4:7], v[182:185], v[214:217], v[4:7]
	v_mfma_f32_16x16x32_bf16 v[4:7], v[178:181], v[210:213], v[4:7]
	s_setprio 0
	s_barrier
	s_add_i32 s13, s13, 2
	s_add_u32 s20, s20, 0x10000
	s_addc_u32 s21, s21, 0
	s_add_u32 s70, s70, 0x10000
	s_addc_u32 s71, s71, 0
	s_cmp_gt_u32 s13, 29
.LBB0_916:
	s_add_u32 s22, s20, 0x4000
	s_addc_u32 s23, s21, 0
	s_cmp_eq_u32 s13, 28
	s_cselect_b32 s26, s19, s22
	s_cselect_b32 s27, s1, s23
	s_cselect_b32 s24, s65, s70
	s_cselect_b32 s25, s9, s71
	s_add_u32 s22, s26, 0x8000
	s_addc_u32 s23, s27, 0
	s_add_i32 s68, 0, 0x10000
	v_add_u32_e32 v36, s68, v155
	s_add_i32 s77, 0, 0x14000
	ds_read_b128 v[150:153], v36
	ds_read_b128 v[158:161], v36 offset:1024
	ds_read_b128 v[162:165], v36 offset:2048
	ds_read_b128 v[166:169], v36 offset:3072
	v_add_u32_e32 v36, s77, v155
	ds_read_b128 v[170:173], v36
	ds_read_b128 v[174:177], v36 offset:1024
	ds_read_b128 v[178:181], v36 offset:2048
	ds_read_b128 v[182:185], v36 offset:3072
	s_add_i32 m0, s31, 0xc000
	ds_read_b128 v[186:189], v157
	ds_read_b128 v[190:193], v157 offset:1024
	ds_read_b128 v[194:197], v157 offset:2048
	ds_read_b128 v[198:201], v157 offset:3072
	ds_read_b128 v[202:205], v157 offset:4096
	ds_read_b128 v[206:209], v157 offset:5120
	ds_read_b128 v[210:213], v157 offset:6144
	ds_read_b128 v[214:217], v157 offset:7168
	global_load_lds_dwordx4 v146, s[20:21]
	s_add_i32 m0, s31, 0xe000
	s_nop 0
	global_load_lds_dwordx4 v148, s[20:21]
	s_waitcnt lgkmcnt(0)
	v_mfma_f32_16x16x32_bf16 v[132:135], v[150:153], v[186:189], v[132:135]
	v_mfma_f32_16x16x32_bf16 v[132:135], v[158:161], v[190:193], v[132:135]
	v_mfma_f32_16x16x32_bf16 v[128:131], v[166:169], v[190:193], v[128:131]
	v_mfma_f32_16x16x32_bf16 v[128:131], v[162:165], v[186:189], v[128:131]
	s_waitcnt vmcnt(8)
	s_barrier
; #define PG8_STAGE(bufoff, gbase, voff) do { _Pragma("unroll") for (int _i = 0; _i < 2; ++_i) \
;         __builtin_amdgcn_global_load_lds((const unsigned*)((const char*)(gbase) + (voff)[_i]), (PG8_LAS unsigned*)(lds + (bufoff) + ldsw + _i * 8192), 16, 0, 0); } while (0)
; #define PG8_LDA(dst, b, h) do { _Pragma("unroll") for (int m = 0; m < 4; ++m) _Pragma("unroll") for (int k = 0; k < 2; ++k) dst[m][k] = *(const PG8_LAS bf16x8*)(lds + PG8_SA(b, h) + aoff + m * 2048 + k * 1024); } while (0)
; #define PG8_MMA(ai, bj, At, Bt) do { __builtin_amdgcn_s_setprio(1); _Pragma("unroll") for (int m = 0; m < 4; ++m) _Pragma("unroll") for (int n = 0; n < 2; ++n) _Pragma("unroll") for (int k = 0; k < 2; ++k) \
;         acc[ai][bj][m][n] = __builtin_amdgcn_mfma_f32_16x16x32_bf16(Bt[n][k], At[m][k], acc[ai][bj][m][n], 0, 0, 0); __builtin_amdgcn_s_setprio(0); } while (0)
; #define PG8_WAIT_V(n) asm volatile("s_waitcnt vmcnt(" #n ")" ::: "memory")
; #define PG8_WAIT_L(n) asm volatile("s_waitcnt lgkmcnt(" #n ")" ::: "memory")
; #define PG8_BAR __builtin_amdgcn_s_barrier()
; #define PG8_SCHED __builtin_amdgcn_sched_barrier(0)
; template <class Epi, class Sched, bool ALIGN_EPI = false, bool SP2 = false, bool ABLK = false, bool BBLK = false>
; __device__ __forceinline__ void gemm_phase(PG8_LAS unsigned char* lds, const Gemm g, const Sched& S, const Epi& E) {
;     ...
;             PG8_WAIT_V(8); PG8_WAIT_L(0); PG8_BAR; PG8_MMA(0, 0, At, B0); PG8_MMA(0, 1, At, B1); PG8_BAR; PG8_SCHED;
;             PG8_LDA(At, 0, 1); PG8_STAGE(PG8_SB(0, 0), b2, voffB); PG8_STAGE(PG8_SB(0, 1), b2 + hstepB, voffB); PG8_STAGE(PG8_SA(0, 0), a2, voffA);
;             PG8_WAIT_V(8); PG8_WAIT_L(0); PG8_BAR; PG8_MMA(1, 0, At, B0); PG8_MMA(1, 1, At, B1); PG8_BAR; PG8_SCHED;
	s_setprio 1
	v_mfma_f32_16x16x32_bf16 v[116:119], v[162:165], v[194:197], v[116:119]
	v_mfma_f32_16x16x32_bf16 v[116:119], v[166:169], v[198:201], v[116:119]
	v_mfma_f32_16x16x32_bf16 v[124:127], v[158:161], v[198:201], v[124:127]
	v_mfma_f32_16x16x32_bf16 v[124:127], v[150:153], v[194:197], v[124:127]
	v_mfma_f32_16x16x32_bf16 v[108:111], v[150:153], v[202:205], v[108:111]
	v_mfma_f32_16x16x32_bf16 v[108:111], v[158:161], v[206:209], v[108:111]
	v_mfma_f32_16x16x32_bf16 v[100:103], v[166:169], v[206:209], v[100:103]
	v_mfma_f32_16x16x32_bf16 v[100:103], v[162:165], v[202:205], v[100:103]
	v_mfma_f32_16x16x32_bf16 v[84:87], v[162:165], v[210:213], v[84:87]
	v_mfma_f32_16x16x32_bf16 v[84:87], v[166:169], v[214:217], v[84:87]
	v_mfma_f32_16x16x32_bf16 v[92:95], v[158:161], v[214:217], v[92:95]
	v_mfma_f32_16x16x32_bf16 v[92:95], v[150:153], v[210:213], v[92:95]
	v_mfma_f32_16x16x32_bf16 v[76:79], v[170:173], v[210:213], v[76:79]
	v_mfma_f32_16x16x32_bf16 v[76:79], v[174:177], v[214:217], v[76:79]
	v_mfma_f32_16x16x32_bf16 v[120:123], v[174:177], v[190:193], v[120:123]
	v_mfma_f32_16x16x32_bf16 v[120:123], v[170:173], v[186:189], v[120:123]
	v_mfma_f32_16x16x32_bf16 v[112:115], v[178:181], v[186:189], v[112:115]
	v_mfma_f32_16x16x32_bf16 v[112:115], v[182:185], v[190:193], v[112:115]
	v_mfma_f32_16x16x32_bf16 v[96:99], v[182:185], v[198:201], v[96:99]
	v_mfma_f32_16x16x32_bf16 v[96:99], v[178:181], v[194:197], v[96:99]
	v_mfma_f32_16x16x32_bf16 v[104:107], v[170:173], v[194:197], v[104:107]
	v_mfma_f32_16x16x32_bf16 v[104:107], v[174:177], v[198:201], v[104:107]
	v_mfma_f32_16x16x32_bf16 v[88:91], v[174:177], v[206:209], v[88:91]
	v_mfma_f32_16x16x32_bf16 v[88:91], v[170:173], v[202:205], v[88:91]
	v_mfma_f32_16x16x32_bf16 v[80:83], v[178:181], v[202:205], v[80:83]
	v_mfma_f32_16x16x32_bf16 v[80:83], v[182:185], v[206:209], v[80:83]
	v_mfma_f32_16x16x32_bf16 v[72:75], v[182:185], v[214:217], v[72:75]
	v_mfma_f32_16x16x32_bf16 v[72:75], v[178:181], v[210:213], v[72:75]
	s_setprio 0
	s_barrier
	s_add_i32 s68, s68, s29
	s_mov_b32 m0, s68
	ds_read_b128 v[186:189], v157 offset:16384
	ds_read_b128 v[190:193], v157 offset:17408
	ds_read_b128 v[194:197], v157 offset:18432
	ds_read_b128 v[198:201], v157 offset:19456
	ds_read_b128 v[202:205], v157 offset:20480
	ds_read_b128 v[206:209], v157 offset:21504
	ds_read_b128 v[210:213], v157 offset:22528
	ds_read_b128 v[214:217], v157 offset:23552
	global_load_lds_dwordx4 v140, s[24:25]
	s_add_i32 m0, s68, 0x2000
	s_add_u32 s68, s24, 0x4000
	s_addc_u32 s69, s25, 0
	s_add_i32 s77, s77, s29
	global_load_lds_dwordx4 v136, s[24:25]
	s_mov_b32 m0, s77
	s_nop 0
	global_load_lds_dwordx4 v140, s[68:69]
	s_add_i32 m0, s77, 0x2000
	s_nop 0
	global_load_lds_dwordx4 v136, s[68:69]
	s_mov_b32 m0, s31
	s_nop 0
	global_load_lds_dwordx4 v142, s[26:27]
	s_mov_b32 m0, s34
	s_nop 0
	global_load_lds_dwordx4 v138, s[26:27]
	s_waitcnt lgkmcnt(0)
	v_mfma_f32_16x16x32_bf16 v[68:71], v[150:153], v[186:189], v[68:71]
	v_mfma_f32_16x16x32_bf16 v[68:71], v[158:161], v[190:193], v[68:71]
	v_mfma_f32_16x16x32_bf16 v[64:67], v[166:169], v[190:193], v[64:67]
	v_mfma_f32_16x16x32_bf16 v[64:67], v[162:165], v[186:189], v[64:67]
	s_waitcnt vmcnt(8)
	s_barrier
	s_setprio 1
	v_mfma_f32_16x16x32_bf16 v[52:55], v[162:165], v[194:197], v[52:55]
	v_mfma_f32_16x16x32_bf16 v[52:55], v[166:169], v[198:201], v[52:55]
	v_mfma_f32_16x16x32_bf16 v[60:63], v[158:161], v[198:201], v[60:63]
	v_mfma_f32_16x16x32_bf16 v[60:63], v[150:153], v[194:197], v[60:63]
	v_mfma_f32_16x16x32_bf16 v[44:47], v[150:153], v[202:205], v[44:47]
	v_mfma_f32_16x16x32_bf16 v[44:47], v[158:161], v[206:209], v[44:47]
	v_mfma_f32_16x16x32_bf16 v[32:35], v[166:169], v[206:209], v[32:35]
	v_mfma_f32_16x16x32_bf16 v[32:35], v[162:165], v[202:205], v[32:35]
	v_mfma_f32_16x16x32_bf16 v[16:19], v[162:165], v[210:213], v[16:19]
	v_mfma_f32_16x16x32_bf16 v[16:19], v[166:169], v[214:217], v[16:19]
	v_mfma_f32_16x16x32_bf16 v[24:27], v[158:161], v[214:217], v[24:27]
	v_mfma_f32_16x16x32_bf16 v[24:27], v[150:153], v[210:213], v[24:27]
	v_mfma_f32_16x16x32_bf16 v[8:11], v[170:173], v[210:213], v[8:11]
	v_mfma_f32_16x16x32_bf16 v[8:11], v[174:177], v[214:217], v[8:11]
	v_mfma_f32_16x16x32_bf16 v[56:59], v[174:177], v[190:193], v[56:59]
	v_mfma_f32_16x16x32_bf16 v[56:59], v[170:173], v[186:189], v[56:59]
	v_mfma_f32_16x16x32_bf16 v[48:51], v[178:181], v[186:189], v[48:51]
	v_mfma_f32_16x16x32_bf16 v[48:51], v[182:185], v[190:193], v[48:51]
	v_mfma_f32_16x16x32_bf16 v[28:31], v[182:185], v[198:201], v[28:31]
	v_mfma_f32_16x16x32_bf16 v[28:31], v[178:181], v[194:197], v[28:31]
	v_mfma_f32_16x16x32_bf16 v[40:43], v[170:173], v[194:197], v[40:43]
	v_mfma_f32_16x16x32_bf16 v[40:43], v[174:177], v[198:201], v[40:43]
	v_mfma_f32_16x16x32_bf16 v[20:23], v[174:177], v[206:209], v[20:23]
	v_mfma_f32_16x16x32_bf16 v[20:23], v[170:173], v[202:205], v[20:23]
	v_mfma_f32_16x16x32_bf16 v[12:15], v[178:181], v[202:205], v[12:15]
	v_mfma_f32_16x16x32_bf16 v[12:15], v[182:185], v[206:209], v[12:15]
	v_mfma_f32_16x16x32_bf16 v[4:7], v[182:185], v[214:217], v[4:7]
	v_mfma_f32_16x16x32_bf16 v[4:7], v[178:181], v[210:213], v[4:7]
	s_setprio 0
	s_barrier
; #define PG8_STAGE(bufoff, gbase, voff) do { _Pragma("unroll") for (int _i = 0; _i < 2; ++_i) \
;         __builtin_amdgcn_global_load_lds((const unsigned*)((const char*)(gbase) + (voff)[_i]), (PG8_LAS unsigned*)(lds + (bufoff) + ldsw + _i * 8192), 16, 0, 0); } while (0)
; #define PG8_LDA(dst, b, h) do { _Pragma("unroll") for (int m = 0; m < 4; ++m) _Pragma("unroll") for (int k = 0; k < 2; ++k) dst[m][k] = *(const PG8_LAS bf16x8*)(lds + PG8_SA(b, h) + aoff + m * 2048 + k * 1024); } while (0)
; #define PG8_LDB(dst, b, h) do { _Pragma("unroll") for (int n = 0; n < 2; ++n) _Pragma("unroll") for (int k = 0; k < 2; ++k) dst[n][k] = *(const PG8_LAS bf16x8*)(lds + PG8_SB(b, h) + boff + n * 2048 + k * 1024); } while (0)
; #define PG8_MMA(ai, bj, At, Bt) do { __builtin_amdgcn_s_setprio(1); _Pragma("unroll") for (int m = 0; m < 4; ++m) _Pragma("unroll") for (int n = 0; n < 2; ++n) _Pragma("unroll") for (int k = 0; k < 2; ++k) \
;         acc[ai][bj][m][n] = __builtin_amdgcn_mfma_f32_16x16x32_bf16(Bt[n][k], At[m][k], acc[ai][bj][m][n], 0, 0, 0); __builtin_amdgcn_s_setprio(0); } while (0)
; #define PG8_WAIT_V(n) asm volatile("s_waitcnt vmcnt(" #n ")" ::: "memory")
; #define PG8_BAR __builtin_amdgcn_s_barrier()
; template <class Epi, class Sched, bool ALIGN_EPI = false, bool SP2 = false, bool ABLK = false, bool BBLK = false>
; __device__ __forceinline__ void gemm_phase(PG8_LAS unsigned char* lds, const Gemm g, const Sched& S, const Epi& E) {
;     ...
;         for (int t = 0; t < nt; t += 2) {
;             const bool last = (t == nt - 2);
;             const char* a1 = cA + (size_t)(t + 1) * kstepA;
;             const char* a2 = last ? nA : cA + (size_t)(t + 2) * kstepA; const char* b2 = last ? nB : cB + (size_t)(t + 2) * kstepB;
;             const char* a3 = a2 + kstepA; const char* b3 = b2 + kstepB;
;     ...
;             PG8_LDB(B0, 1, 0); PG8_LDB(B1, 1, 1); PG8_SCHED; PG8_LDA(At, 1, 0); PG8_STAGE(PG8_SA(0, 1), a2 + hstepA, voffA);
;             PG8_WAIT_V(8); PG8_WAIT_L(0); PG8_BAR; PG8_MMA(0, 0, At, B0); PG8_MMA(0, 1, At, B1); PG8_BAR; PG8_SCHED;
;             PG8_LDA(At, 1, 1); PG8_STAGE(PG8_SB(1, 0), b3, voffB); PG8_STAGE(PG8_SB(1, 1), b3 + hstepB, voffB); PG8_STAGE(PG8_SA(1, 0), a3, voffA);
;             PG8_WAIT_V(8); PG8_WAIT_L(0); PG8_BAR; PG8_MMA(1, 0, At, B0); PG8_MMA(1, 1, At, B1); PG8_BAR; PG8_SCHED;
;     ...
;         if constexpr (ALIGN_EPI) { if (wr == 0) PG8_BAR; }
	s_add_i32 s68, 0, 0x18000
	v_add_u32_e32 v36, s68, v155
	s_add_i32 s69, 0, 0x1c000
	ds_read_b128 v[150:153], v36
	ds_read_b128 v[158:161], v36 offset:1024
	ds_read_b128 v[162:165], v36 offset:2048
	ds_read_b128 v[166:169], v36 offset:3072
	v_add_u32_e32 v36, s69, v155
	ds_read_b128 v[170:173], v36
	ds_read_b128 v[174:177], v36 offset:1024
	ds_read_b128 v[178:181], v36 offset:2048
	ds_read_b128 v[182:185], v36 offset:3072
	s_add_u32 s26, s26, 0x4000
	s_addc_u32 s27, s27, 0
	s_mov_b32 m0, s35
	ds_read_b128 v[186:189], v157 offset:32768
	ds_read_b128 v[190:193], v157 offset:33792
	ds_read_b128 v[194:197], v157 offset:34816
	ds_read_b128 v[198:201], v157 offset:35840
	ds_read_b128 v[202:205], v157 offset:36864
	ds_read_b128 v[206:209], v157 offset:37888
	ds_read_b128 v[210:213], v157 offset:38912
	ds_read_b128 v[214:217], v157 offset:39936
	global_load_lds_dwordx4 v142, s[26:27]
	s_mov_b32 m0, s36
	s_nop 0
	global_load_lds_dwordx4 v138, s[26:27]
	s_waitcnt lgkmcnt(0)
	v_mfma_f32_16x16x32_bf16 v[132:135], v[150:153], v[186:189], v[132:135]
	v_mfma_f32_16x16x32_bf16 v[132:135], v[158:161], v[190:193], v[132:135]
	v_mfma_f32_16x16x32_bf16 v[128:131], v[166:169], v[190:193], v[128:131]
	v_mfma_f32_16x16x32_bf16 v[128:131], v[162:165], v[186:189], v[128:131]
	s_waitcnt vmcnt(8)
	s_barrier
	s_setprio 1
	v_mfma_f32_16x16x32_bf16 v[116:119], v[162:165], v[194:197], v[116:119]
	v_mfma_f32_16x16x32_bf16 v[116:119], v[166:169], v[198:201], v[116:119]
	v_mfma_f32_16x16x32_bf16 v[124:127], v[158:161], v[198:201], v[124:127]
	v_mfma_f32_16x16x32_bf16 v[124:127], v[150:153], v[194:197], v[124:127]
	v_mfma_f32_16x16x32_bf16 v[108:111], v[150:153], v[202:205], v[108:111]
	v_mfma_f32_16x16x32_bf16 v[108:111], v[158:161], v[206:209], v[108:111]
	v_mfma_f32_16x16x32_bf16 v[100:103], v[166:169], v[206:209], v[100:103]
	v_mfma_f32_16x16x32_bf16 v[100:103], v[162:165], v[202:205], v[100:103]
	v_mfma_f32_16x16x32_bf16 v[84:87], v[162:165], v[210:213], v[84:87]
	v_mfma_f32_16x16x32_bf16 v[84:87], v[166:169], v[214:217], v[84:87]
	v_mfma_f32_16x16x32_bf16 v[92:95], v[158:161], v[214:217], v[92:95]
	v_mfma_f32_16x16x32_bf16 v[92:95], v[150:153], v[210:213], v[92:95]
	v_mfma_f32_16x16x32_bf16 v[76:79], v[170:173], v[210:213], v[76:79]
	v_mfma_f32_16x16x32_bf16 v[76:79], v[174:177], v[214:217], v[76:79]
	v_mfma_f32_16x16x32_bf16 v[120:123], v[174:177], v[190:193], v[120:123]
	v_mfma_f32_16x16x32_bf16 v[120:123], v[170:173], v[186:189], v[120:123]
	v_mfma_f32_16x16x32_bf16 v[112:115], v[178:181], v[186:189], v[112:115]
	v_mfma_f32_16x16x32_bf16 v[112:115], v[182:185], v[190:193], v[112:115]
	v_mfma_f32_16x16x32_bf16 v[96:99], v[182:185], v[198:201], v[96:99]
	v_mfma_f32_16x16x32_bf16 v[96:99], v[178:181], v[194:197], v[96:99]
	v_mfma_f32_16x16x32_bf16 v[104:107], v[170:173], v[194:197], v[104:107]
	v_mfma_f32_16x16x32_bf16 v[104:107], v[174:177], v[198:201], v[104:107]
	v_mfma_f32_16x16x32_bf16 v[88:91], v[174:177], v[206:209], v[88:91]
	v_mfma_f32_16x16x32_bf16 v[88:91], v[170:173], v[202:205], v[88:91]
	v_mfma_f32_16x16x32_bf16 v[80:83], v[178:181], v[202:205], v[80:83]
	v_mfma_f32_16x16x32_bf16 v[80:83], v[182:185], v[206:209], v[80:83]
	v_mfma_f32_16x16x32_bf16 v[72:75], v[182:185], v[214:217], v[72:75]
	v_mfma_f32_16x16x32_bf16 v[72:75], v[178:181], v[210:213], v[72:75]
	s_setprio 0
	s_barrier
	s_add_u32 s26, s24, 0x8000
	s_addc_u32 s27, s25, 0
	s_add_i32 s68, s68, s29
	s_mov_b32 m0, s68
	ds_read_b128 v[186:189], v157 offset:49152
	ds_read_b128 v[190:193], v157 offset:50176
	ds_read_b128 v[194:197], v157 offset:51200
	ds_read_b128 v[198:201], v157 offset:52224
	ds_read_b128 v[202:205], v157 offset:53248
	ds_read_b128 v[206:209], v157 offset:54272
	ds_read_b128 v[210:213], v157 offset:55296
	ds_read_b128 v[214:217], v157 offset:56320
	global_load_lds_dwordx4 v140, s[26:27]
	s_add_i32 m0, s68, 0x2000
	s_add_u32 s24, s24, 0xc000
	s_addc_u32 s25, s25, 0
	global_load_lds_dwordx4 v136, s[26:27]
	s_add_i32 s26, s69, s29
	s_mov_b32 m0, s26
	s_nop 0
	global_load_lds_dwordx4 v140, s[24:25]
	s_add_i32 m0, s26, 0x2000
	s_nop 0
	global_load_lds_dwordx4 v136, s[24:25]
	s_mov_b32 m0, s37
	s_nop 0
	global_load_lds_dwordx4 v142, s[22:23]
	s_mov_b32 m0, s62
	s_nop 0
	global_load_lds_dwordx4 v138, s[22:23]
	s_waitcnt lgkmcnt(0)
	v_mfma_f32_16x16x32_bf16 v[68:71], v[150:153], v[186:189], v[68:71]
	v_mfma_f32_16x16x32_bf16 v[68:71], v[158:161], v[190:193], v[68:71]
	v_mfma_f32_16x16x32_bf16 v[64:67], v[166:169], v[190:193], v[64:67]
	v_mfma_f32_16x16x32_bf16 v[64:67], v[162:165], v[186:189], v[64:67]
	s_waitcnt vmcnt(8)
	s_barrier
	s_setprio 1
	v_mfma_f32_16x16x32_bf16 v[52:55], v[162:165], v[194:197], v[52:55]
	v_mfma_f32_16x16x32_bf16 v[52:55], v[166:169], v[198:201], v[52:55]
	v_mfma_f32_16x16x32_bf16 v[60:63], v[158:161], v[198:201], v[60:63]
	v_mfma_f32_16x16x32_bf16 v[60:63], v[150:153], v[194:197], v[60:63]
	v_mfma_f32_16x16x32_bf16 v[44:47], v[150:153], v[202:205], v[44:47]
	v_mfma_f32_16x16x32_bf16 v[44:47], v[158:161], v[206:209], v[44:47]
	v_mfma_f32_16x16x32_bf16 v[32:35], v[166:169], v[206:209], v[32:35]
	v_mfma_f32_16x16x32_bf16 v[32:35], v[162:165], v[202:205], v[32:35]
	v_mfma_f32_16x16x32_bf16 v[16:19], v[162:165], v[210:213], v[16:19]
	v_mfma_f32_16x16x32_bf16 v[16:19], v[166:169], v[214:217], v[16:19]
	v_mfma_f32_16x16x32_bf16 v[24:27], v[158:161], v[214:217], v[24:27]
	v_mfma_f32_16x16x32_bf16 v[24:27], v[150:153], v[210:213], v[24:27]
	v_mfma_f32_16x16x32_bf16 v[8:11], v[170:173], v[210:213], v[8:11]
	v_mfma_f32_16x16x32_bf16 v[8:11], v[174:177], v[214:217], v[8:11]
	v_mfma_f32_16x16x32_bf16 v[56:59], v[174:177], v[190:193], v[56:59]
	v_mfma_f32_16x16x32_bf16 v[56:59], v[170:173], v[186:189], v[56:59]
	v_mfma_f32_16x16x32_bf16 v[48:51], v[178:181], v[186:189], v[48:51]
	v_mfma_f32_16x16x32_bf16 v[48:51], v[182:185], v[190:193], v[48:51]
	v_mfma_f32_16x16x32_bf16 v[28:31], v[182:185], v[198:201], v[28:31]
	v_mfma_f32_16x16x32_bf16 v[28:31], v[178:181], v[194:197], v[28:31]
	v_mfma_f32_16x16x32_bf16 v[40:43], v[170:173], v[194:197], v[40:43]
	v_mfma_f32_16x16x32_bf16 v[40:43], v[174:177], v[198:201], v[40:43]
	v_mfma_f32_16x16x32_bf16 v[20:23], v[174:177], v[206:209], v[20:23]
	v_mfma_f32_16x16x32_bf16 v[20:23], v[170:173], v[202:205], v[20:23]
	v_mfma_f32_16x16x32_bf16 v[12:15], v[178:181], v[202:205], v[12:15]
	v_mfma_f32_16x16x32_bf16 v[12:15], v[182:185], v[206:209], v[12:15]
	v_mfma_f32_16x16x32_bf16 v[4:7], v[182:185], v[214:217], v[4:7]
	v_mfma_f32_16x16x32_bf16 v[4:7], v[178:181], v[210:213], v[4:7]
	s_setprio 0
	s_barrier
	s_add_i32 s13, s13, 2
	s_add_u32 s20, s20, 0x10000
	s_addc_u32 s21, s21, 0
	s_add_u32 s70, s70, 0x10000
	s_addc_u32 s71, s71, 0
	s_cmp_gt_u32 s13, 29
	s_cbranch_scc0 .LBB0_916
	s_and_b64 vcc, exec, s[6:7]
	s_cbranch_vccz .LBB0_919
	s_barrier

; #define PG8_STAGE(bufoff, gbase, voff) do { _Pragma("unroll") for (int _i = 0; _i < 2; ++_i) \
;         __builtin_amdgcn_global_load_lds((const unsigned*)((const char*)(gbase) + (voff)[_i]), (PG8_LAS unsigned*)(lds + (bufoff) + ldsw + _i * 8192), 16, 0, 0); } while (0)
; #define PG8_LDA(dst, b, h) do { _Pragma("unroll") for (int m = 0; m < 4; ++m) _Pragma("unroll") for (int k = 0; k < 2; ++k) dst[m][k] = *(const PG8_LAS bf16x8*)(lds + PG8_SA(b, h) + aoff + m * 2048 + k * 1024); } while (0)
; #define PG8_LDB(dst, b, h) do { _Pragma("unroll") for (int n = 0; n < 2; ++n) _Pragma("unroll") for (int k = 0; k < 2; ++k) dst[n][k] = *(const PG8_LAS bf16x8*)(lds + PG8_SB(b, h) + boff + n * 2048 + k * 1024); } while (0)
; #define PG8_WAIT_V(n) asm volatile("s_waitcnt vmcnt(" #n ")" ::: "memory")
; #define PG8_WAIT_L(n) asm volatile("s_waitcnt lgkmcnt(" #n ")" ::: "memory")
; #define PG8_BAR __builtin_amdgcn_s_barrier()
; #define PG8_SCHED __builtin_amdgcn_sched_barrier(0)
; template <class Epi, class Sched, bool ALIGN_EPI = false, bool SP2 = false, bool ABLK = false, bool BBLK = false>
; __device__ __forceinline__ void gemm_phase(PG8_LAS unsigned char* lds, const Gemm g, const Sched& S, const Epi& E) {
;     ...
;         const char* nA = has_next ? (const char*)g.A + (size_t)nxt.pm * tstep : cA; const char* nB = has_next ? (const char*)g.Bt + (size_t)nxt.pn * tstep : cB;
;         for (int t = 0; t < nt; t += 2) {
;             const bool last = (t == nt - 2);
;             const char* a1 = cA + (size_t)(t + 1) * kstepA;
;             const char* a2 = last ? nA : cA + (size_t)(t + 2) * kstepA; const char* b2 = last ? nB : cB + (size_t)(t + 2) * kstepB;
;             const char* a3 = a2 + kstepA; const char* b3 = b2 + kstepB;
;             if (last && has_next) S.a_ready(nxt);
;             if constexpr (SP2) {
;             PG8_LDB(B0, 0, 0); PG8_LDB(B1, 0, 1); PG8_SCHED; PG8_LDA(At, 0, 0); PG8_STAGE(PG8_SA(1, 1), a1 + hstepA, voffA);
;             PG8_WAIT_V(8); PG8_WAIT_L(0); PG8_BAR; PG8_MMA(0, 0, At, B0); PG8_MMA(0, 1, At, B1); PG8_BAR; PG8_SCHED;
;             PG8_LDA(At, 0, 1); PG8_STAGE(PG8_SB(0, 0), b2, voffB); PG8_STAGE(PG8_SB(0, 1), b2 + hstepB, voffB); PG8_STAGE(PG8_SA(0, 0), a2, voffA);
;             PG8_WAIT_V(8); PG8_WAIT_L(0); PG8_BAR; PG8_MMA(1, 0, At, B0); PG8_MMA(1, 1, At, B1); PG8_BAR; PG8_SCHED;
.LBB0_2110:
	s_ashr_i32 s17, s16, 31
	s_lshl_b64 s[12:13], s[16:17], 20
	s_add_u32 s18, s72, s12
	s_addc_u32 s19, s73, s13
	s_and_b64 s[12:13], s[4:5], exec
	s_cselect_b32 s12, s19, s23
	s_cselect_b32 s17, s18, s22
	s_ashr_i32 s11, s10, 31
	s_lshl_b64 s[20:21], s[10:11], 20
	v_readlane_b32 s26, v254, 3
	v_readlane_b32 s27, v254, 4
	s_add_u32 s20, s26, s20
	s_addc_u32 s21, s27, s21
	s_and_b64 s[26:27], s[4:5], exec
	s_cselect_b32 s11, s21, s25
	s_cselect_b32 s77, s20, s24
	s_add_u32 s22, s22, 0xc000
	s_addc_u32 s23, s23, 0
	s_add_u32 s82, s24, 0x10000
	s_addc_u32 vcc_lo, s25, 0
	s_mov_b32 s13, -2
	s_add_u32 s24, s22, 0x4000
	s_addc_u32 s25, s23, 0
	s_cmp_eq_u32 s13, 28
	s_cselect_b32 s28, s17, s24
	s_cselect_b32 s29, s12, s25
	s_cselect_b32 s26, s77, s82
	s_cselect_b32 s27, s11, vcc_lo
	s_add_u32 s24, s28, 0x8000
	s_addc_u32 s25, s29, 0
	s_add_i32 s68, 0, 0x10000
	v_add_u32_e32 v151, s68, v148
	s_add_i32 s88, 0, 0x14000
	ds_read_b128 v[36:39], v151
	ds_read_b128 v[152:155], v151 offset:1024
	ds_read_b128 v[156:159], v151 offset:2048
	ds_read_b128 v[160:163], v151 offset:3072
	v_add_u32_e32 v151, s88, v148
	ds_read_b128 v[164:167], v151
	ds_read_b128 v[168:171], v151 offset:1024
	ds_read_b128 v[172:175], v151 offset:2048
	ds_read_b128 v[176:179], v151 offset:3072
	s_add_i32 m0, s9, 0xc000
	ds_read_b128 v[180:183], v150
	ds_read_b128 v[184:187], v150 offset:1024
	ds_read_b128 v[188:191], v150 offset:2048
	ds_read_b128 v[192:195], v150 offset:3072
	ds_read_b128 v[196:199], v150 offset:4096
	ds_read_b128 v[200:203], v150 offset:5120
	ds_read_b128 v[204:207], v150 offset:6144
	ds_read_b128 v[208:211], v150 offset:7168
	global_load_lds_dwordx4 v144, s[22:23]
	s_add_i32 m0, s9, 0xe000
	s_nop 0
	global_load_lds_dwordx4 v146, s[22:23]
	s_waitcnt lgkmcnt(0)
	v_mfma_f32_16x16x32_bf16 v[132:135], v[36:39], v[180:183], 0
	v_mfma_f32_16x16x32_bf16 v[132:135], v[152:155], v[184:187], v[132:135]
	v_mfma_f32_16x16x32_bf16 v[128:131], v[160:163], v[184:187], 0
	v_mfma_f32_16x16x32_bf16 v[128:131], v[156:159], v[180:183], v[128:131]
	s_waitcnt vmcnt(8)
	s_barrier
	s_setprio 1
	v_mfma_f32_16x16x32_bf16 v[120:123], v[156:159], v[188:191], 0
	v_mfma_f32_16x16x32_bf16 v[120:123], v[160:163], v[192:195], v[120:123]
	v_mfma_f32_16x16x32_bf16 v[124:127], v[152:155], v[192:195], 0
	v_mfma_f32_16x16x32_bf16 v[124:127], v[36:39], v[188:191], v[124:127]
	v_mfma_f32_16x16x32_bf16 v[108:111], v[36:39], v[196:199], 0
	v_mfma_f32_16x16x32_bf16 v[108:111], v[152:155], v[200:203], v[108:111]
	v_mfma_f32_16x16x32_bf16 v[104:107], v[160:163], v[200:203], 0
	v_mfma_f32_16x16x32_bf16 v[104:107], v[156:159], v[196:199], v[104:107]
	v_mfma_f32_16x16x32_bf16 v[88:91], v[156:159], v[204:207], 0
	v_mfma_f32_16x16x32_bf16 v[88:91], v[160:163], v[208:211], v[88:91]
	v_mfma_f32_16x16x32_bf16 v[92:95], v[152:155], v[208:211], 0
	v_mfma_f32_16x16x32_bf16 v[92:95], v[36:39], v[204:207], v[92:95]
	v_mfma_f32_16x16x32_bf16 v[76:79], v[164:167], v[204:207], 0
	v_mfma_f32_16x16x32_bf16 v[76:79], v[168:171], v[208:211], v[76:79]
	v_mfma_f32_16x16x32_bf16 v[116:119], v[168:171], v[184:187], 0
	v_mfma_f32_16x16x32_bf16 v[116:119], v[164:167], v[180:183], v[116:119]
	v_mfma_f32_16x16x32_bf16 v[112:115], v[172:175], v[180:183], 0
	v_mfma_f32_16x16x32_bf16 v[112:115], v[176:179], v[184:187], v[112:115]
	v_mfma_f32_16x16x32_bf16 v[96:99], v[176:179], v[192:195], 0
	v_mfma_f32_16x16x32_bf16 v[96:99], v[172:175], v[188:191], v[96:99]
	v_mfma_f32_16x16x32_bf16 v[100:103], v[164:167], v[188:191], 0
	v_mfma_f32_16x16x32_bf16 v[100:103], v[168:171], v[192:195], v[100:103]
	v_mfma_f32_16x16x32_bf16 v[84:87], v[168:171], v[200:203], 0
	v_mfma_f32_16x16x32_bf16 v[84:87], v[164:167], v[196:199], v[84:87]
	v_mfma_f32_16x16x32_bf16 v[80:83], v[172:175], v[196:199], 0
	v_mfma_f32_16x16x32_bf16 v[80:83], v[176:179], v[200:203], v[80:83]
	v_mfma_f32_16x16x32_bf16 v[72:75], v[176:179], v[208:211], 0
	v_mfma_f32_16x16x32_bf16 v[72:75], v[172:175], v[204:207], v[72:75]
	s_setprio 0
	s_barrier
	s_add_i32 s68, s68, s34
	s_mov_b32 m0, s68
	ds_read_b128 v[180:183], v150 offset:16384
	ds_read_b128 v[184:187], v150 offset:17408
	ds_read_b128 v[188:191], v150 offset:18432
	ds_read_b128 v[192:195], v150 offset:19456
	ds_read_b128 v[196:199], v150 offset:20480
	ds_read_b128 v[200:203], v150 offset:21504
	ds_read_b128 v[204:207], v150 offset:22528
	ds_read_b128 v[208:211], v150 offset:23552
	global_load_lds_dwordx4 v138, s[26:27]
	s_add_i32 m0, s68, 0x2000
	s_add_u32 s68, s26, 0x4000
	s_addc_u32 s69, s27, 0
	s_add_i32 s88, s88, s34
	global_load_lds_dwordx4 v142, s[26:27]
	s_mov_b32 m0, s88
	s_nop 0
	global_load_lds_dwordx4 v138, s[68:69]
	s_add_i32 m0, s88, 0x2000
	s_nop 0
	global_load_lds_dwordx4 v142, s[68:69]
	s_mov_b32 m0, s9
	s_nop 0
	global_load_lds_dwordx4 v136, s[28:29]
	s_mov_b32 m0, s35
	s_nop 0
	global_load_lds_dwordx4 v140, s[28:29]
	s_waitcnt lgkmcnt(0)
	v_mfma_f32_16x16x32_bf16 v[68:71], v[36:39], v[180:183], 0
	v_mfma_f32_16x16x32_bf16 v[68:71], v[152:155], v[184:187], v[68:71]
	v_mfma_f32_16x16x32_bf16 v[64:67], v[160:163], v[184:187], 0
	v_mfma_f32_16x16x32_bf16 v[64:67], v[156:159], v[180:183], v[64:67]
	s_waitcnt vmcnt(8)
	s_barrier
; #define PG8_STAGE(bufoff, gbase, voff) do { _Pragma("unroll") for (int _i = 0; _i < 2; ++_i) \
;         __builtin_amdgcn_global_load_lds((const unsigned*)((const char*)(gbase) + (voff)[_i]), (PG8_LAS unsigned*)(lds + (bufoff) + ldsw + _i * 8192), 16, 0, 0); } while (0)
; #define PG8_LDA(dst, b, h) do { _Pragma("unroll") for (int m = 0; m < 4; ++m) _Pragma("unroll") for (int k = 0; k < 2; ++k) dst[m][k] = *(const PG8_LAS bf16x8*)(lds + PG8_SA(b, h) + aoff + m * 2048 + k * 1024); } while (0)
; #define PG8_LDB(dst, b, h) do { _Pragma("unroll") for (int n = 0; n < 2; ++n) _Pragma("unroll") for (int k = 0; k < 2; ++k) dst[n][k] = *(const PG8_LAS bf16x8*)(lds + PG8_SB(b, h) + boff + n * 2048 + k * 1024); } while (0)
; #define PG8_MMA(ai, bj, At, Bt) do { __builtin_amdgcn_s_setprio(1); _Pragma("unroll") for (int m = 0; m < 4; ++m) _Pragma("unroll") for (int n = 0; n < 2; ++n) _Pragma("unroll") for (int k = 0; k < 2; ++k) \
;         acc[ai][bj][m][n] = __builtin_amdgcn_mfma_f32_16x16x32_bf16(Bt[n][k], At[m][k], acc[ai][bj][m][n], 0, 0, 0); __builtin_amdgcn_s_setprio(0); } while (0)
; #define PG8_WAIT_V(n) asm volatile("s_waitcnt vmcnt(" #n ")" ::: "memory")
; #define PG8_WAIT_L(n) asm volatile("s_waitcnt lgkmcnt(" #n ")" ::: "memory")
; #define PG8_BAR __builtin_amdgcn_s_barrier()
; #define PG8_SCHED __builtin_amdgcn_sched_barrier(0)
; template <class Epi, class Sched, bool ALIGN_EPI = false, bool SP2 = false, bool ABLK = false, bool BBLK = false>
; __device__ __forceinline__ void gemm_phase(PG8_LAS unsigned char* lds, const Gemm g, const Sched& S, const Epi& E) {
;     ...
;             PG8_WAIT_V(8); PG8_WAIT_L(0); PG8_BAR; PG8_MMA(1, 0, At, B0); PG8_MMA(1, 1, At, B1); PG8_BAR; PG8_SCHED;
;             PG8_LDB(B0, 1, 0); PG8_LDB(B1, 1, 1); PG8_SCHED; PG8_LDA(At, 1, 0); PG8_STAGE(PG8_SA(0, 1), a2 + hstepA, voffA);
;             PG8_WAIT_V(8); PG8_WAIT_L(0); PG8_BAR; PG8_MMA(0, 0, At, B0); PG8_MMA(0, 1, At, B1); PG8_BAR; PG8_SCHED;
	s_setprio 1
	v_mfma_f32_16x16x32_bf16 v[56:59], v[156:159], v[188:191], 0
	v_mfma_f32_16x16x32_bf16 v[56:59], v[160:163], v[192:195], v[56:59]
	v_mfma_f32_16x16x32_bf16 v[60:63], v[152:155], v[192:195], 0
	v_mfma_f32_16x16x32_bf16 v[60:63], v[36:39], v[188:191], v[60:63]
	v_mfma_f32_16x16x32_bf16 v[44:47], v[36:39], v[196:199], 0
	v_mfma_f32_16x16x32_bf16 v[44:47], v[152:155], v[200:203], v[44:47]
	v_mfma_f32_16x16x32_bf16 v[40:43], v[160:163], v[200:203], 0
	v_mfma_f32_16x16x32_bf16 v[40:43], v[156:159], v[196:199], v[40:43]
	v_mfma_f32_16x16x32_bf16 v[20:23], v[156:159], v[204:207], 0
	v_mfma_f32_16x16x32_bf16 v[20:23], v[160:163], v[208:211], v[20:23]
	v_mfma_f32_16x16x32_bf16 v[24:27], v[152:155], v[208:211], 0
	v_mfma_f32_16x16x32_bf16 v[24:27], v[36:39], v[204:207], v[24:27]
	v_mfma_f32_16x16x32_bf16 v[48:51], v[172:175], v[180:183], 0
	v_mfma_f32_16x16x32_bf16 v[32:35], v[164:167], v[188:191], 0
	v_mfma_f32_16x16x32_bf16 v[28:31], v[172:175], v[188:191], 0
	v_mfma_f32_16x16x32_bf16 v[16:19], v[164:167], v[196:199], 0
	v_mfma_f32_16x16x32_bf16 v[12:15], v[172:175], v[196:199], 0
	v_mfma_f32_16x16x32_bf16 v[8:11], v[164:167], v[204:207], 0
	v_mfma_f32_16x16x32_bf16 v[4:7], v[172:175], v[204:207], 0
	v_mfma_f32_16x16x32_bf16 v[36:39], v[164:167], v[180:183], 0
	v_mfma_f32_16x16x32_bf16 v[48:51], v[176:179], v[184:187], v[48:51]
	v_mfma_f32_16x16x32_bf16 v[32:35], v[168:171], v[192:195], v[32:35]
	v_mfma_f32_16x16x32_bf16 v[28:31], v[176:179], v[192:195], v[28:31]
	v_mfma_f32_16x16x32_bf16 v[16:19], v[168:171], v[200:203], v[16:19]
	v_mfma_f32_16x16x32_bf16 v[12:15], v[176:179], v[200:203], v[12:15]
	v_mfma_f32_16x16x32_bf16 v[8:11], v[168:171], v[208:211], v[8:11]
	v_mfma_f32_16x16x32_bf16 v[4:7], v[176:179], v[208:211], v[4:7]
	v_mfma_f32_16x16x32_bf16 v[36:39], v[168:171], v[184:187], v[36:39]
	s_setprio 0
	s_barrier
	s_add_i32 s68, 0, 0x18000
	v_add_u32_e32 v151, s68, v148
	s_add_i32 s69, 0, 0x1c000
	ds_read_b128 v[52:55], v151
	ds_read_b128 v[152:155], v151 offset:1024
	ds_read_b128 v[156:159], v151 offset:2048
	ds_read_b128 v[160:163], v151 offset:3072
	v_add_u32_e32 v151, s69, v148
	ds_read_b128 v[164:167], v151
	ds_read_b128 v[168:171], v151 offset:1024
	ds_read_b128 v[172:175], v151 offset:2048
	ds_read_b128 v[176:179], v151 offset:3072
	s_add_u32 s28, s28, 0x4000
	s_addc_u32 s29, s29, 0
	s_mov_b32 m0, s36
	ds_read_b128 v[180:183], v150 offset:32768
	ds_read_b128 v[184:187], v150 offset:33792
	ds_read_b128 v[188:191], v150 offset:34816
	ds_read_b128 v[192:195], v150 offset:35840
	ds_read_b128 v[196:199], v150 offset:36864
	ds_read_b128 v[200:203], v150 offset:37888
	ds_read_b128 v[204:207], v150 offset:38912
	ds_read_b128 v[208:211], v150 offset:39936
	global_load_lds_dwordx4 v136, s[28:29]
	s_mov_b32 m0, s37
	s_nop 0
	global_load_lds_dwordx4 v140, s[28:29]
	s_waitcnt lgkmcnt(0)
	v_mfma_f32_16x16x32_bf16 v[132:135], v[52:55], v[180:183], v[132:135]
	v_mfma_f32_16x16x32_bf16 v[132:135], v[152:155], v[184:187], v[132:135]
	v_mfma_f32_16x16x32_bf16 v[128:131], v[160:163], v[184:187], v[128:131]
	v_mfma_f32_16x16x32_bf16 v[128:131], v[156:159], v[180:183], v[128:131]
	s_waitcnt vmcnt(8)
	s_barrier
	s_setprio 1
	v_mfma_f32_16x16x32_bf16 v[120:123], v[156:159], v[188:191], v[120:123]
	v_mfma_f32_16x16x32_bf16 v[120:123], v[160:163], v[192:195], v[120:123]
	v_mfma_f32_16x16x32_bf16 v[124:127], v[152:155], v[192:195], v[124:127]
	v_mfma_f32_16x16x32_bf16 v[124:127], v[52:55], v[188:191], v[124:127]
	v_mfma_f32_16x16x32_bf16 v[108:111], v[52:55], v[196:199], v[108:111]
	v_mfma_f32_16x16x32_bf16 v[108:111], v[152:155], v[200:203], v[108:111]
	v_mfma_f32_16x16x32_bf16 v[104:107], v[160:163], v[200:203], v[104:107]
	v_mfma_f32_16x16x32_bf16 v[104:107], v[156:159], v[196:199], v[104:107]
	v_mfma_f32_16x16x32_bf16 v[88:91], v[156:159], v[204:207], v[88:91]
	v_mfma_f32_16x16x32_bf16 v[88:91], v[160:163], v[208:211], v[88:91]
	v_mfma_f32_16x16x32_bf16 v[92:95], v[152:155], v[208:211], v[92:95]
	v_mfma_f32_16x16x32_bf16 v[92:95], v[52:55], v[204:207], v[92:95]
	v_mfma_f32_16x16x32_bf16 v[76:79], v[164:167], v[204:207], v[76:79]
	v_mfma_f32_16x16x32_bf16 v[76:79], v[168:171], v[208:211], v[76:79]
	v_mfma_f32_16x16x32_bf16 v[116:119], v[168:171], v[184:187], v[116:119]
	v_mfma_f32_16x16x32_bf16 v[116:119], v[164:167], v[180:183], v[116:119]
	v_mfma_f32_16x16x32_bf16 v[112:115], v[172:175], v[180:183], v[112:115]
	v_mfma_f32_16x16x32_bf16 v[112:115], v[176:179], v[184:187], v[112:115]
	v_mfma_f32_16x16x32_bf16 v[96:99], v[176:179], v[192:195], v[96:99]
	v_mfma_f32_16x16x32_bf16 v[96:99], v[172:175], v[188:191], v[96:99]
	v_mfma_f32_16x16x32_bf16 v[100:103], v[164:167], v[188:191], v[100:103]
	v_mfma_f32_16x16x32_bf16 v[100:103], v[168:171], v[192:195], v[100:103]
	v_mfma_f32_16x16x32_bf16 v[84:87], v[168:171], v[200:203], v[84:87]
	v_mfma_f32_16x16x32_bf16 v[84:87], v[164:167], v[196:199], v[84:87]
	v_mfma_f32_16x16x32_bf16 v[80:83], v[172:175], v[196:199], v[80:83]
	v_mfma_f32_16x16x32_bf16 v[80:83], v[176:179], v[200:203], v[80:83]
	v_mfma_f32_16x16x32_bf16 v[72:75], v[176:179], v[208:211], v[72:75]
	v_mfma_f32_16x16x32_bf16 v[72:75], v[172:175], v[204:207], v[72:75]
	s_setprio 0
	s_barrier
; #define PG8_STAGE(bufoff, gbase, voff) do { _Pragma("unroll") for (int _i = 0; _i < 2; ++_i) \
;         __builtin_amdgcn_global_load_lds((const unsigned*)((const char*)(gbase) + (voff)[_i]), (PG8_LAS unsigned*)(lds + (bufoff) + ldsw + _i * 8192), 16, 0, 0); } while (0)
; #define PG8_LDA(dst, b, h) do { _Pragma("unroll") for (int m = 0; m < 4; ++m) _Pragma("unroll") for (int k = 0; k < 2; ++k) dst[m][k] = *(const PG8_LAS bf16x8*)(lds + PG8_SA(b, h) + aoff + m * 2048 + k * 1024); } while (0)
; #define PG8_LDB(dst, b, h) do { _Pragma("unroll") for (int n = 0; n < 2; ++n) _Pragma("unroll") for (int k = 0; k < 2; ++k) dst[n][k] = *(const PG8_LAS bf16x8*)(lds + PG8_SB(b, h) + boff + n * 2048 + k * 1024); } while (0)
; #define PG8_WAIT_V(n) asm volatile("s_waitcnt vmcnt(" #n ")" ::: "memory")
; #define PG8_WAIT_L(n) asm volatile("s_waitcnt lgkmcnt(" #n ")" ::: "memory")
; #define PG8_BAR __builtin_amdgcn_s_barrier()
; template <class Epi, class Sched, bool ALIGN_EPI = false, bool SP2 = false, bool ABLK = false, bool BBLK = false>
; __device__ __forceinline__ void gemm_phase(PG8_LAS unsigned char* lds, const Gemm g, const Sched& S, const Epi& E) {
;     ...
;         for (int t = 0; t < nt; t += 2) {
;             const bool last = (t == nt - 2);
;             const char* a1 = cA + (size_t)(t + 1) * kstepA;
;             const char* a2 = last ? nA : cA + (size_t)(t + 2) * kstepA; const char* b2 = last ? nB : cB + (size_t)(t + 2) * kstepB;
;             const char* a3 = a2 + kstepA; const char* b3 = b2 + kstepB;
;             if (last && has_next) S.a_ready(nxt);
;             if constexpr (SP2) {
;             PG8_LDB(B0, 0, 0); PG8_LDB(B1, 0, 1); PG8_SCHED; PG8_LDA(At, 0, 0); PG8_STAGE(PG8_SA(1, 1), a1 + hstepA, voffA);
;             PG8_WAIT_V(8); PG8_WAIT_L(0); PG8_BAR; PG8_MMA(0, 0, At, B0); PG8_MMA(0, 1, At, B1); PG8_BAR; PG8_SCHED;
;             PG8_LDA(At, 0, 1); PG8_STAGE(PG8_SB(0, 0), b2, voffB); PG8_STAGE(PG8_SB(0, 1), b2 + hstepB, voffB); PG8_STAGE(PG8_SA(0, 0), a2, voffA);
;             PG8_WAIT_V(8); PG8_WAIT_L(0); PG8_BAR; PG8_MMA(1, 0, At, B0); PG8_MMA(1, 1, At, B1); PG8_BAR; PG8_SCHED;
;     ...
;             PG8_LDA(At, 1, 1); PG8_STAGE(PG8_SB(1, 0), b3, voffB); PG8_STAGE(PG8_SB(1, 1), b3 + hstepB, voffB); PG8_STAGE(PG8_SA(1, 0), a3, voffA);
;             PG8_WAIT_V(8); PG8_WAIT_L(0); PG8_BAR; PG8_MMA(1, 0, At, B0); PG8_MMA(1, 1, At, B1); PG8_BAR; PG8_SCHED;
	s_add_u32 s28, s26, 0x8000
	s_addc_u32 s29, s27, 0
	s_add_i32 s68, s68, s34
	s_mov_b32 m0, s68
	ds_read_b128 v[180:183], v150 offset:49152
	ds_read_b128 v[184:187], v150 offset:50176
	ds_read_b128 v[188:191], v150 offset:51200
	ds_read_b128 v[192:195], v150 offset:52224
	ds_read_b128 v[196:199], v150 offset:53248
	ds_read_b128 v[200:203], v150 offset:54272
	ds_read_b128 v[204:207], v150 offset:55296
	ds_read_b128 v[208:211], v150 offset:56320
	global_load_lds_dwordx4 v138, s[28:29]
	s_add_i32 m0, s68, 0x2000
	s_add_u32 s26, s26, 0xc000
	s_addc_u32 s27, s27, 0
	global_load_lds_dwordx4 v142, s[28:29]
	s_add_i32 s28, s69, s34
	s_mov_b32 m0, s28
	s_nop 0
	global_load_lds_dwordx4 v138, s[26:27]
	s_add_i32 m0, s28, 0x2000
	s_nop 0
	global_load_lds_dwordx4 v142, s[26:27]
	s_mov_b32 m0, s64
	s_nop 0
	global_load_lds_dwordx4 v136, s[24:25]
	s_mov_b32 m0, s65
	s_nop 0
	global_load_lds_dwordx4 v140, s[24:25]
	s_waitcnt lgkmcnt(0)
	v_mfma_f32_16x16x32_bf16 v[68:71], v[52:55], v[180:183], v[68:71]
	v_mfma_f32_16x16x32_bf16 v[68:71], v[152:155], v[184:187], v[68:71]
	v_mfma_f32_16x16x32_bf16 v[64:67], v[160:163], v[184:187], v[64:67]
	v_mfma_f32_16x16x32_bf16 v[64:67], v[156:159], v[180:183], v[64:67]
	s_waitcnt vmcnt(8)
	s_barrier
	s_setprio 1
	v_mfma_f32_16x16x32_bf16 v[56:59], v[156:159], v[188:191], v[56:59]
	v_mfma_f32_16x16x32_bf16 v[56:59], v[160:163], v[192:195], v[56:59]
	v_mfma_f32_16x16x32_bf16 v[60:63], v[152:155], v[192:195], v[60:63]
	v_mfma_f32_16x16x32_bf16 v[60:63], v[52:55], v[188:191], v[60:63]
	v_mfma_f32_16x16x32_bf16 v[44:47], v[52:55], v[196:199], v[44:47]
	v_mfma_f32_16x16x32_bf16 v[44:47], v[152:155], v[200:203], v[44:47]
	v_mfma_f32_16x16x32_bf16 v[40:43], v[160:163], v[200:203], v[40:43]
	v_mfma_f32_16x16x32_bf16 v[40:43], v[156:159], v[196:199], v[40:43]
	v_mfma_f32_16x16x32_bf16 v[20:23], v[156:159], v[204:207], v[20:23]
	v_mfma_f32_16x16x32_bf16 v[20:23], v[160:163], v[208:211], v[20:23]
	v_mfma_f32_16x16x32_bf16 v[24:27], v[152:155], v[208:211], v[24:27]
	v_mfma_f32_16x16x32_bf16 v[24:27], v[52:55], v[204:207], v[24:27]
	v_mfma_f32_16x16x32_bf16 v[36:39], v[164:167], v[180:183], v[36:39]
	v_mfma_f32_16x16x32_bf16 v[52:55], v[168:171], v[184:187], v[36:39]
	v_mfma_f32_16x16x32_bf16 v[36:39], v[172:175], v[180:183], v[48:51]
	v_mfma_f32_16x16x32_bf16 v[32:35], v[164:167], v[188:191], v[32:35]
	v_mfma_f32_16x16x32_bf16 v[28:31], v[172:175], v[188:191], v[28:31]
	v_mfma_f32_16x16x32_bf16 v[16:19], v[164:167], v[196:199], v[16:19]
	v_mfma_f32_16x16x32_bf16 v[12:15], v[172:175], v[196:199], v[12:15]
	v_mfma_f32_16x16x32_bf16 v[8:11], v[164:167], v[204:207], v[8:11]
	v_mfma_f32_16x16x32_bf16 v[4:7], v[172:175], v[204:207], v[4:7]
	v_mfma_f32_16x16x32_bf16 v[48:51], v[176:179], v[184:187], v[36:39]
	v_mfma_f32_16x16x32_bf16 v[32:35], v[168:171], v[192:195], v[32:35]
	v_mfma_f32_16x16x32_bf16 v[28:31], v[176:179], v[192:195], v[28:31]
	v_mfma_f32_16x16x32_bf16 v[16:19], v[168:171], v[200:203], v[16:19]
	v_mfma_f32_16x16x32_bf16 v[12:15], v[176:179], v[200:203], v[12:15]
	v_mfma_f32_16x16x32_bf16 v[8:11], v[168:171], v[208:211], v[8:11]
	v_mfma_f32_16x16x32_bf16 v[4:7], v[176:179], v[208:211], v[4:7]
	s_setprio 0
	s_barrier
	s_add_i32 s13, s13, 2
	s_add_u32 s22, s22, 0x10000
	s_addc_u32 s23, s23, 0
	s_add_u32 s82, s82, 0x10000
	s_addc_u32 vcc_lo, vcc_lo, 0
	s_cmp_gt_u32 s13, 29
.LBB0_2111:
	s_add_u32 s24, s22, 0x4000
	s_addc_u32 s25, s23, 0
	s_cmp_eq_u32 s13, 28
	s_cselect_b32 s28, s17, s24
	s_cselect_b32 s29, s12, s25
	s_cselect_b32 s26, s77, s82
	s_cselect_b32 s27, s11, vcc_lo
	s_add_u32 s24, s28, 0x8000
	s_addc_u32 s25, s29, 0
	s_add_i32 s68, 0, 0x10000
	v_add_u32_e32 v151, s68, v148
	s_add_i32 s88, 0, 0x14000
	ds_read_b128 v[36:39], v151
	ds_read_b128 v[152:155], v151 offset:1024
	ds_read_b128 v[156:159], v151 offset:2048
	ds_read_b128 v[160:163], v151 offset:3072
	v_add_u32_e32 v151, s88, v148
	ds_read_b128 v[164:167], v151
	ds_read_b128 v[168:171], v151 offset:1024
	ds_read_b128 v[172:175], v151 offset:2048
	ds_read_b128 v[176:179], v151 offset:3072
	s_add_i32 m0, s9, 0xc000
	ds_read_b128 v[180:183], v150
	ds_read_b128 v[184:187], v150 offset:1024
	ds_read_b128 v[188:191], v150 offset:2048
	ds_read_b128 v[192:195], v150 offset:3072
	ds_read_b128 v[196:199], v150 offset:4096
	ds_read_b128 v[200:203], v150 offset:5120
	ds_read_b128 v[204:207], v150 offset:6144
	ds_read_b128 v[208:211], v150 offset:7168
	global_load_lds_dwordx4 v144, s[22:23]
	s_add_i32 m0, s9, 0xe000
	s_nop 0
	global_load_lds_dwordx4 v146, s[22:23]
	s_waitcnt lgkmcnt(0)
	v_mfma_f32_16x16x32_bf16 v[132:135], v[36:39], v[180:183], v[132:135]
	v_mfma_f32_16x16x32_bf16 v[132:135], v[152:155], v[184:187], v[132:135]
	v_mfma_f32_16x16x32_bf16 v[128:131], v[160:163], v[184:187], v[128:131]
	v_mfma_f32_16x16x32_bf16 v[128:131], v[156:159], v[180:183], v[128:131]
	s_waitcnt vmcnt(8)
	s_barrier
; #define PG8_STAGE(bufoff, gbase, voff) do { _Pragma("unroll") for (int _i = 0; _i < 2; ++_i) \
;         __builtin_amdgcn_global_load_lds((const unsigned*)((const char*)(gbase) + (voff)[_i]), (PG8_LAS unsigned*)(lds + (bufoff) + ldsw + _i * 8192), 16, 0, 0); } while (0)
; #define PG8_LDA(dst, b, h) do { _Pragma("unroll") for (int m = 0; m < 4; ++m) _Pragma("unroll") for (int k = 0; k < 2; ++k) dst[m][k] = *(const PG8_LAS bf16x8*)(lds + PG8_SA(b, h) + aoff + m * 2048 + k * 1024); } while (0)
; #define PG8_MMA(ai, bj, At, Bt) do { __builtin_amdgcn_s_setprio(1); _Pragma("unroll") for (int m = 0; m < 4; ++m) _Pragma("unroll") for (int n = 0; n < 2; ++n) _Pragma("unroll") for (int k = 0; k < 2; ++k) \
;         acc[ai][bj][m][n] = __builtin_amdgcn_mfma_f32_16x16x32_bf16(Bt[n][k], At[m][k], acc[ai][bj][m][n], 0, 0, 0); __builtin_amdgcn_s_setprio(0); } while (0)
; #define PG8_WAIT_V(n) asm volatile("s_waitcnt vmcnt(" #n ")" ::: "memory")
; #define PG8_WAIT_L(n) asm volatile("s_waitcnt lgkmcnt(" #n ")" ::: "memory")
; #define PG8_BAR __builtin_amdgcn_s_barrier()
; #define PG8_SCHED __builtin_amdgcn_sched_barrier(0)
; template <class Epi, class Sched, bool ALIGN_EPI = false, bool SP2 = false, bool ABLK = false, bool BBLK = false>
; __device__ __forceinline__ void gemm_phase(PG8_LAS unsigned char* lds, const Gemm g, const Sched& S, const Epi& E) {
;     ...
;             PG8_WAIT_V(8); PG8_WAIT_L(0); PG8_BAR; PG8_MMA(0, 0, At, B0); PG8_MMA(0, 1, At, B1); PG8_BAR; PG8_SCHED;
;             PG8_LDA(At, 0, 1); PG8_STAGE(PG8_SB(0, 0), b2, voffB); PG8_STAGE(PG8_SB(0, 1), b2 + hstepB, voffB); PG8_STAGE(PG8_SA(0, 0), a2, voffA);
;             PG8_WAIT_V(8); PG8_WAIT_L(0); PG8_BAR; PG8_MMA(1, 0, At, B0); PG8_MMA(1, 1, At, B1); PG8_BAR; PG8_SCHED;
	s_setprio 1
	v_mfma_f32_16x16x32_bf16 v[120:123], v[156:159], v[188:191], v[120:123]
	v_mfma_f32_16x16x32_bf16 v[120:123], v[160:163], v[192:195], v[120:123]
	v_mfma_f32_16x16x32_bf16 v[124:127], v[152:155], v[192:195], v[124:127]
	v_mfma_f32_16x16x32_bf16 v[124:127], v[36:39], v[188:191], v[124:127]
	v_mfma_f32_16x16x32_bf16 v[108:111], v[36:39], v[196:199], v[108:111]
	v_mfma_f32_16x16x32_bf16 v[108:111], v[152:155], v[200:203], v[108:111]
	v_mfma_f32_16x16x32_bf16 v[104:107], v[160:163], v[200:203], v[104:107]
	v_mfma_f32_16x16x32_bf16 v[104:107], v[156:159], v[196:199], v[104:107]
	v_mfma_f32_16x16x32_bf16 v[88:91], v[156:159], v[204:207], v[88:91]
	v_mfma_f32_16x16x32_bf16 v[88:91], v[160:163], v[208:211], v[88:91]
	v_mfma_f32_16x16x32_bf16 v[92:95], v[152:155], v[208:211], v[92:95]
	v_mfma_f32_16x16x32_bf16 v[92:95], v[36:39], v[204:207], v[92:95]
	v_mfma_f32_16x16x32_bf16 v[76:79], v[164:167], v[204:207], v[76:79]
	v_mfma_f32_16x16x32_bf16 v[76:79], v[168:171], v[208:211], v[76:79]
	v_mfma_f32_16x16x32_bf16 v[116:119], v[168:171], v[184:187], v[116:119]
	v_mfma_f32_16x16x32_bf16 v[116:119], v[164:167], v[180:183], v[116:119]
	v_mfma_f32_16x16x32_bf16 v[112:115], v[172:175], v[180:183], v[112:115]
	v_mfma_f32_16x16x32_bf16 v[112:115], v[176:179], v[184:187], v[112:115]
	v_mfma_f32_16x16x32_bf16 v[96:99], v[176:179], v[192:195], v[96:99]
	v_mfma_f32_16x16x32_bf16 v[96:99], v[172:175], v[188:191], v[96:99]
	v_mfma_f32_16x16x32_bf16 v[100:103], v[164:167], v[188:191], v[100:103]
	v_mfma_f32_16x16x32_bf16 v[100:103], v[168:171], v[192:195], v[100:103]
	v_mfma_f32_16x16x32_bf16 v[84:87], v[168:171], v[200:203], v[84:87]
	v_mfma_f32_16x16x32_bf16 v[84:87], v[164:167], v[196:199], v[84:87]
	v_mfma_f32_16x16x32_bf16 v[80:83], v[172:175], v[196:199], v[80:83]
	v_mfma_f32_16x16x32_bf16 v[80:83], v[176:179], v[200:203], v[80:83]
	v_mfma_f32_16x16x32_bf16 v[72:75], v[176:179], v[208:211], v[72:75]
	v_mfma_f32_16x16x32_bf16 v[72:75], v[172:175], v[204:207], v[72:75]
	s_setprio 0
	s_barrier
	s_add_i32 s68, s68, s34
	s_mov_b32 m0, s68
	ds_read_b128 v[180:183], v150 offset:16384
	ds_read_b128 v[184:187], v150 offset:17408
	ds_read_b128 v[188:191], v150 offset:18432
	ds_read_b128 v[192:195], v150 offset:19456
	ds_read_b128 v[196:199], v150 offset:20480
	ds_read_b128 v[200:203], v150 offset:21504
	ds_read_b128 v[204:207], v150 offset:22528
	ds_read_b128 v[208:211], v150 offset:23552
	global_load_lds_dwordx4 v138, s[26:27]
	s_add_i32 m0, s68, 0x2000
	s_add_u32 s68, s26, 0x4000
	s_addc_u32 s69, s27, 0
	s_add_i32 s88, s88, s34
	global_load_lds_dwordx4 v142, s[26:27]
	s_mov_b32 m0, s88
	s_nop 0
	global_load_lds_dwordx4 v138, s[68:69]
	s_add_i32 m0, s88, 0x2000
	s_nop 0
	global_load_lds_dwordx4 v142, s[68:69]
	s_mov_b32 m0, s9
	s_nop 0
	global_load_lds_dwordx4 v136, s[28:29]
	s_mov_b32 m0, s35
	s_nop 0
	global_load_lds_dwordx4 v140, s[28:29]
	s_waitcnt lgkmcnt(0)
	v_mfma_f32_16x16x32_bf16 v[68:71], v[36:39], v[180:183], v[68:71]
	v_mfma_f32_16x16x32_bf16 v[68:71], v[152:155], v[184:187], v[68:71]
	v_mfma_f32_16x16x32_bf16 v[64:67], v[160:163], v[184:187], v[64:67]
	v_mfma_f32_16x16x32_bf16 v[64:67], v[156:159], v[180:183], v[64:67]
	s_waitcnt vmcnt(8)
	s_barrier
	s_setprio 1
	v_mfma_f32_16x16x32_bf16 v[56:59], v[156:159], v[188:191], v[56:59]
	v_mfma_f32_16x16x32_bf16 v[56:59], v[160:163], v[192:195], v[56:59]
	v_mfma_f32_16x16x32_bf16 v[60:63], v[152:155], v[192:195], v[60:63]
	v_mfma_f32_16x16x32_bf16 v[60:63], v[36:39], v[188:191], v[60:63]
	v_mfma_f32_16x16x32_bf16 v[44:47], v[36:39], v[196:199], v[44:47]
	v_mfma_f32_16x16x32_bf16 v[44:47], v[152:155], v[200:203], v[44:47]
	v_mfma_f32_16x16x32_bf16 v[40:43], v[160:163], v[200:203], v[40:43]
	v_mfma_f32_16x16x32_bf16 v[40:43], v[156:159], v[196:199], v[40:43]
	v_mfma_f32_16x16x32_bf16 v[20:23], v[156:159], v[204:207], v[20:23]
	v_mfma_f32_16x16x32_bf16 v[20:23], v[160:163], v[208:211], v[20:23]
	v_mfma_f32_16x16x32_bf16 v[24:27], v[152:155], v[208:211], v[24:27]
	v_mfma_f32_16x16x32_bf16 v[24:27], v[36:39], v[204:207], v[24:27]
	v_mfma_f32_16x16x32_bf16 v[48:51], v[172:175], v[180:183], v[48:51]
	v_mfma_f32_16x16x32_bf16 v[32:35], v[164:167], v[188:191], v[32:35]
	v_mfma_f32_16x16x32_bf16 v[28:31], v[172:175], v[188:191], v[28:31]
	v_mfma_f32_16x16x32_bf16 v[16:19], v[164:167], v[196:199], v[16:19]
	v_mfma_f32_16x16x32_bf16 v[12:15], v[172:175], v[196:199], v[12:15]
	v_mfma_f32_16x16x32_bf16 v[8:11], v[164:167], v[204:207], v[8:11]
	v_mfma_f32_16x16x32_bf16 v[4:7], v[172:175], v[204:207], v[4:7]
	v_mfma_f32_16x16x32_bf16 v[36:39], v[164:167], v[180:183], v[52:55]
	v_mfma_f32_16x16x32_bf16 v[48:51], v[176:179], v[184:187], v[48:51]
	v_mfma_f32_16x16x32_bf16 v[32:35], v[168:171], v[192:195], v[32:35]
	v_mfma_f32_16x16x32_bf16 v[28:31], v[176:179], v[192:195], v[28:31]
	v_mfma_f32_16x16x32_bf16 v[16:19], v[168:171], v[200:203], v[16:19]
	v_mfma_f32_16x16x32_bf16 v[12:15], v[176:179], v[200:203], v[12:15]
	v_mfma_f32_16x16x32_bf16 v[8:11], v[168:171], v[208:211], v[8:11]
	v_mfma_f32_16x16x32_bf16 v[4:7], v[176:179], v[208:211], v[4:7]
	v_mfma_f32_16x16x32_bf16 v[36:39], v[168:171], v[184:187], v[36:39]
	s_setprio 0
	s_barrier
; #define PG8_STAGE(bufoff, gbase, voff) do { _Pragma("unroll") for (int _i = 0; _i < 2; ++_i) \
;         __builtin_amdgcn_global_load_lds((const unsigned*)((const char*)(gbase) + (voff)[_i]), (PG8_LAS unsigned*)(lds + (bufoff) + ldsw + _i * 8192), 16, 0, 0); } while (0)
; #define PG8_LDA(dst, b, h) do { _Pragma("unroll") for (int m = 0; m < 4; ++m) _Pragma("unroll") for (int k = 0; k < 2; ++k) dst[m][k] = *(const PG8_LAS bf16x8*)(lds + PG8_SA(b, h) + aoff + m * 2048 + k * 1024); } while (0)
; #define PG8_LDB(dst, b, h) do { _Pragma("unroll") for (int n = 0; n < 2; ++n) _Pragma("unroll") for (int k = 0; k < 2; ++k) dst[n][k] = *(const PG8_LAS bf16x8*)(lds + PG8_SB(b, h) + boff + n * 2048 + k * 1024); } while (0)
; #define PG8_MMA(ai, bj, At, Bt) do { __builtin_amdgcn_s_setprio(1); _Pragma("unroll") for (int m = 0; m < 4; ++m) _Pragma("unroll") for (int n = 0; n < 2; ++n) _Pragma("unroll") for (int k = 0; k < 2; ++k) \
;         acc[ai][bj][m][n] = __builtin_amdgcn_mfma_f32_16x16x32_bf16(Bt[n][k], At[m][k], acc[ai][bj][m][n], 0, 0, 0); __builtin_amdgcn_s_setprio(0); } while (0)
; #define PG8_WAIT_V(n) asm volatile("s_waitcnt vmcnt(" #n ")" ::: "memory")
; #define PG8_BAR __builtin_amdgcn_s_barrier()
; template <class Epi, class Sched, bool ALIGN_EPI = false, bool SP2 = false, bool ABLK = false, bool BBLK = false>
; __device__ __forceinline__ void gemm_phase(PG8_LAS unsigned char* lds, const Gemm g, const Sched& S, const Epi& E) {
;     ...
;         for (int t = 0; t < nt; t += 2) {
;             const bool last = (t == nt - 2);
;             const char* a1 = cA + (size_t)(t + 1) * kstepA;
;             const char* a2 = last ? nA : cA + (size_t)(t + 2) * kstepA; const char* b2 = last ? nB : cB + (size_t)(t + 2) * kstepB;
;             const char* a3 = a2 + kstepA; const char* b3 = b2 + kstepB;
;     ...
;             PG8_LDB(B0, 1, 0); PG8_LDB(B1, 1, 1); PG8_SCHED; PG8_LDA(At, 1, 0); PG8_STAGE(PG8_SA(0, 1), a2 + hstepA, voffA);
;             PG8_WAIT_V(8); PG8_WAIT_L(0); PG8_BAR; PG8_MMA(0, 0, At, B0); PG8_MMA(0, 1, At, B1); PG8_BAR; PG8_SCHED;
;             PG8_LDA(At, 1, 1); PG8_STAGE(PG8_SB(1, 0), b3, voffB); PG8_STAGE(PG8_SB(1, 1), b3 + hstepB, voffB); PG8_STAGE(PG8_SA(1, 0), a3, voffA);
;             PG8_WAIT_V(8); PG8_WAIT_L(0); PG8_BAR; PG8_MMA(1, 0, At, B0); PG8_MMA(1, 1, At, B1); PG8_BAR; PG8_SCHED;
;     ...
;         if constexpr (ALIGN_EPI) { if (wr == 0) PG8_BAR; }
	s_add_i32 s68, 0, 0x18000
	v_add_u32_e32 v151, s68, v148
	s_add_i32 s69, 0, 0x1c000
	ds_read_b128 v[52:55], v151
	ds_read_b128 v[152:155], v151 offset:1024
	ds_read_b128 v[156:159], v151 offset:2048
	ds_read_b128 v[160:163], v151 offset:3072
	v_add_u32_e32 v151, s69, v148
	ds_read_b128 v[164:167], v151
	ds_read_b128 v[168:171], v151 offset:1024
	ds_read_b128 v[172:175], v151 offset:2048
	ds_read_b128 v[176:179], v151 offset:3072
	s_add_u32 s28, s28, 0x4000
	s_addc_u32 s29, s29, 0
	s_mov_b32 m0, s36
	ds_read_b128 v[180:183], v150 offset:32768
	ds_read_b128 v[184:187], v150 offset:33792
	ds_read_b128 v[188:191], v150 offset:34816
	ds_read_b128 v[192:195], v150 offset:35840
	ds_read_b128 v[196:199], v150 offset:36864
	ds_read_b128 v[200:203], v150 offset:37888
	ds_read_b128 v[204:207], v150 offset:38912
	ds_read_b128 v[208:211], v150 offset:39936
	global_load_lds_dwordx4 v136, s[28:29]
	s_mov_b32 m0, s37
	s_nop 0
	global_load_lds_dwordx4 v140, s[28:29]
	s_waitcnt lgkmcnt(0)
	v_mfma_f32_16x16x32_bf16 v[132:135], v[52:55], v[180:183], v[132:135]
	v_mfma_f32_16x16x32_bf16 v[132:135], v[152:155], v[184:187], v[132:135]
	v_mfma_f32_16x16x32_bf16 v[128:131], v[160:163], v[184:187], v[128:131]
	v_mfma_f32_16x16x32_bf16 v[128:131], v[156:159], v[180:183], v[128:131]
	s_waitcnt vmcnt(8)
	s_barrier
	s_setprio 1
	v_mfma_f32_16x16x32_bf16 v[120:123], v[156:159], v[188:191], v[120:123]
	v_mfma_f32_16x16x32_bf16 v[120:123], v[160:163], v[192:195], v[120:123]
	v_mfma_f32_16x16x32_bf16 v[124:127], v[152:155], v[192:195], v[124:127]
	v_mfma_f32_16x16x32_bf16 v[124:127], v[52:55], v[188:191], v[124:127]
	v_mfma_f32_16x16x32_bf16 v[108:111], v[52:55], v[196:199], v[108:111]
	v_mfma_f32_16x16x32_bf16 v[108:111], v[152:155], v[200:203], v[108:111]
	v_mfma_f32_16x16x32_bf16 v[104:107], v[160:163], v[200:203], v[104:107]
	v_mfma_f32_16x16x32_bf16 v[104:107], v[156:159], v[196:199], v[104:107]
	v_mfma_f32_16x16x32_bf16 v[88:91], v[156:159], v[204:207], v[88:91]
	v_mfma_f32_16x16x32_bf16 v[88:91], v[160:163], v[208:211], v[88:91]
	v_mfma_f32_16x16x32_bf16 v[92:95], v[152:155], v[208:211], v[92:95]
	v_mfma_f32_16x16x32_bf16 v[92:95], v[52:55], v[204:207], v[92:95]
	v_mfma_f32_16x16x32_bf16 v[76:79], v[164:167], v[204:207], v[76:79]
	v_mfma_f32_16x16x32_bf16 v[76:79], v[168:171], v[208:211], v[76:79]
	v_mfma_f32_16x16x32_bf16 v[116:119], v[168:171], v[184:187], v[116:119]
	v_mfma_f32_16x16x32_bf16 v[116:119], v[164:167], v[180:183], v[116:119]
	v_mfma_f32_16x16x32_bf16 v[112:115], v[172:175], v[180:183], v[112:115]
	v_mfma_f32_16x16x32_bf16 v[112:115], v[176:179], v[184:187], v[112:115]
	v_mfma_f32_16x16x32_bf16 v[96:99], v[176:179], v[192:195], v[96:99]
	v_mfma_f32_16x16x32_bf16 v[96:99], v[172:175], v[188:191], v[96:99]
	v_mfma_f32_16x16x32_bf16 v[100:103], v[164:167], v[188:191], v[100:103]
	v_mfma_f32_16x16x32_bf16 v[100:103], v[168:171], v[192:195], v[100:103]
	v_mfma_f32_16x16x32_bf16 v[84:87], v[168:171], v[200:203], v[84:87]
	v_mfma_f32_16x16x32_bf16 v[84:87], v[164:167], v[196:199], v[84:87]
	v_mfma_f32_16x16x32_bf16 v[80:83], v[172:175], v[196:199], v[80:83]
	v_mfma_f32_16x16x32_bf16 v[80:83], v[176:179], v[200:203], v[80:83]
	v_mfma_f32_16x16x32_bf16 v[72:75], v[176:179], v[208:211], v[72:75]
	v_mfma_f32_16x16x32_bf16 v[72:75], v[172:175], v[204:207], v[72:75]
	s_setprio 0
	s_barrier
	s_add_u32 s28, s26, 0x8000
	s_addc_u32 s29, s27, 0
	s_add_i32 s68, s68, s34
	s_mov_b32 m0, s68
	ds_read_b128 v[180:183], v150 offset:49152
	ds_read_b128 v[184:187], v150 offset:50176
	ds_read_b128 v[188:191], v150 offset:51200
	ds_read_b128 v[192:195], v150 offset:52224
	ds_read_b128 v[196:199], v150 offset:53248
	ds_read_b128 v[200:203], v150 offset:54272
	ds_read_b128 v[204:207], v150 offset:55296
	ds_read_b128 v[208:211], v150 offset:56320
	global_load_lds_dwordx4 v138, s[28:29]
	s_add_i32 m0, s68, 0x2000
	s_add_u32 s26, s26, 0xc000
	s_addc_u32 s27, s27, 0
	global_load_lds_dwordx4 v142, s[28:29]
	s_add_i32 s28, s69, s34
	s_mov_b32 m0, s28
	s_nop 0
	global_load_lds_dwordx4 v138, s[26:27]
	s_add_i32 m0, s28, 0x2000
	s_nop 0
	global_load_lds_dwordx4 v142, s[26:27]
	s_mov_b32 m0, s64
	s_nop 0
	global_load_lds_dwordx4 v136, s[24:25]
	s_mov_b32 m0, s65
	s_nop 0
	global_load_lds_dwordx4 v140, s[24:25]
	s_waitcnt lgkmcnt(0)
	v_mfma_f32_16x16x32_bf16 v[68:71], v[52:55], v[180:183], v[68:71]
	v_mfma_f32_16x16x32_bf16 v[68:71], v[152:155], v[184:187], v[68:71]
	v_mfma_f32_16x16x32_bf16 v[64:67], v[160:163], v[184:187], v[64:67]
	v_mfma_f32_16x16x32_bf16 v[64:67], v[156:159], v[180:183], v[64:67]
	s_waitcnt vmcnt(8)
	s_barrier
	s_setprio 1
	v_mfma_f32_16x16x32_bf16 v[56:59], v[156:159], v[188:191], v[56:59]
	v_mfma_f32_16x16x32_bf16 v[56:59], v[160:163], v[192:195], v[56:59]
	v_mfma_f32_16x16x32_bf16 v[60:63], v[152:155], v[192:195], v[60:63]
	v_mfma_f32_16x16x32_bf16 v[60:63], v[52:55], v[188:191], v[60:63]
	v_mfma_f32_16x16x32_bf16 v[44:47], v[52:55], v[196:199], v[44:47]
	v_mfma_f32_16x16x32_bf16 v[44:47], v[152:155], v[200:203], v[44:47]
	v_mfma_f32_16x16x32_bf16 v[40:43], v[160:163], v[200:203], v[40:43]
	v_mfma_f32_16x16x32_bf16 v[40:43], v[156:159], v[196:199], v[40:43]
	v_mfma_f32_16x16x32_bf16 v[20:23], v[156:159], v[204:207], v[20:23]
	v_mfma_f32_16x16x32_bf16 v[20:23], v[160:163], v[208:211], v[20:23]
	v_mfma_f32_16x16x32_bf16 v[24:27], v[152:155], v[208:211], v[24:27]
	v_mfma_f32_16x16x32_bf16 v[24:27], v[52:55], v[204:207], v[24:27]
	v_mfma_f32_16x16x32_bf16 v[36:39], v[164:167], v[180:183], v[36:39]
	v_mfma_f32_16x16x32_bf16 v[52:55], v[168:171], v[184:187], v[36:39]
	v_mfma_f32_16x16x32_bf16 v[36:39], v[172:175], v[180:183], v[48:51]
	v_mfma_f32_16x16x32_bf16 v[32:35], v[164:167], v[188:191], v[32:35]
	v_mfma_f32_16x16x32_bf16 v[28:31], v[172:175], v[188:191], v[28:31]
	v_mfma_f32_16x16x32_bf16 v[16:19], v[164:167], v[196:199], v[16:19]
	v_mfma_f32_16x16x32_bf16 v[12:15], v[172:175], v[196:199], v[12:15]
	v_mfma_f32_16x16x32_bf16 v[8:11], v[164:167], v[204:207], v[8:11]
	v_mfma_f32_16x16x32_bf16 v[4:7], v[172:175], v[204:207], v[4:7]
	v_mfma_f32_16x16x32_bf16 v[48:51], v[176:179], v[184:187], v[36:39]
	v_mfma_f32_16x16x32_bf16 v[32:35], v[168:171], v[192:195], v[32:35]
	v_mfma_f32_16x16x32_bf16 v[28:31], v[176:179], v[192:195], v[28:31]
	v_mfma_f32_16x16x32_bf16 v[16:19], v[168:171], v[200:203], v[16:19]
	v_mfma_f32_16x16x32_bf16 v[12:15], v[176:179], v[200:203], v[12:15]
	v_mfma_f32_16x16x32_bf16 v[8:11], v[168:171], v[208:211], v[8:11]
	v_mfma_f32_16x16x32_bf16 v[4:7], v[176:179], v[208:211], v[4:7]
	s_setprio 0
	s_barrier
	s_add_i32 s13, s13, 2
	s_add_u32 s22, s22, 0x10000
	s_addc_u32 s23, s23, 0
	s_add_u32 s82, s82, 0x10000
	s_addc_u32 vcc_lo, vcc_lo, 0
	s_cmp_gt_u32 s13, 29
	s_cbranch_scc0 .LBB0_2111
	s_and_b64 vcc, exec, s[6:7]
	s_movk_i32 s77, 0x1000
	s_cbranch_vccz .LBB0_2114
	s_barrier
